# conv phase: row loads of each 8-token block issued together behind counted waits instead of one round trip per row
# speedup vs baseline: 1.0028x; 1.0028x over previous
; __device__ __forceinline__ void conv_phase(const Params& P, const int pass, const int wvi) {
;     ...
;   for (int idx = blockIdx.x * NTHR + tid; idx < nitems; idx += gridDim.x * NTHR) {
;     const int cgp = idx % 768, tch = idx / 768;
;     const int c0 = cgp * 8, t0 = tch * TCH;
;     const int pos0 = t0 % S;
;     float wgt[5][8], bias[8];
; #pragma unroll
;     for (int j = 0; j < 5; ++j) {
;       float4 a = *(const float4*)(conv_w + j * CONVD + c0), b = *(const float4*)(conv_w + j * CONVD + c0 + 4);
;       wgt[j][0] = a.x; wgt[j][1] = a.y; wgt[j][2] = a.z; wgt[j][3] = a.w; wgt[j][4] = b.x; wgt[j][5] = b.y; wgt[j][6] = b.z; wgt[j][7] = b.w;
;     }
;     {
;       float4 a = *(const float4*)(conv_b + c0), b = *(const float4*)(conv_b + c0 + 4);
;       bias[0] = a.x; bias[1] = a.y; bias[2] = a.z; bias[3] = a.w; bias[4] = b.x; bias[5] = b.y; bias[6] = b.z; bias[7] = b.w;
;     }
;     const uint4 zz = make_uint4(0, 0, 0, 0);
;     uint4 r1, r2, r3, r4;
;     {
;       const bool v1 = (pos0 - 2 >= 0), v2 = (pos0 - 1 >= 0);
;       const uint4 l1 = *(const uint4*)(xin + (size_t)(v1 ? t0 - 2 : t0) * CONVD + c0);
;       const uint4 l2 = *(const uint4*)(xin + (size_t)(v2 ? t0 - 1 : t0) * CONVD + c0);
;       r1.x = v1 ? l1.x : 0u; r1.y = v1 ? l1.y : 0u; r1.z = v1 ? l1.z : 0u; r1.w = v1 ? l1.w : 0u;
;       r2.x = v2 ? l2.x : 0u; r2.y = v2 ? l2.y : 0u; r2.z = v2 ? l2.z : 0u; r2.w = v2 ? l2.w : 0u;
;     }
;     r3 = *(const uint4*)(xin + (size_t)(t0) * CONVD + c0);
;     r4 = *(const uint4*)(xin + (size_t)(t0 + 1) * CONVD + c0);
;     ...
;     uint4 R[12];
;     R[0] = r1; R[1] = r2; R[2] = r3; R[3] = r4;
; #pragma unroll
;     for (int blk = 0; blk < TCH / 8; ++blk) {
; #pragma unroll
;       for (int j = 0; j < 8; ++j) {
;         const int tt2 = blk * 8 + j + 2;
;         const bool v4 = (pos0 + tt2 < S);
;         const uint4 l4 = *(const uint4*)(xin + (size_t)(v4 ? t0 + tt2 : t0) * CONVD + c0);
;         R[4 + j].x = v4 ? l4.x : 0u; R[4 + j].y = v4 ? l4.y : 0u; R[4 + j].z = v4 ? l4.z : 0u; R[4 + j].w = v4 ? l4.w : 0u;
;       }
.LBB0_324:
	s_mov_b32 s2, 0x2aaaaaab
	v_mul_hi_i32 v0, v122, s2
	v_lshrrev_b32_e32 v1, 31, v0
	v_ashrrev_i32_e32 v0, 7, v0
	v_add_u32_e32 v4, v0, v1
	v_lshlrev_b32_e32 v125, 5, v4
	v_sub_u32_e32 v5, 0, v125
	v_max_i32_e32 v5, v125, v5
	v_mul_hi_u32 v6, v5, v123
	v_mul_lo_u32 v6, v6, s0
	v_mul_i32_i24_e32 v0, 0x300, v4
	v_sub_u32_e32 v5, v5, v6
	v_lshlrev_b32_e32 v0, 3, v0
	v_cmp_le_u32_e32 vcc, s0, v5
	v_subrev_u32_e32 v6, s0, v5
	v_sub_u32_e32 v0, v124, v0
	v_cndmask_b32_e32 v5, v5, v6, vcc
	v_ashrrev_i32_e32 v1, 31, v0
	v_cmp_le_u32_e32 vcc, s0, v5
	v_subrev_u32_e32 v6, s0, v5
	v_lshlrev_b64 v[2:3], 2, v[0:1]
	v_ashrrev_i32_e32 v4, 31, v4
	v_cndmask_b32_e32 v5, v5, v6, vcc
	v_lshl_add_u64 v[20:21], s[36:37], 0, v[2:3]
	s_mov_b64 s[2:3], 0x6000
	v_xor_b32_e32 v5, v5, v4
	v_lshl_add_u64 v[8:9], v[20:21], 0, s[2:3]
	s_mov_b64 s[2:3], 0xc000
	v_sub_u32_e32 v18, v5, v4
	v_lshl_add_u64 v[12:13], v[20:21], 0, s[2:3]
	s_mov_b64 s[2:3], 0x12000
	v_lshl_add_u64 v[44:45], s[38:39], 0, v[2:3]
	v_cmp_lt_i32_e64 s[6:7], 1, v18
	v_add_u32_e32 v2, -2, v125
	v_lshl_add_u64 v[16:17], v[20:21], 0, s[2:3]
	s_mov_b64 s[2:3], 0x18000
	v_cndmask_b32_e64 v2, v125, v2, s[6:7]
	v_mov_b64_e32 v[10:11], s[34:35]
	v_lshl_add_u64 v[22:23], v[20:21], 0, s[2:3]
	v_mad_i64_i32 v[2:3], s[2:3], v2, s85, v[10:11]
	v_lshlrev_b64 v[14:15], 1, v[0:1]
	v_cmp_lt_i32_e32 vcc, 0, v18
	v_lshl_add_u64 v[0:1], v[2:3], 0, v[14:15]
	global_load_dwordx4 v[0:3], v[0:1], off
	v_subbrev_co_u32_e64 v4, s[8:9], 0, v125, vcc
	v_mad_i64_i32 v[4:5], s[2:3], v4, s85, v[10:11]
	v_lshl_add_u64 v[4:5], v[4:5], 0, v[14:15]
	global_load_dwordx4 v[4:7], v[4:5], off
	v_or_b32_e32 v127, 1, v125
	v_sub_u32_e32 v126, s0, v18
	v_lshl_add_u64 v[58:59], s[34:35], 0, v[14:15]
	v_lshl_add_u64 v[56:57], s[4:5], 0, v[14:15]
	v_add_u32_e32 v122, s18, v122
	v_add_u32_e32 v124, s1, v124
	s_waitcnt vmcnt(1)
	v_cndmask_b32_e64 v19, 0, v0, s[6:7]
	v_cndmask_b32_e64 v24, 0, v1, s[6:7]
	v_mad_i64_i32 v[0:1], s[2:3], v125, s85, v[10:11]
	v_lshl_add_u64 v[0:1], v[0:1], 0, v[14:15]
	global_load_dwordx4 v[48:51], v[0:1], off
	v_mad_i64_i32 v[0:1], s[2:3], v127, s85, v[10:11]
	s_waitcnt vmcnt(1)
	v_cndmask_b32_e32 v4, 0, v4, vcc
	v_cndmask_b32_e32 v5, 0, v5, vcc
	v_cndmask_b32_e32 v6, 0, v6, vcc
	v_cndmask_b32_e32 v7, 0, v7, vcc
	v_lshl_add_u64 v[0:1], v[0:1], 0, v[14:15]
	v_cmp_lt_i32_e32 vcc, 2, v126
	global_load_dwordx4 v[52:55], v[0:1], off
	v_cndmask_b32_e64 v25, 0, v2, s[6:7]
	v_cndmask_b32_e64 v0, 0, 2, vcc
	v_or_b32_e32 v0, v0, v125
	v_mad_i64_i32 v[0:1], s[2:3], v0, s85, v[58:59]
	v_cndmask_b32_e64 v26, 0, v3, s[6:7]
	global_load_dwordx4 v[0:3], v[0:1], off
	v_lshlrev_b32_e32 v70, 16, v19
	v_and_b32_e32 v71, 0xffff0000, v19
	v_lshlrev_b32_e32 v90, 16, v4
	v_and_b32_e32 v91, 0xffff0000, v4
	v_lshlrev_b32_e32 v88, 16, v5
	v_and_b32_e32 v89, 0xffff0000, v5
	v_lshlrev_b32_e32 v62, 16, v6
	v_and_b32_e32 v63, 0xffff0000, v6
	v_lshlrev_b32_e32 v60, 16, v7
	v_and_b32_e32 v61, 0xffff0000, v7
	v_lshlrev_b32_e32 v68, 16, v24
	v_and_b32_e32 v69, 0xffff0000, v24
	v_lshlrev_b32_e32 v66, 16, v25
	v_and_b32_e32 v67, 0xffff0000, v25
	v_lshlrev_b32_e32 v64, 16, v26
	v_and_b32_e32 v65, 0xffff0000, v26
	s_waitcnt vmcnt(2)
	v_lshlrev_b32_e32 v98, 16, v48
	v_and_b32_e32 v99, 0xffff0000, v48
	v_lshlrev_b32_e32 v100, 16, v49
	v_and_b32_e32 v101, 0xffff0000, v49
	v_lshlrev_b32_e32 v116, 16, v50
	v_and_b32_e32 v117, 0xffff0000, v50
	v_lshlrev_b32_e32 v118, 16, v51
	v_and_b32_e32 v119, 0xffff0000, v51
	s_waitcnt vmcnt(1)
	v_lshlrev_b32_e32 v80, 16, v52
	v_and_b32_e32 v81, 0xffff0000, v52
	v_lshlrev_b32_e32 v84, 16, v54
	v_and_b32_e32 v85, 0xffff0000, v54
	v_lshlrev_b32_e32 v86, 16, v55
	v_and_b32_e32 v87, 0xffff0000, v55
	s_waitcnt vmcnt(0)
	v_cndmask_b32_e32 v10, 0, v0, vcc
	v_cndmask_b32_e32 v11, 0, v1, vcc
	v_cndmask_b32_e32 v14, 0, v2, vcc
	v_cndmask_b32_e32 v15, 0, v3, vcc
	v_cmp_lt_i32_e32 vcc, 3, v126
	s_nop 1
	v_cndmask_b32_e64 v210, 0, 3, vcc
	v_or_b32_e32 v210, v210, v125
	v_mad_i64_i32 v[210:211], s[2:3], v210, s85, v[58:59]
	global_load_dwordx4 v[210:213], v[210:211], off
	v_cmp_lt_i32_e32 vcc, 4, v126
	s_nop 1
	v_cndmask_b32_e64 v214, 0, 4, vcc
	v_or_b32_e32 v214, v214, v125
	v_mad_i64_i32 v[214:215], s[2:3], v214, s85, v[58:59]
	global_load_dwordx4 v[214:217], v[214:215], off
	v_cmp_lt_i32_e32 vcc, 5, v126
	s_nop 1
	v_cndmask_b32_e64 v218, 0, 5, vcc
	v_or_b32_e32 v218, v218, v125
	v_mad_i64_i32 v[218:219], s[2:3], v218, s85, v[58:59]
	global_load_dwordx4 v[218:221], v[218:219], off
	v_cmp_lt_i32_e32 vcc, 6, v126
	s_nop 1
	v_cndmask_b32_e64 v222, 0, 6, vcc
	v_or_b32_e32 v222, v222, v125
	v_mad_i64_i32 v[222:223], s[2:3], v222, s85, v[58:59]
	global_load_dwordx4 v[222:225], v[222:223], off
	v_cmp_lt_i32_e32 vcc, 7, v126
	s_nop 1
	v_cndmask_b32_e64 v226, 0, 7, vcc
	v_or_b32_e32 v226, v226, v125
	v_mad_i64_i32 v[226:227], s[2:3], v226, s85, v[58:59]
	global_load_dwordx4 v[226:229], v[226:227], off
	v_cmp_lt_i32_e32 vcc, 8, v126
	s_nop 1
	v_cndmask_b32_e64 v230, 0, 8, vcc
	v_or_b32_e32 v230, v230, v125
	v_mad_i64_i32 v[230:231], s[2:3], v230, s85, v[58:59]
	global_load_dwordx4 v[230:233], v[230:231], off
	v_cmp_lt_i32_e32 vcc, 9, v126
	s_nop 1
	v_cndmask_b32_e64 v234, 0, 9, vcc
	v_or_b32_e32 v234, v234, v125
	v_mad_i64_i32 v[234:235], s[2:3], v234, s85, v[58:59]
	global_load_dwordx4 v[234:237], v[234:235], off
	s_waitcnt vmcnt(6)
	v_cmp_lt_i32_e32 vcc, 3, v126
	s_nop 1
	v_cndmask_b32_e32 v128, 0, v210, vcc
	v_cndmask_b32_e32 v129, 0, v211, vcc
	v_cndmask_b32_e32 v130, 0, v212, vcc
	v_cndmask_b32_e32 v131, 0, v213, vcc
	s_waitcnt vmcnt(5)
; __device__ __forceinline__ void conv_phase(const Params& P, const int pass, const int wvi) {
;     ...
; #pragma unroll
;     for (int j = 0; j < 5; ++j) {
;       float4 a = *(const float4*)(conv_w + j * CONVD + c0), b = *(const float4*)(conv_w + j * CONVD + c0 + 4);
;       wgt[j][0] = a.x; wgt[j][1] = a.y; wgt[j][2] = a.z; wgt[j][3] = a.w; wgt[j][4] = b.x; wgt[j][5] = b.y; wgt[j][6] = b.z; wgt[j][7] = b.w;
;     }
;     {
;       float4 a = *(const float4*)(conv_b + c0), b = *(const float4*)(conv_b + c0 + 4);
;       bias[0] = a.x; bias[1] = a.y; bias[2] = a.z; bias[3] = a.w; bias[4] = b.x; bias[5] = b.y; bias[6] = b.z; bias[7] = b.w;
;     }
;     const uint4 zz = make_uint4(0, 0, 0, 0);
;     uint4 r1, r2, r3, r4;
;     {
;       const bool v1 = (pos0 - 2 >= 0), v2 = (pos0 - 1 >= 0);
;       const uint4 l1 = *(const uint4*)(xin + (size_t)(v1 ? t0 - 2 : t0) * CONVD + c0);
;       const uint4 l2 = *(const uint4*)(xin + (size_t)(v2 ? t0 - 1 : t0) * CONVD + c0);
;       r1.x = v1 ? l1.x : 0u; r1.y = v1 ? l1.y : 0u; r1.z = v1 ? l1.z : 0u; r1.w = v1 ? l1.w : 0u;
;       r2.x = v2 ? l2.x : 0u; r2.y = v2 ? l2.y : 0u; r2.z = v2 ? l2.z : 0u; r2.w = v2 ? l2.w : 0u;
;     }
;     r3 = *(const uint4*)(xin + (size_t)(t0) * CONVD + c0);
;     r4 = *(const uint4*)(xin + (size_t)(t0 + 1) * CONVD + c0);
;     ...
;     uint4 R[12];
;     R[0] = r1; R[1] = r2; R[2] = r3; R[3] = r4;
; #pragma unroll
;     for (int blk = 0; blk < TCH / 8; ++blk) {
; #pragma unroll
;       for (int j = 0; j < 8; ++j) {
;         const int tt2 = blk * 8 + j + 2;
;         const bool v4 = (pos0 + tt2 < S);
;         const uint4 l4 = *(const uint4*)(xin + (size_t)(v4 ? t0 + tt2 : t0) * CONVD + c0);
;         R[4 + j].x = v4 ? l4.x : 0u; R[4 + j].y = v4 ? l4.y : 0u; R[4 + j].z = v4 ? l4.z : 0u; R[4 + j].w = v4 ? l4.w : 0u;
;       }
; #pragma unroll
;       for (int j = 0; j < 8; ++j) {
;         float o[8];
; #pragma unroll
;         for (int e = 0; e < 8; ++e) o[e] = bias[e];
;         CONV_ACC(R[j], 0); CONV_ACC(R[j + 1], 1); CONV_ACC(R[j + 2], 2); CONV_ACC(R[j + 3], 3); CONV_ACC(R[j + 4], 4);
;         uint4 ov;
;         ov.x = pk2(siluf_(o[0]), siluf_(o[1])); ov.y = pk2(siluf_(o[2]), siluf_(o[3]));
;         ov.z = pk2(siluf_(o[4]), siluf_(o[5])); ov.w = pk2(siluf_(o[6]), siluf_(o[7]));
;         *(uint4*)(xo + (size_t)(t0 + blk * 8 + j) * CONVD + c0) = ov;
	v_cmp_lt_i32_e32 vcc, 4, v126
	s_nop 1
	v_cndmask_b32_e32 v132, 0, v214, vcc
	v_cndmask_b32_e32 v133, 0, v215, vcc
	v_cndmask_b32_e32 v134, 0, v216, vcc
	v_cndmask_b32_e32 v135, 0, v217, vcc
	s_waitcnt vmcnt(4)
	v_cmp_lt_i32_e32 vcc, 5, v126
	s_nop 1
	v_cndmask_b32_e32 v97, 0, v218, vcc
	v_cndmask_b32_e32 v96, 0, v219, vcc
	v_cndmask_b32_e32 v94, 0, v220, vcc
	v_cndmask_b32_e32 v95, 0, v221, vcc
	s_waitcnt vmcnt(3)
	v_cmp_lt_i32_e32 vcc, 6, v126
	s_nop 1
	v_cndmask_b32_e32 v115, 0, v222, vcc
	v_cndmask_b32_e32 v114, 0, v223, vcc
	v_cndmask_b32_e32 v113, 0, v224, vcc
	v_cndmask_b32_e32 v92, 0, v225, vcc
	s_waitcnt vmcnt(2)
	v_cmp_lt_i32_e32 vcc, 7, v126
	s_nop 1
	v_cndmask_b32_e32 v93, 0, v226, vcc
	v_cndmask_b32_e32 v112, 0, v227, vcc
	v_cndmask_b32_e32 v111, 0, v228, vcc
	v_cndmask_b32_e32 v110, 0, v229, vcc
	s_waitcnt vmcnt(1)
	v_cmp_lt_i32_e32 vcc, 8, v126
	s_nop 1
	v_cndmask_b32_e32 v109, 0, v230, vcc
	v_cndmask_b32_e32 v108, 0, v231, vcc
	v_cndmask_b32_e32 v107, 0, v232, vcc
	v_cndmask_b32_e32 v106, 0, v233, vcc
	s_waitcnt vmcnt(0)
	v_cmp_lt_i32_e32 vcc, 9, v126
	s_nop 1
	v_cndmask_b32_e32 v105, 0, v234, vcc
	v_cndmask_b32_e32 v104, 0, v235, vcc
	v_cndmask_b32_e32 v103, 0, v236, vcc
	v_cndmask_b32_e32 v102, 0, v237, vcc
	v_lshlrev_b32_e32 v78, 16, v10
	v_and_b32_e32 v79, 0xffff0000, v10
	v_lshlrev_b32_e32 v76, 16, v11
	v_and_b32_e32 v77, 0xffff0000, v11
	v_lshlrev_b32_e32 v74, 16, v14
	v_and_b32_e32 v75, 0xffff0000, v14
	v_lshlrev_b32_e32 v72, 16, v15
	v_and_b32_e32 v73, 0xffff0000, v15
	s_movk_i32 s2, 0x6000
	v_add_co_u32_e32 v10, vcc, s2, v20
	s_mov_b32 s2, 0xc000
	s_nop 0
	v_addc_co_u32_e32 v11, vcc, 0, v21, vcc
	v_add_co_u32_e32 v14, vcc, s2, v20
	s_mov_b32 s2, 0x12000
	s_nop 0
	v_addc_co_u32_e32 v15, vcc, 0, v21, vcc
	v_add_co_u32_e32 v18, vcc, s2, v20
	s_mov_b32 s2, 0x18000
	s_nop 0
	v_addc_co_u32_e32 v19, vcc, 0, v21, vcc
	global_load_dwordx4 v[0:3], v[20:21], off offset:16
	global_load_dwordx4 v[4:7], v[20:21], off
	v_add_co_u32_e32 v20, vcc, s2, v20
	global_load_dwordx4 v[24:27], v[10:11], off
	s_nop 0
	global_load_dwordx4 v[8:11], v[8:9], off offset:16
	v_addc_co_u32_e32 v21, vcc, 0, v21, vcc
	global_load_dwordx4 v[32:35], v[14:15], off
	s_nop 0
	global_load_dwordx4 v[12:15], v[12:13], off offset:16
	s_nop 0
	global_load_dwordx4 v[36:39], v[18:19], off
	s_nop 0
	global_load_dwordx4 v[16:19], v[16:17], off offset:16
	s_nop 0
	global_load_dwordx4 v[40:43], v[20:21], off
	s_nop 0
	global_load_dwordx4 v[20:23], v[22:23], off offset:16
	s_nop 0
	global_load_dwordx4 v[28:31], v[44:45], off offset:16
	s_nop 0
	global_load_dwordx4 v[44:47], v[44:45], off
	v_cmp_lt_i32_e32 vcc, 10, v126
	s_waitcnt vmcnt(0)
	v_pk_fma_f32 v[70:71], v[4:5], v[70:71], v[44:45]
	s_nop 0
	v_pk_fma_f32 v[70:71], v[24:25], v[90:91], v[70:71]
	v_pk_fma_f32 v[68:69], v[6:7], v[68:69], v[46:47]
	v_pk_fma_f32 v[70:71], v[32:33], v[98:99], v[70:71]
	v_pk_fma_f32 v[68:69], v[26:27], v[88:89], v[68:69]
	v_pk_fma_f32 v[70:71], v[36:37], v[80:81], v[70:71]
	v_pk_fma_f32 v[68:69], v[34:35], v[100:101], v[68:69]
	v_pk_fma_f32 v[70:71], v[40:41], v[78:79], v[70:71]
	s_nop 0
	v_mul_f32_e32 v48, 0xbfb8aa3b, v70
	v_exp_f32_e32 v48, v48
	s_nop 0
	v_add_f32_e32 v48, 1.0, v48
	v_rcp_f32_e32 v82, v48
	v_mul_f32_e32 v48, 0xbfb8aa3b, v71
	v_exp_f32_e32 v48, v48
	s_nop 0
	v_add_f32_e32 v48, 1.0, v48
	v_rcp_f32_e32 v83, v48
	s_nop 0
	v_pk_mul_f32 v[70:71], v[70:71], v[82:83]
	v_lshlrev_b32_e32 v82, 16, v53
	v_and_b32_e32 v83, 0xffff0000, v53
	v_pk_fma_f32 v[52:53], v[38:39], v[82:83], v[68:69]
	v_cvt_pk_bf16_f32 v48, v70, v71
	v_pk_fma_f32 v[52:53], v[42:43], v[76:77], v[52:53]
	v_lshlrev_b32_e32 v70, 16, v128
	v_mul_f32_e32 v49, 0xbfb8aa3b, v52
	v_exp_f32_e32 v49, v49
	v_and_b32_e32 v71, 0xffff0000, v128
	v_add_f32_e32 v49, 1.0, v49
	v_rcp_f32_e32 v68, v49
	v_mul_f32_e32 v49, 0xbfb8aa3b, v53
	v_exp_f32_e32 v49, v49
	s_nop 0
	v_add_f32_e32 v49, 1.0, v49
	v_rcp_f32_e32 v69, v49
	s_nop 0
	v_pk_mul_f32 v[52:53], v[52:53], v[68:69]
	s_nop 0
	v_cvt_pk_bf16_f32 v49, v52, v53
	v_pk_fma_f32 v[52:53], v[0:1], v[66:67], v[28:29]
	v_lshlrev_b32_e32 v68, 16, v129
	v_pk_fma_f32 v[52:53], v[8:9], v[62:63], v[52:53]
	v_and_b32_e32 v69, 0xffff0000, v129
	v_pk_fma_f32 v[52:53], v[12:13], v[116:117], v[52:53]
	s_nop 0
	v_pk_fma_f32 v[52:53], v[16:17], v[84:85], v[52:53]
	s_nop 0
	v_pk_fma_f32 v[52:53], v[20:21], v[74:75], v[52:53]
	s_nop 0
	v_mul_f32_e32 v50, 0xbfb8aa3b, v52
	v_exp_f32_e32 v50, v50
	s_nop 0
	v_add_f32_e32 v50, 1.0, v50
	v_rcp_f32_e32 v66, v50
	v_mul_f32_e32 v50, 0xbfb8aa3b, v53
	v_exp_f32_e32 v50, v50
	s_nop 0
	v_add_f32_e32 v50, 1.0, v50
	v_rcp_f32_e32 v67, v50
	s_nop 0
	v_pk_mul_f32 v[52:53], v[52:53], v[66:67]
	s_nop 0
	v_cvt_pk_bf16_f32 v50, v52, v53
	v_pk_fma_f32 v[52:53], v[2:3], v[64:65], v[30:31]
	v_lshlrev_b32_e32 v66, 16, v130
	v_pk_fma_f32 v[52:53], v[10:11], v[60:61], v[52:53]
	v_and_b32_e32 v67, 0xffff0000, v130
	v_pk_fma_f32 v[52:53], v[14:15], v[118:119], v[52:53]
	v_lshlrev_b32_e32 v64, 16, v131
	v_pk_fma_f32 v[52:53], v[18:19], v[86:87], v[52:53]
	v_and_b32_e32 v65, 0xffff0000, v131
	v_pk_fma_f32 v[52:53], v[22:23], v[72:73], v[52:53]
	s_nop 0
	v_mul_f32_e32 v51, 0xbfb8aa3b, v52
	v_exp_f32_e32 v51, v51
	s_nop 0
	v_add_f32_e32 v51, 1.0, v51
	v_rcp_f32_e32 v54, v51
	v_mul_f32_e32 v51, 0xbfb8aa3b, v53
	v_exp_f32_e32 v51, v51
	s_nop 0
	v_add_f32_e32 v51, 1.0, v51
	v_rcp_f32_e32 v55, v51
	s_nop 0
	v_pk_mul_f32 v[52:53], v[52:53], v[54:55]
	s_nop 0
	v_cvt_pk_bf16_f32 v51, v52, v53
	v_mad_i64_i32 v[52:53], s[2:3], v125, s85, v[56:57]
	global_store_dwordx4 v[52:53], v[48:51], off
	s_nop 1
	v_pk_fma_f32 v[48:49], v[4:5], v[90:91], v[44:45]
	s_nop 0
; __device__ __forceinline__ float siluf_(float x) { return x * __builtin_amdgcn_rcpf(1.f + __expf(-x)); }
; #define CONV_ACC(rv, j) do { \
;         o[0] += bflo(rv.x) * wgt[j][0]; o[1] += bfhi(rv.x) * wgt[j][1]; \
;         o[2] += bflo(rv.y) * wgt[j][2]; o[3] += bfhi(rv.y) * wgt[j][3]; \
;         o[4] += bflo(rv.z) * wgt[j][4]; o[5] += bfhi(rv.z) * wgt[j][5]; \
;         o[6] += bflo(rv.w) * wgt[j][6]; o[7] += bfhi(rv.w) * wgt[j][7]; } while (0)
; __device__ __forceinline__ void conv_phase(const Params& P, const int pass, const int wvi) {
;     ...
;       for (int j = 0; j < 8; ++j) {
;         float o[8];
; #pragma unroll
;         for (int e = 0; e < 8; ++e) o[e] = bias[e];
;         CONV_ACC(R[j], 0); CONV_ACC(R[j + 1], 1); CONV_ACC(R[j + 2], 2); CONV_ACC(R[j + 3], 3); CONV_ACC(R[j + 4], 4);
;         uint4 ov;
;         ov.x = pk2(siluf_(o[0]), siluf_(o[1])); ov.y = pk2(siluf_(o[2]), siluf_(o[3]));
;         ov.z = pk2(siluf_(o[4]), siluf_(o[5])); ov.w = pk2(siluf_(o[6]), siluf_(o[7]));
;         *(uint4*)(xo + (size_t)(t0 + blk * 8 + j) * CONVD + c0) = ov;
	v_pk_fma_f32 v[48:49], v[24:25], v[98:99], v[48:49]
	s_nop 0
	v_pk_fma_f32 v[48:49], v[32:33], v[80:81], v[48:49]
	s_nop 0
	v_pk_fma_f32 v[48:49], v[36:37], v[78:79], v[48:49]
	s_nop 0
	v_pk_fma_f32 v[48:49], v[40:41], v[70:71], v[48:49]
	s_nop 0
	v_mul_f32_e32 v50, 0xbfb8aa3b, v48
	v_mul_f32_e32 v51, 0xbfb8aa3b, v49
	v_exp_f32_e32 v50, v50
	v_exp_f32_e32 v51, v51
	v_add_f32_e32 v50, 1.0, v50
	v_add_f32_e32 v51, 1.0, v51
	v_rcp_f32_e32 v50, v50
	v_rcp_f32_e32 v51, v51
	s_nop 0
	v_pk_mul_f32 v[48:49], v[48:49], v[50:51]
	v_pk_fma_f32 v[50:51], v[6:7], v[88:89], v[46:47]
	v_cvt_pk_bf16_f32 v48, v48, v49
	v_pk_fma_f32 v[50:51], v[26:27], v[100:101], v[50:51]
	s_nop 0
	v_pk_fma_f32 v[50:51], v[34:35], v[82:83], v[50:51]
	s_nop 0
	v_pk_fma_f32 v[50:51], v[38:39], v[76:77], v[50:51]
	s_nop 0
	v_pk_fma_f32 v[50:51], v[42:43], v[68:69], v[50:51]
	s_nop 0
	v_mul_f32_e32 v49, 0xbfb8aa3b, v50
	v_exp_f32_e32 v49, v49
	s_nop 0
	v_add_f32_e32 v49, 1.0, v49
	v_rcp_f32_e32 v52, v49
	v_mul_f32_e32 v49, 0xbfb8aa3b, v51
	v_exp_f32_e32 v49, v49
	s_nop 0
	v_add_f32_e32 v49, 1.0, v49
	v_rcp_f32_e32 v53, v49
	s_nop 0
	v_pk_mul_f32 v[50:51], v[50:51], v[52:53]
	s_nop 0
	v_cvt_pk_bf16_f32 v49, v50, v51
	v_pk_fma_f32 v[50:51], v[0:1], v[62:63], v[28:29]
	v_lshlrev_b32_e32 v62, 16, v132
	v_pk_fma_f32 v[50:51], v[8:9], v[116:117], v[50:51]
	v_and_b32_e32 v63, 0xffff0000, v132
	v_pk_fma_f32 v[50:51], v[12:13], v[84:85], v[50:51]
	s_nop 0
	v_pk_fma_f32 v[50:51], v[16:17], v[74:75], v[50:51]
	s_nop 0
	v_pk_fma_f32 v[50:51], v[20:21], v[66:67], v[50:51]
	s_nop 0
	v_mul_f32_e32 v52, 0xbfb8aa3b, v50
	v_mul_f32_e32 v53, 0xbfb8aa3b, v51
	v_exp_f32_e32 v52, v52
	v_exp_f32_e32 v53, v53
	v_add_f32_e32 v52, 1.0, v52
	v_add_f32_e32 v53, 1.0, v53
	v_rcp_f32_e32 v52, v52
	v_rcp_f32_e32 v53, v53
	s_nop 0
	v_pk_mul_f32 v[50:51], v[50:51], v[52:53]
	v_pk_fma_f32 v[52:53], v[2:3], v[60:61], v[30:31]
	v_cvt_pk_bf16_f32 v50, v50, v51
	v_pk_fma_f32 v[52:53], v[10:11], v[118:119], v[52:53]
	v_lshlrev_b32_e32 v60, 16, v133
	v_pk_fma_f32 v[52:53], v[14:15], v[86:87], v[52:53]
	v_and_b32_e32 v61, 0xffff0000, v133
	v_pk_fma_f32 v[52:53], v[18:19], v[72:73], v[52:53]
	s_nop 0
	v_pk_fma_f32 v[52:53], v[22:23], v[64:65], v[52:53]
	s_nop 0
	v_mul_f32_e32 v51, 0xbfb8aa3b, v52
	v_exp_f32_e32 v51, v51
	s_nop 0
	v_add_f32_e32 v51, 1.0, v51
	v_rcp_f32_e32 v54, v51
	v_mul_f32_e32 v51, 0xbfb8aa3b, v53
	v_exp_f32_e32 v51, v51
	s_nop 0
	v_add_f32_e32 v51, 1.0, v51
	v_rcp_f32_e32 v55, v51
	s_nop 0
	v_pk_mul_f32 v[52:53], v[52:53], v[54:55]
	s_nop 0
	v_cvt_pk_bf16_f32 v51, v52, v53
	v_mad_i64_i32 v[52:53], s[2:3], v127, s85, v[56:57]
	global_store_dwordx4 v[52:53], v[48:51], off
	v_lshlrev_b32_e32 v54, 16, v134
	v_and_b32_e32 v55, 0xffff0000, v134
	v_pk_fma_f32 v[48:49], v[4:5], v[98:99], v[44:45]
	v_lshlrev_b32_e32 v52, 16, v135
	v_pk_fma_f32 v[48:49], v[24:25], v[80:81], v[48:49]
	v_and_b32_e32 v53, 0xffff0000, v135
	v_pk_fma_f32 v[48:49], v[32:33], v[78:79], v[48:49]
	v_lshlrev_b32_e32 v98, 16, v96
	v_pk_fma_f32 v[48:49], v[36:37], v[70:71], v[48:49]
	v_and_b32_e32 v99, 0xffff0000, v96
	v_pk_fma_f32 v[48:49], v[40:41], v[62:63], v[48:49]
	v_lshlrev_b32_e32 v96, 16, v94
	v_mul_f32_e32 v50, 0xbfb8aa3b, v48
	v_mul_f32_e32 v51, 0xbfb8aa3b, v49
	v_exp_f32_e32 v50, v50
	v_exp_f32_e32 v51, v51
	v_add_f32_e32 v50, 1.0, v50
	v_add_f32_e32 v51, 1.0, v51
	v_rcp_f32_e32 v50, v50
	v_rcp_f32_e32 v51, v51
	s_nop 0
	v_pk_mul_f32 v[48:49], v[48:49], v[50:51]
	v_pk_fma_f32 v[50:51], v[6:7], v[100:101], v[46:47]
	v_cvt_pk_bf16_f32 v48, v48, v49
	v_pk_fma_f32 v[50:51], v[26:27], v[82:83], v[50:51]
	v_lshlrev_b32_e32 v100, 16, v97
	v_pk_fma_f32 v[50:51], v[34:35], v[76:77], v[50:51]
	v_and_b32_e32 v101, 0xffff0000, v97
	v_pk_fma_f32 v[50:51], v[38:39], v[68:69], v[50:51]
	v_and_b32_e32 v97, 0xffff0000, v94
	v_pk_fma_f32 v[50:51], v[42:43], v[60:61], v[50:51]
	v_lshlrev_b32_e32 v94, 16, v95
	v_mul_f32_e32 v49, 0xbfb8aa3b, v50
	v_exp_f32_e32 v49, v49
	v_and_b32_e32 v95, 0xffff0000, v95
	v_add_f32_e32 v49, 1.0, v49
	v_rcp_f32_e32 v88, v49
	v_mul_f32_e32 v49, 0xbfb8aa3b, v51
	v_exp_f32_e32 v49, v49
	s_nop 0
	v_add_f32_e32 v49, 1.0, v49
	v_rcp_f32_e32 v89, v49
	s_nop 0
	v_pk_mul_f32 v[50:51], v[50:51], v[88:89]
	s_nop 0
	v_cvt_pk_bf16_f32 v49, v50, v51
	v_pk_fma_f32 v[50:51], v[0:1], v[116:117], v[28:29]
	s_nop 0
	v_pk_fma_f32 v[50:51], v[8:9], v[84:85], v[50:51]
	s_nop 0
	v_pk_fma_f32 v[50:51], v[12:13], v[74:75], v[50:51]
	s_nop 0
	v_pk_fma_f32 v[50:51], v[16:17], v[66:67], v[50:51]
	s_nop 0
	v_pk_fma_f32 v[50:51], v[20:21], v[54:55], v[50:51]
	s_nop 0
	v_mul_f32_e32 v88, 0xbfb8aa3b, v50
	v_mul_f32_e32 v89, 0xbfb8aa3b, v51
	v_exp_f32_e32 v88, v88
	v_exp_f32_e32 v89, v89
	v_add_f32_e32 v88, 1.0, v88
	v_add_f32_e32 v89, 1.0, v89
	v_rcp_f32_e32 v88, v88
	v_rcp_f32_e32 v89, v89
	s_nop 0
	v_pk_mul_f32 v[50:51], v[50:51], v[88:89]
	v_pk_fma_f32 v[88:89], v[2:3], v[118:119], v[30:31]
	v_cvt_pk_bf16_f32 v50, v50, v51
	v_pk_fma_f32 v[88:89], v[10:11], v[86:87], v[88:89]
	s_nop 0
	v_pk_fma_f32 v[88:89], v[14:15], v[72:73], v[88:89]
	s_nop 0
	v_pk_fma_f32 v[88:89], v[18:19], v[64:65], v[88:89]
	s_nop 0
	v_pk_fma_f32 v[88:89], v[22:23], v[52:53], v[88:89]
	s_nop 0
	v_mul_f32_e32 v51, 0xbfb8aa3b, v88
	v_exp_f32_e32 v51, v51
	s_nop 0
	v_add_f32_e32 v51, 1.0, v51
	v_rcp_f32_e32 v90, v51
	v_mul_f32_e32 v51, 0xbfb8aa3b, v89
	v_exp_f32_e32 v51, v51
	s_nop 0
	v_add_f32_e32 v51, 1.0, v51
	v_rcp_f32_e32 v91, v51
	s_nop 0
	v_pk_mul_f32 v[88:89], v[88:89], v[90:91]
	s_nop 0
	v_cvt_pk_bf16_f32 v51, v88, v89
	v_or_b32_e32 v88, 2, v125
	v_mad_i64_i32 v[88:89], s[2:3], v88, s85, v[56:57]
	global_store_dwordx4 v[88:89], v[48:51], off
; __device__ __forceinline__ float siluf_(float x) { return x * __builtin_amdgcn_rcpf(1.f + __expf(-x)); }
; #define CONV_ACC(rv, j) do { \
;         o[0] += bflo(rv.x) * wgt[j][0]; o[1] += bfhi(rv.x) * wgt[j][1]; \
;         o[2] += bflo(rv.y) * wgt[j][2]; o[3] += bfhi(rv.y) * wgt[j][3]; \
;         o[4] += bflo(rv.z) * wgt[j][4]; o[5] += bfhi(rv.z) * wgt[j][5]; \
;         o[6] += bflo(rv.w) * wgt[j][6]; o[7] += bfhi(rv.w) * wgt[j][7]; } while (0)
; __device__ __forceinline__ void conv_phase(const Params& P, const int pass, const int wvi) {
;     ...
;       for (int j = 0; j < 8; ++j) {
;         float o[8];
; #pragma unroll
;         for (int e = 0; e < 8; ++e) o[e] = bias[e];
;         CONV_ACC(R[j], 0); CONV_ACC(R[j + 1], 1); CONV_ACC(R[j + 2], 2); CONV_ACC(R[j + 3], 3); CONV_ACC(R[j + 4], 4);
;         uint4 ov;
;         ov.x = pk2(siluf_(o[0]), siluf_(o[1])); ov.y = pk2(siluf_(o[2]), siluf_(o[3]));
;         ov.z = pk2(siluf_(o[4]), siluf_(o[5])); ov.w = pk2(siluf_(o[6]), siluf_(o[7]));
;         *(uint4*)(xo + (size_t)(t0 + blk * 8 + j) * CONVD + c0) = ov;
	v_lshlrev_b32_e32 v90, 16, v112
	v_and_b32_e32 v91, 0xffff0000, v112
	v_pk_fma_f32 v[48:49], v[4:5], v[80:81], v[44:45]
	v_lshlrev_b32_e32 v88, 16, v111
	v_pk_fma_f32 v[48:49], v[24:25], v[78:79], v[48:49]
	v_and_b32_e32 v89, 0xffff0000, v111
	v_pk_fma_f32 v[48:49], v[32:33], v[70:71], v[48:49]
	s_nop 0
	v_pk_fma_f32 v[48:49], v[36:37], v[62:63], v[48:49]
	s_nop 0
	v_pk_fma_f32 v[48:49], v[40:41], v[100:101], v[48:49]
	s_nop 0
	v_mul_f32_e32 v50, 0xbfb8aa3b, v48
	v_mul_f32_e32 v51, 0xbfb8aa3b, v49
	v_exp_f32_e32 v50, v50
	v_exp_f32_e32 v51, v51
	v_add_f32_e32 v50, 1.0, v50
	v_add_f32_e32 v51, 1.0, v51
	v_rcp_f32_e32 v50, v50
	v_rcp_f32_e32 v51, v51
	s_nop 0
	v_pk_mul_f32 v[48:49], v[48:49], v[50:51]
	v_pk_fma_f32 v[50:51], v[6:7], v[82:83], v[46:47]
	v_cvt_pk_bf16_f32 v48, v48, v49
	v_pk_fma_f32 v[50:51], v[26:27], v[76:77], v[50:51]
	s_nop 0
	v_pk_fma_f32 v[50:51], v[34:35], v[68:69], v[50:51]
	s_nop 0
	v_pk_fma_f32 v[50:51], v[38:39], v[60:61], v[50:51]
	s_nop 0
	v_pk_fma_f32 v[50:51], v[42:43], v[98:99], v[50:51]
	s_nop 0
	v_mul_f32_e32 v49, 0xbfb8aa3b, v50
	v_exp_f32_e32 v49, v49
	s_nop 0
	v_add_f32_e32 v49, 1.0, v49
	v_rcp_f32_e32 v80, v49
	v_mul_f32_e32 v49, 0xbfb8aa3b, v51
	v_exp_f32_e32 v49, v49
	s_nop 0
	v_add_f32_e32 v49, 1.0, v49
	v_rcp_f32_e32 v81, v49
	s_nop 0
	v_pk_mul_f32 v[50:51], v[50:51], v[80:81]
	s_nop 0
	v_cvt_pk_bf16_f32 v49, v50, v51
	v_pk_fma_f32 v[50:51], v[0:1], v[84:85], v[28:29]
	v_lshlrev_b32_e32 v84, 16, v114
	v_pk_fma_f32 v[50:51], v[8:9], v[74:75], v[50:51]
	v_and_b32_e32 v85, 0xffff0000, v114
	v_pk_fma_f32 v[50:51], v[12:13], v[66:67], v[50:51]
	s_nop 0
	v_pk_fma_f32 v[50:51], v[16:17], v[54:55], v[50:51]
	s_nop 0
	v_pk_fma_f32 v[50:51], v[20:21], v[96:97], v[50:51]
	s_nop 0
	v_mul_f32_e32 v80, 0xbfb8aa3b, v50
	v_mul_f32_e32 v81, 0xbfb8aa3b, v51
	v_exp_f32_e32 v80, v80
	v_exp_f32_e32 v81, v81
	v_add_f32_e32 v80, 1.0, v80
	v_add_f32_e32 v81, 1.0, v81
	v_rcp_f32_e32 v80, v80
	v_rcp_f32_e32 v81, v81
	s_nop 0
	v_pk_mul_f32 v[50:51], v[50:51], v[80:81]
	v_pk_fma_f32 v[80:81], v[2:3], v[86:87], v[30:31]
	v_cvt_pk_bf16_f32 v50, v50, v51
	v_pk_fma_f32 v[80:81], v[10:11], v[72:73], v[80:81]
	v_lshlrev_b32_e32 v86, 16, v115
	v_pk_fma_f32 v[80:81], v[14:15], v[64:65], v[80:81]
	v_and_b32_e32 v87, 0xffff0000, v115
	v_pk_fma_f32 v[80:81], v[18:19], v[52:53], v[80:81]
	v_pk_fma_f32 v[72:73], v[2:3], v[72:73], v[30:31]
	v_pk_fma_f32 v[80:81], v[22:23], v[94:95], v[80:81]
	v_pk_fma_f32 v[72:73], v[10:11], v[64:65], v[72:73]
	v_mul_f32_e32 v51, 0xbfb8aa3b, v80
	v_exp_f32_e32 v51, v51
	v_pk_fma_f32 v[72:73], v[14:15], v[52:53], v[72:73]
	v_pk_fma_f32 v[64:65], v[2:3], v[64:65], v[30:31]
	v_pk_fma_f32 v[72:73], v[18:19], v[94:95], v[72:73]
	v_add_f32_e32 v51, 1.0, v51
	v_rcp_f32_e32 v82, v51
	v_mul_f32_e32 v51, 0xbfb8aa3b, v81
	v_exp_f32_e32 v51, v51
	v_pk_fma_f32 v[64:65], v[10:11], v[52:53], v[64:65]
	v_pk_fma_f32 v[52:53], v[2:3], v[52:53], v[30:31]
	v_pk_fma_f32 v[64:65], v[14:15], v[94:95], v[64:65]
	v_add_f32_e32 v51, 1.0, v51
	v_rcp_f32_e32 v83, v51
	v_pk_fma_f32 v[52:53], v[10:11], v[94:95], v[52:53]
	v_pk_mul_f32 v[80:81], v[80:81], v[82:83]
	s_nop 0
	v_cvt_pk_bf16_f32 v51, v80, v81
	v_or_b32_e32 v80, 3, v125
	v_mad_i64_i32 v[80:81], s[2:3], v80, s85, v[56:57]
	global_store_dwordx4 v[80:81], v[48:51], off
	v_lshlrev_b32_e32 v82, 16, v113
	v_and_b32_e32 v83, 0xffff0000, v113
	v_pk_fma_f32 v[48:49], v[4:5], v[78:79], v[44:45]
	v_lshlrev_b32_e32 v80, 16, v92
	v_pk_fma_f32 v[48:49], v[24:25], v[70:71], v[48:49]
	v_and_b32_e32 v81, 0xffff0000, v92
	v_pk_fma_f32 v[48:49], v[32:33], v[62:63], v[48:49]
	v_pk_fma_f32 v[72:73], v[22:23], v[80:81], v[72:73]
	v_pk_fma_f32 v[48:49], v[36:37], v[100:101], v[48:49]
	v_lshlrev_b32_e32 v92, 16, v93
	v_pk_fma_f32 v[48:49], v[40:41], v[86:87], v[48:49]
	v_and_b32_e32 v93, 0xffff0000, v93
	v_mul_f32_e32 v50, 0xbfb8aa3b, v48
	v_mul_f32_e32 v51, 0xbfb8aa3b, v49
	v_exp_f32_e32 v50, v50
	v_exp_f32_e32 v51, v51
	v_pk_fma_f32 v[64:65], v[18:19], v[80:81], v[64:65]
	v_pk_fma_f32 v[52:53], v[14:15], v[80:81], v[52:53]
	v_add_f32_e32 v50, 1.0, v50
	v_add_f32_e32 v51, 1.0, v51
	v_rcp_f32_e32 v50, v50
	v_rcp_f32_e32 v51, v51
	s_nop 0
	v_pk_mul_f32 v[48:49], v[48:49], v[50:51]
	v_pk_fma_f32 v[50:51], v[6:7], v[76:77], v[46:47]
	v_cvt_pk_bf16_f32 v48, v48, v49
	v_pk_fma_f32 v[50:51], v[26:27], v[68:69], v[50:51]
	s_nop 0
	v_pk_fma_f32 v[50:51], v[34:35], v[60:61], v[50:51]
	s_nop 0
	v_pk_fma_f32 v[50:51], v[38:39], v[98:99], v[50:51]
	s_nop 0
	v_pk_fma_f32 v[50:51], v[42:43], v[84:85], v[50:51]
	s_nop 0
	v_mul_f32_e32 v49, 0xbfb8aa3b, v50
	v_exp_f32_e32 v49, v49
	s_nop 0
	v_add_f32_e32 v49, 1.0, v49
	v_rcp_f32_e32 v76, v49
	v_mul_f32_e32 v49, 0xbfb8aa3b, v51
	v_exp_f32_e32 v49, v49
	s_nop 0
	v_add_f32_e32 v49, 1.0, v49
	v_rcp_f32_e32 v77, v49
	s_nop 0
	v_pk_mul_f32 v[50:51], v[50:51], v[76:77]
	s_nop 0
	v_cvt_pk_bf16_f32 v49, v50, v51
	v_pk_fma_f32 v[50:51], v[0:1], v[74:75], v[28:29]
	s_nop 0
	v_pk_fma_f32 v[50:51], v[8:9], v[66:67], v[50:51]
	s_nop 0
	v_pk_fma_f32 v[50:51], v[12:13], v[54:55], v[50:51]
	s_nop 0
	v_pk_fma_f32 v[50:51], v[16:17], v[96:97], v[50:51]
	s_nop 0
	v_pk_fma_f32 v[50:51], v[20:21], v[82:83], v[50:51]
	s_nop 0
	v_mul_f32_e32 v74, 0xbfb8aa3b, v50
	v_mul_f32_e32 v75, 0xbfb8aa3b, v51
	v_exp_f32_e32 v74, v74
	v_exp_f32_e32 v75, v75
	v_add_f32_e32 v74, 1.0, v74
	v_add_f32_e32 v75, 1.0, v75
	v_rcp_f32_e32 v74, v74
	v_rcp_f32_e32 v75, v75
	s_nop 0
	v_pk_mul_f32 v[50:51], v[50:51], v[74:75]
	s_nop 0
	v_cvt_pk_bf16_f32 v50, v50, v51
	v_mul_f32_e32 v51, 0xbfb8aa3b, v72
	v_exp_f32_e32 v51, v51
	s_nop 0
	v_add_f32_e32 v51, 1.0, v51
	v_rcp_f32_e32 v74, v51
	v_mul_f32_e32 v51, 0xbfb8aa3b, v73
; __device__ __forceinline__ float siluf_(float x) { return x * __builtin_amdgcn_rcpf(1.f + __expf(-x)); }
; #define CONV_ACC(rv, j) do { \
;         o[0] += bflo(rv.x) * wgt[j][0]; o[1] += bfhi(rv.x) * wgt[j][1]; \
;         o[2] += bflo(rv.y) * wgt[j][2]; o[3] += bfhi(rv.y) * wgt[j][3]; \
;         o[4] += bflo(rv.z) * wgt[j][4]; o[5] += bfhi(rv.z) * wgt[j][5]; \
;         o[6] += bflo(rv.w) * wgt[j][6]; o[7] += bfhi(rv.w) * wgt[j][7]; } while (0)
; __device__ __forceinline__ void conv_phase(const Params& P, const int pass, const int wvi) {
;     ...
;       for (int j = 0; j < 8; ++j) {
;         float o[8];
; #pragma unroll
;         for (int e = 0; e < 8; ++e) o[e] = bias[e];
;         CONV_ACC(R[j], 0); CONV_ACC(R[j + 1], 1); CONV_ACC(R[j + 2], 2); CONV_ACC(R[j + 3], 3); CONV_ACC(R[j + 4], 4);
;         uint4 ov;
;         ov.x = pk2(siluf_(o[0]), siluf_(o[1])); ov.y = pk2(siluf_(o[2]), siluf_(o[3]));
;         ov.z = pk2(siluf_(o[4]), siluf_(o[5])); ov.w = pk2(siluf_(o[6]), siluf_(o[7]));
;         *(uint4*)(xo + (size_t)(t0 + blk * 8 + j) * CONVD + c0) = ov;
	v_exp_f32_e32 v51, v51
	s_nop 0
	v_add_f32_e32 v51, 1.0, v51
	v_rcp_f32_e32 v75, v51
	s_nop 0
	v_pk_mul_f32 v[72:73], v[72:73], v[74:75]
	s_nop 0
	v_cvt_pk_bf16_f32 v51, v72, v73
	v_or_b32_e32 v72, 4, v125
	v_mad_i64_i32 v[72:73], s[2:3], v72, s85, v[56:57]
	global_store_dwordx4 v[72:73], v[48:51], off
	v_lshlrev_b32_e32 v74, 16, v110
	v_and_b32_e32 v75, 0xffff0000, v110
	v_pk_fma_f32 v[48:49], v[4:5], v[70:71], v[44:45]
	v_pk_fma_f32 v[64:65], v[22:23], v[74:75], v[64:65]
	v_pk_fma_f32 v[48:49], v[24:25], v[62:63], v[48:49]
	v_lshlrev_b32_e32 v70, 16, v109
	v_pk_fma_f32 v[48:49], v[32:33], v[100:101], v[48:49]
	v_and_b32_e32 v71, 0xffff0000, v109
	v_pk_fma_f32 v[48:49], v[36:37], v[86:87], v[48:49]
	v_pk_fma_f32 v[52:53], v[18:19], v[74:75], v[52:53]
	v_pk_fma_f32 v[48:49], v[40:41], v[92:93], v[48:49]
	s_nop 0
	v_mul_f32_e32 v50, 0xbfb8aa3b, v48
	v_mul_f32_e32 v51, 0xbfb8aa3b, v49
	v_exp_f32_e32 v50, v50
	v_exp_f32_e32 v51, v51
	v_add_f32_e32 v50, 1.0, v50
	v_add_f32_e32 v51, 1.0, v51
	v_rcp_f32_e32 v50, v50
	v_rcp_f32_e32 v51, v51
	s_nop 0
	v_pk_mul_f32 v[48:49], v[48:49], v[50:51]
	v_pk_fma_f32 v[50:51], v[6:7], v[68:69], v[46:47]
	v_cvt_pk_bf16_f32 v48, v48, v49
	v_pk_fma_f32 v[50:51], v[26:27], v[60:61], v[50:51]
	s_nop 0
	v_pk_fma_f32 v[50:51], v[34:35], v[98:99], v[50:51]
	s_nop 0
	v_pk_fma_f32 v[50:51], v[38:39], v[84:85], v[50:51]
	s_nop 0
	v_pk_fma_f32 v[50:51], v[42:43], v[90:91], v[50:51]
	s_nop 0
	v_mul_f32_e32 v49, 0xbfb8aa3b, v50
	v_exp_f32_e32 v49, v49
	s_nop 0
	v_add_f32_e32 v49, 1.0, v49
	v_rcp_f32_e32 v68, v49
	v_mul_f32_e32 v49, 0xbfb8aa3b, v51
	v_exp_f32_e32 v49, v49
	s_nop 0
	v_add_f32_e32 v49, 1.0, v49
	v_rcp_f32_e32 v69, v49
	s_nop 0
	v_pk_mul_f32 v[50:51], v[50:51], v[68:69]
	s_nop 0
	v_cvt_pk_bf16_f32 v49, v50, v51
	v_pk_fma_f32 v[50:51], v[0:1], v[66:67], v[28:29]
	v_lshlrev_b32_e32 v68, 16, v108
	v_pk_fma_f32 v[50:51], v[8:9], v[54:55], v[50:51]
	v_and_b32_e32 v69, 0xffff0000, v108
	v_pk_fma_f32 v[50:51], v[12:13], v[96:97], v[50:51]
	s_nop 0
	v_pk_fma_f32 v[50:51], v[16:17], v[82:83], v[50:51]
	s_nop 0
	v_pk_fma_f32 v[50:51], v[20:21], v[88:89], v[50:51]
	s_nop 0
	v_mul_f32_e32 v66, 0xbfb8aa3b, v50
	v_mul_f32_e32 v67, 0xbfb8aa3b, v51
	v_exp_f32_e32 v66, v66
	v_exp_f32_e32 v67, v67
	v_add_f32_e32 v66, 1.0, v66
	v_add_f32_e32 v67, 1.0, v67
	v_rcp_f32_e32 v66, v66
	v_rcp_f32_e32 v67, v67
	s_nop 0
	v_pk_mul_f32 v[50:51], v[50:51], v[66:67]
	s_nop 0
	v_cvt_pk_bf16_f32 v50, v50, v51
	v_mul_f32_e32 v51, 0xbfb8aa3b, v64
	v_exp_f32_e32 v51, v51
	s_nop 0
	v_add_f32_e32 v51, 1.0, v51
	v_rcp_f32_e32 v66, v51
	v_mul_f32_e32 v51, 0xbfb8aa3b, v65
	v_exp_f32_e32 v51, v51
	s_nop 0
	v_add_f32_e32 v51, 1.0, v51
	v_rcp_f32_e32 v67, v51
	s_nop 0
	v_pk_mul_f32 v[64:65], v[64:65], v[66:67]
	s_nop 0
	v_cvt_pk_bf16_f32 v51, v64, v65
	v_or_b32_e32 v64, 5, v125
	v_mad_i64_i32 v[64:65], s[2:3], v64, s85, v[56:57]
	global_store_dwordx4 v[64:65], v[48:51], off
	v_lshlrev_b32_e32 v66, 16, v107
	v_and_b32_e32 v67, 0xffff0000, v107
	v_pk_fma_f32 v[48:49], v[4:5], v[62:63], v[44:45]
	v_lshlrev_b32_e32 v64, 16, v106
	v_pk_fma_f32 v[48:49], v[24:25], v[100:101], v[48:49]
	v_and_b32_e32 v65, 0xffff0000, v106
	v_pk_fma_f32 v[48:49], v[32:33], v[86:87], v[48:49]
	v_pk_fma_f32 v[52:53], v[22:23], v[64:65], v[52:53]
	v_pk_fma_f32 v[48:49], v[36:37], v[92:93], v[48:49]
	v_lshlrev_b32_e32 v62, 16, v105
	v_pk_fma_f32 v[48:49], v[40:41], v[70:71], v[48:49]
	v_and_b32_e32 v63, 0xffff0000, v105
	v_mul_f32_e32 v50, 0xbfb8aa3b, v48
	v_mul_f32_e32 v51, 0xbfb8aa3b, v49
	v_exp_f32_e32 v50, v50
	v_exp_f32_e32 v51, v51
	v_or_b32_e32 v106, 8, v125
	v_add_f32_e32 v50, 1.0, v50
	v_add_f32_e32 v51, 1.0, v51
	v_rcp_f32_e32 v50, v50
	v_rcp_f32_e32 v51, v51
	s_nop 0
	v_pk_mul_f32 v[48:49], v[48:49], v[50:51]
	v_pk_fma_f32 v[50:51], v[6:7], v[60:61], v[46:47]
	v_cvt_pk_bf16_f32 v48, v48, v49
	v_pk_fma_f32 v[50:51], v[26:27], v[98:99], v[50:51]
	s_nop 0
	v_pk_fma_f32 v[50:51], v[34:35], v[84:85], v[50:51]
	s_nop 0
	v_pk_fma_f32 v[50:51], v[38:39], v[90:91], v[50:51]
	s_nop 0
	v_pk_fma_f32 v[50:51], v[42:43], v[68:69], v[50:51]
	s_nop 0
	v_mul_f32_e32 v49, 0xbfb8aa3b, v50
	v_exp_f32_e32 v49, v49
	s_nop 0
	v_add_f32_e32 v49, 1.0, v49
	v_rcp_f32_e32 v60, v49
	v_mul_f32_e32 v49, 0xbfb8aa3b, v51
	v_exp_f32_e32 v49, v49
	s_nop 0
	v_add_f32_e32 v49, 1.0, v49
	v_rcp_f32_e32 v61, v49
	s_nop 0
	v_pk_mul_f32 v[50:51], v[50:51], v[60:61]
	s_nop 0
	v_cvt_pk_bf16_f32 v49, v50, v51
	v_pk_fma_f32 v[50:51], v[0:1], v[54:55], v[28:29]
	v_lshlrev_b32_e32 v60, 16, v104
	v_pk_fma_f32 v[50:51], v[8:9], v[96:97], v[50:51]
	v_and_b32_e32 v61, 0xffff0000, v104
	v_pk_fma_f32 v[50:51], v[12:13], v[82:83], v[50:51]
	s_nop 0
	v_pk_fma_f32 v[50:51], v[16:17], v[88:89], v[50:51]
	s_nop 0
	v_pk_fma_f32 v[50:51], v[20:21], v[66:67], v[50:51]
	s_nop 0
	v_mul_f32_e32 v54, 0xbfb8aa3b, v50
	v_mul_f32_e32 v55, 0xbfb8aa3b, v51
	v_exp_f32_e32 v54, v54
	v_exp_f32_e32 v55, v55
	v_add_f32_e32 v54, 1.0, v54
	v_add_f32_e32 v55, 1.0, v55
	v_rcp_f32_e32 v54, v54
	v_rcp_f32_e32 v55, v55
	s_nop 0
	v_pk_mul_f32 v[50:51], v[50:51], v[54:55]
	s_nop 0
	v_cvt_pk_bf16_f32 v50, v50, v51
	v_mul_f32_e32 v51, 0xbfb8aa3b, v52
	v_exp_f32_e32 v51, v51
	s_nop 0
	v_add_f32_e32 v51, 1.0, v51
	v_rcp_f32_e32 v54, v51
	v_mul_f32_e32 v51, 0xbfb8aa3b, v53
	v_exp_f32_e32 v51, v51
	s_nop 0
	v_add_f32_e32 v51, 1.0, v51
	v_rcp_f32_e32 v55, v51
	s_nop 0
	v_pk_mul_f32 v[52:53], v[52:53], v[54:55]
	s_nop 0
	v_cvt_pk_bf16_f32 v51, v52, v53
	v_or_b32_e32 v52, 6, v125
	v_mad_i64_i32 v[52:53], s[2:3], v52, s85, v[56:57]
	global_store_dwordx4 v[52:53], v[48:51], off
	v_lshlrev_b32_e32 v54, 16, v103
	v_and_b32_e32 v55, 0xffff0000, v103
; __device__ __forceinline__ float siluf_(float x) { return x * __builtin_amdgcn_rcpf(1.f + __expf(-x)); }
; #define CONV_ACC(rv, j) do { \
;         o[0] += bflo(rv.x) * wgt[j][0]; o[1] += bfhi(rv.x) * wgt[j][1]; \
;         o[2] += bflo(rv.y) * wgt[j][2]; o[3] += bfhi(rv.y) * wgt[j][3]; \
;         o[4] += bflo(rv.z) * wgt[j][4]; o[5] += bfhi(rv.z) * wgt[j][5]; \
;         o[6] += bflo(rv.w) * wgt[j][6]; o[7] += bfhi(rv.w) * wgt[j][7]; } while (0)
; __device__ __forceinline__ void conv_phase(const Params& P, const int pass, const int wvi) {
;     ...
;     for (int blk = 0; blk < TCH / 8; ++blk) {
; #pragma unroll
;       for (int j = 0; j < 8; ++j) {
;         const int tt2 = blk * 8 + j + 2;
;         const bool v4 = (pos0 + tt2 < S);
;         const uint4 l4 = *(const uint4*)(xin + (size_t)(v4 ? t0 + tt2 : t0) * CONVD + c0);
;         R[4 + j].x = v4 ? l4.x : 0u; R[4 + j].y = v4 ? l4.y : 0u; R[4 + j].z = v4 ? l4.z : 0u; R[4 + j].w = v4 ? l4.w : 0u;
;       }
; #pragma unroll
;       for (int j = 0; j < 8; ++j) {
;         float o[8];
; #pragma unroll
;         for (int e = 0; e < 8; ++e) o[e] = bias[e];
;         CONV_ACC(R[j], 0); CONV_ACC(R[j + 1], 1); CONV_ACC(R[j + 2], 2); CONV_ACC(R[j + 3], 3); CONV_ACC(R[j + 4], 4);
;         uint4 ov;
;         ov.x = pk2(siluf_(o[0]), siluf_(o[1])); ov.y = pk2(siluf_(o[2]), siluf_(o[3]));
;         ov.z = pk2(siluf_(o[4]), siluf_(o[5])); ov.w = pk2(siluf_(o[6]), siluf_(o[7]));
;         *(uint4*)(xo + (size_t)(t0 + blk * 8 + j) * CONVD + c0) = ov;
	v_pk_fma_f32 v[48:49], v[4:5], v[100:101], v[44:45]
	v_lshlrev_b32_e32 v52, 16, v102
	v_pk_fma_f32 v[48:49], v[24:25], v[86:87], v[48:49]
	v_and_b32_e32 v53, 0xffff0000, v102
	v_pk_fma_f32 v[48:49], v[32:33], v[92:93], v[48:49]
	s_nop 0
	v_pk_fma_f32 v[48:49], v[36:37], v[70:71], v[48:49]
	s_nop 0
	v_pk_fma_f32 v[48:49], v[40:41], v[62:63], v[48:49]
	s_nop 0
	v_mul_f32_e32 v50, 0xbfb8aa3b, v48
	v_mul_f32_e32 v51, 0xbfb8aa3b, v49
	v_exp_f32_e32 v50, v50
	v_exp_f32_e32 v51, v51
	v_add_f32_e32 v50, 1.0, v50
	v_add_f32_e32 v51, 1.0, v51
	v_rcp_f32_e32 v50, v50
	v_rcp_f32_e32 v51, v51
	s_nop 0
	v_pk_mul_f32 v[48:49], v[48:49], v[50:51]
	v_pk_fma_f32 v[50:51], v[6:7], v[98:99], v[46:47]
	v_cvt_pk_bf16_f32 v48, v48, v49
	v_pk_fma_f32 v[50:51], v[26:27], v[84:85], v[50:51]
	s_nop 0
	v_pk_fma_f32 v[50:51], v[34:35], v[90:91], v[50:51]
	s_nop 0
	v_pk_fma_f32 v[50:51], v[38:39], v[68:69], v[50:51]
	s_nop 0
	v_pk_fma_f32 v[50:51], v[42:43], v[60:61], v[50:51]
	s_nop 0
	v_mul_f32_e32 v49, 0xbfb8aa3b, v50
	v_exp_f32_e32 v49, v49
	s_nop 0
	v_add_f32_e32 v49, 1.0, v49
	v_rcp_f32_e32 v72, v49
	v_mul_f32_e32 v49, 0xbfb8aa3b, v51
	v_exp_f32_e32 v49, v49
	s_nop 0
	v_add_f32_e32 v49, 1.0, v49
	v_rcp_f32_e32 v73, v49
	s_nop 0
	v_pk_mul_f32 v[50:51], v[50:51], v[72:73]
	s_nop 0
	v_cvt_pk_bf16_f32 v49, v50, v51
	v_pk_fma_f32 v[50:51], v[0:1], v[96:97], v[28:29]
	s_nop 0
	v_pk_fma_f32 v[50:51], v[8:9], v[82:83], v[50:51]
	s_nop 0
	v_pk_fma_f32 v[50:51], v[12:13], v[88:89], v[50:51]
	s_nop 0
	v_pk_fma_f32 v[50:51], v[16:17], v[66:67], v[50:51]
	s_nop 0
	v_pk_fma_f32 v[50:51], v[20:21], v[54:55], v[50:51]
	s_nop 0
	v_mul_f32_e32 v72, 0xbfb8aa3b, v50
	v_mul_f32_e32 v73, 0xbfb8aa3b, v51
	v_exp_f32_e32 v72, v72
	v_exp_f32_e32 v73, v73
	v_add_f32_e32 v72, 1.0, v72
	v_add_f32_e32 v73, 1.0, v73
	v_rcp_f32_e32 v72, v72
	v_rcp_f32_e32 v73, v73
	s_nop 0
	v_pk_mul_f32 v[50:51], v[50:51], v[72:73]
	v_pk_fma_f32 v[72:73], v[2:3], v[94:95], v[30:31]
	v_cvt_pk_bf16_f32 v50, v50, v51
	v_pk_fma_f32 v[72:73], v[10:11], v[80:81], v[72:73]
	s_nop 0
	v_pk_fma_f32 v[72:73], v[14:15], v[74:75], v[72:73]
	s_nop 0
	v_pk_fma_f32 v[72:73], v[18:19], v[64:65], v[72:73]
	s_nop 0
	v_pk_fma_f32 v[72:73], v[22:23], v[52:53], v[72:73]
	s_nop 0
	v_mul_f32_e32 v51, 0xbfb8aa3b, v72
	v_exp_f32_e32 v51, v51
	s_nop 0
	v_add_f32_e32 v51, 1.0, v51
	v_rcp_f32_e32 v76, v51
	v_mul_f32_e32 v51, 0xbfb8aa3b, v73
	v_exp_f32_e32 v51, v51
	s_nop 0
	v_add_f32_e32 v51, 1.0, v51
	v_rcp_f32_e32 v77, v51
	s_nop 0
	v_pk_mul_f32 v[72:73], v[72:73], v[76:77]
	s_nop 0
	v_cvt_pk_bf16_f32 v51, v72, v73
	v_or_b32_e32 v72, 7, v125
	v_mad_i64_i32 v[72:73], s[2:3], v72, s85, v[56:57]
	global_store_dwordx4 v[72:73], v[48:51], off
	v_cmp_lt_i32_e32 vcc, 10, v126
	s_nop 1
	v_cndmask_b32_e64 v210, 0, 10, vcc
	v_or_b32_e32 v210, v210, v125
	v_mad_i64_i32 v[210:211], s[2:3], v210, s85, v[58:59]
	global_load_dwordx4 v[210:213], v[210:211], off
	v_cmp_lt_i32_e32 vcc, 11, v126
	s_nop 1
	v_cndmask_b32_e64 v214, 0, 11, vcc
	v_or_b32_e32 v214, v214, v125
	v_mad_i64_i32 v[214:215], s[2:3], v214, s85, v[58:59]
	global_load_dwordx4 v[214:217], v[214:215], off
	v_cmp_lt_i32_e32 vcc, 12, v126
	s_nop 1
	v_cndmask_b32_e64 v218, 0, 12, vcc
	v_or_b32_e32 v218, v218, v125
	v_mad_i64_i32 v[218:219], s[2:3], v218, s85, v[58:59]
	global_load_dwordx4 v[218:221], v[218:219], off
	v_cmp_lt_i32_e32 vcc, 13, v126
	s_nop 1
	v_cndmask_b32_e64 v222, 0, 13, vcc
	v_or_b32_e32 v222, v222, v125
	v_mad_i64_i32 v[222:223], s[2:3], v222, s85, v[58:59]
	global_load_dwordx4 v[222:225], v[222:223], off
	v_cmp_lt_i32_e32 vcc, 14, v126
	s_nop 1
	v_cndmask_b32_e64 v226, 0, 14, vcc
	v_or_b32_e32 v226, v226, v125
	v_mad_i64_i32 v[226:227], s[2:3], v226, s85, v[58:59]
	global_load_dwordx4 v[226:229], v[226:227], off
	v_cmp_lt_i32_e32 vcc, 15, v126
	s_nop 1
	v_cndmask_b32_e64 v230, 0, 15, vcc
	v_or_b32_e32 v230, v230, v125
	v_mad_i64_i32 v[230:231], s[2:3], v230, s85, v[58:59]
	global_load_dwordx4 v[230:233], v[230:231], off
	v_cmp_lt_i32_e32 vcc, 16, v126
	s_nop 1
	v_cndmask_b32_e64 v234, 0, 16, vcc
	v_or_b32_e32 v234, v234, v125
	v_mad_i64_i32 v[234:235], s[2:3], v234, s85, v[58:59]
	global_load_dwordx4 v[234:237], v[234:235], off
	v_cmp_lt_i32_e32 vcc, 17, v126
	s_nop 1
	v_cndmask_b32_e64 v238, 0, 17, vcc
	v_or_b32_e32 v238, v238, v125
	v_mad_i64_i32 v[238:239], s[2:3], v238, s85, v[58:59]
	global_load_dwordx4 v[238:241], v[238:239], off
	s_waitcnt vmcnt(7)
	v_cmp_lt_i32_e32 vcc, 10, v126
	s_nop 1
	v_cndmask_b32_e32 v72, 0, v210, vcc
	v_cndmask_b32_e32 v73, 0, v211, vcc
	v_cndmask_b32_e32 v76, 0, v212, vcc
	v_cndmask_b32_e32 v77, 0, v213, vcc
	s_waitcnt vmcnt(6)
	v_cmp_lt_i32_e32 vcc, 11, v126
	s_nop 1
	v_cndmask_b32_e32 v78, 0, v214, vcc
	v_cndmask_b32_e32 v79, 0, v215, vcc
	v_cndmask_b32_e32 v101, 0, v216, vcc
	v_cndmask_b32_e32 v105, 0, v217, vcc
	s_waitcnt vmcnt(5)
	v_cmp_lt_i32_e32 vcc, 12, v126
	s_nop 1
	v_cndmask_b32_e32 v100, 0, v218, vcc
	v_cndmask_b32_e32 v96, 0, v219, vcc
	v_cndmask_b32_e32 v97, 0, v220, vcc
	v_cndmask_b32_e32 v104, 0, v221, vcc
	s_waitcnt vmcnt(4)
	v_cmp_lt_i32_e32 vcc, 13, v126
	s_nop 1
	v_cndmask_b32_e32 v98, 0, v222, vcc
	v_cndmask_b32_e32 v99, 0, v223, vcc
	v_cndmask_b32_e32 v136, 0, v224, vcc
	v_cndmask_b32_e32 v135, 0, v225, vcc
	s_waitcnt vmcnt(3)
	v_cmp_lt_i32_e32 vcc, 14, v126
	s_nop 1
	v_cndmask_b32_e32 v134, 0, v226, vcc
	v_cndmask_b32_e32 v133, 0, v227, vcc
	v_cndmask_b32_e32 v132, 0, v228, vcc
	v_cndmask_b32_e32 v131, 0, v229, vcc
	s_waitcnt vmcnt(2)
	v_cmp_lt_i32_e32 vcc, 15, v126
	s_nop 1
	v_cndmask_b32_e32 v130, 0, v230, vcc
	v_cndmask_b32_e32 v129, 0, v231, vcc
	v_cndmask_b32_e32 v128, 0, v232, vcc
	v_cndmask_b32_e32 v127, 0, v233, vcc
	s_waitcnt vmcnt(1)
; __device__ __forceinline__ float siluf_(float x) { return x * __builtin_amdgcn_rcpf(1.f + __expf(-x)); }
; #define CONV_ACC(rv, j) do { \
;         o[0] += bflo(rv.x) * wgt[j][0]; o[1] += bfhi(rv.x) * wgt[j][1]; \
;         o[2] += bflo(rv.y) * wgt[j][2]; o[3] += bfhi(rv.y) * wgt[j][3]; \
;         o[4] += bflo(rv.z) * wgt[j][4]; o[5] += bfhi(rv.z) * wgt[j][5]; \
;         o[6] += bflo(rv.w) * wgt[j][6]; o[7] += bfhi(rv.w) * wgt[j][7]; } while (0)
; __device__ __forceinline__ void conv_phase(const Params& P, const int pass, const int wvi) {
;     ...
;     for (int blk = 0; blk < TCH / 8; ++blk) {
; #pragma unroll
;       for (int j = 0; j < 8; ++j) {
;         const int tt2 = blk * 8 + j + 2;
;         const bool v4 = (pos0 + tt2 < S);
;         const uint4 l4 = *(const uint4*)(xin + (size_t)(v4 ? t0 + tt2 : t0) * CONVD + c0);
;         R[4 + j].x = v4 ? l4.x : 0u; R[4 + j].y = v4 ? l4.y : 0u; R[4 + j].z = v4 ? l4.z : 0u; R[4 + j].w = v4 ? l4.w : 0u;
;       }
; #pragma unroll
;       for (int j = 0; j < 8; ++j) {
;         float o[8];
; #pragma unroll
;         for (int e = 0; e < 8; ++e) o[e] = bias[e];
;         CONV_ACC(R[j], 0); CONV_ACC(R[j + 1], 1); CONV_ACC(R[j + 2], 2); CONV_ACC(R[j + 3], 3); CONV_ACC(R[j + 4], 4);
;         uint4 ov;
;         ov.x = pk2(siluf_(o[0]), siluf_(o[1])); ov.y = pk2(siluf_(o[2]), siluf_(o[3]));
;         ov.z = pk2(siluf_(o[4]), siluf_(o[5])); ov.w = pk2(siluf_(o[6]), siluf_(o[7]));
;         *(uint4*)(xo + (size_t)(t0 + blk * 8 + j) * CONVD + c0) = ov;
	v_cmp_lt_i32_e32 vcc, 16, v126
	s_nop 1
	v_cndmask_b32_e32 v119, 0, v234, vcc
	v_cndmask_b32_e32 v118, 0, v235, vcc
	v_cndmask_b32_e32 v117, 0, v236, vcc
	v_cndmask_b32_e32 v116, 0, v237, vcc
	s_waitcnt vmcnt(0)
	v_cmp_lt_i32_e32 vcc, 17, v126
	s_nop 1
	v_cndmask_b32_e32 v115, 0, v238, vcc
	v_cndmask_b32_e32 v114, 0, v239, vcc
	v_cndmask_b32_e32 v113, 0, v240, vcc
	v_cndmask_b32_e32 v112, 0, v241, vcc
	v_lshlrev_b32_e32 v110, 16, v72
	v_and_b32_e32 v111, 0xffff0000, v72
	v_lshlrev_b32_e32 v108, 16, v73
	v_and_b32_e32 v109, 0xffff0000, v73
	v_lshlrev_b32_e32 v102, 16, v76
	v_and_b32_e32 v103, 0xffff0000, v76
	v_lshlrev_b32_e32 v94, 16, v77
	v_and_b32_e32 v95, 0xffff0000, v77
	v_and_b32_e32 v107, 0xffff0000, v100
	s_nop 0
	v_pk_fma_f32 v[48:49], v[4:5], v[86:87], v[44:45]
	s_nop 0
	v_pk_fma_f32 v[48:49], v[24:25], v[92:93], v[48:49]
	s_nop 0
	v_pk_fma_f32 v[48:49], v[32:33], v[70:71], v[48:49]
	v_lshlrev_b32_e32 v86, 16, v136
	v_pk_fma_f32 v[48:49], v[36:37], v[62:63], v[48:49]
	v_and_b32_e32 v87, 0xffff0000, v136
	v_pk_fma_f32 v[48:49], v[40:41], v[110:111], v[48:49]
	v_cmp_lt_i32_e32 vcc, 18, v126
	v_mul_f32_e32 v50, 0xbfb8aa3b, v48
	v_mul_f32_e32 v51, 0xbfb8aa3b, v49
	v_exp_f32_e32 v50, v50
	v_exp_f32_e32 v51, v51
	v_add_f32_e32 v50, 1.0, v50
	v_add_f32_e32 v51, 1.0, v51
	v_rcp_f32_e32 v50, v50
	v_rcp_f32_e32 v51, v51
	s_nop 0
	v_pk_mul_f32 v[48:49], v[48:49], v[50:51]
	v_pk_fma_f32 v[50:51], v[6:7], v[84:85], v[46:47]
	v_cvt_pk_bf16_f32 v48, v48, v49
	v_pk_fma_f32 v[50:51], v[26:27], v[90:91], v[50:51]
	v_lshlrev_b32_e32 v84, 16, v104
	v_pk_fma_f32 v[50:51], v[34:35], v[68:69], v[50:51]
	v_and_b32_e32 v85, 0xffff0000, v104
	v_pk_fma_f32 v[50:51], v[38:39], v[60:61], v[50:51]
	v_lshlrev_b32_e32 v104, 16, v98
	v_pk_fma_f32 v[50:51], v[42:43], v[108:109], v[50:51]
	s_nop 0
	v_mul_f32_e32 v49, 0xbfb8aa3b, v50
	v_exp_f32_e32 v49, v49
	s_nop 0
	v_add_f32_e32 v49, 1.0, v49
	v_rcp_f32_e32 v72, v49
	v_mul_f32_e32 v49, 0xbfb8aa3b, v51
	v_exp_f32_e32 v49, v49
	s_nop 0
	v_add_f32_e32 v49, 1.0, v49
	v_rcp_f32_e32 v73, v49
	s_nop 0
	v_pk_mul_f32 v[50:51], v[50:51], v[72:73]
	s_nop 0
	v_cvt_pk_bf16_f32 v49, v50, v51
	v_pk_fma_f32 v[50:51], v[0:1], v[82:83], v[28:29]
	s_nop 0
	v_pk_fma_f32 v[50:51], v[8:9], v[88:89], v[50:51]
	s_nop 0
	v_pk_fma_f32 v[50:51], v[12:13], v[66:67], v[50:51]
	s_nop 0
	v_pk_fma_f32 v[50:51], v[16:17], v[54:55], v[50:51]
	s_nop 0
	v_pk_fma_f32 v[50:51], v[20:21], v[102:103], v[50:51]
	s_nop 0
	v_mul_f32_e32 v72, 0xbfb8aa3b, v50
	v_mul_f32_e32 v73, 0xbfb8aa3b, v51
	v_exp_f32_e32 v72, v72
	v_exp_f32_e32 v73, v73
	v_add_f32_e32 v72, 1.0, v72
	v_add_f32_e32 v73, 1.0, v73
	v_rcp_f32_e32 v72, v72
	v_rcp_f32_e32 v73, v73
	s_nop 0
	v_pk_mul_f32 v[50:51], v[50:51], v[72:73]
	v_pk_fma_f32 v[72:73], v[2:3], v[80:81], v[30:31]
	v_cvt_pk_bf16_f32 v50, v50, v51
	v_pk_fma_f32 v[72:73], v[10:11], v[74:75], v[72:73]
	v_lshlrev_b32_e32 v80, 16, v78
	v_pk_fma_f32 v[72:73], v[14:15], v[64:65], v[72:73]
	v_and_b32_e32 v81, 0xffff0000, v78
	v_pk_fma_f32 v[72:73], v[18:19], v[52:53], v[72:73]
	v_lshlrev_b32_e32 v78, 16, v79
	v_pk_fma_f32 v[72:73], v[22:23], v[94:95], v[72:73]
	v_and_b32_e32 v79, 0xffff0000, v79
	v_mul_f32_e32 v51, 0xbfb8aa3b, v72
	v_exp_f32_e32 v51, v51
	v_pk_fma_f32 v[74:75], v[2:3], v[74:75], v[30:31]
	v_add_f32_e32 v51, 1.0, v51
	v_rcp_f32_e32 v76, v51
	v_mul_f32_e32 v51, 0xbfb8aa3b, v73
	v_exp_f32_e32 v51, v51
	v_pk_fma_f32 v[74:75], v[10:11], v[64:65], v[74:75]
	v_pk_fma_f32 v[64:65], v[2:3], v[64:65], v[30:31]
	v_pk_fma_f32 v[74:75], v[14:15], v[52:53], v[74:75]
	v_add_f32_e32 v51, 1.0, v51
	v_rcp_f32_e32 v77, v51
	v_pk_fma_f32 v[74:75], v[18:19], v[94:95], v[74:75]
	v_pk_fma_f32 v[64:65], v[10:11], v[52:53], v[64:65]
	v_pk_fma_f32 v[52:53], v[2:3], v[52:53], v[30:31]
	v_pk_mul_f32 v[72:73], v[72:73], v[76:77]
	v_lshlrev_b32_e32 v76, 16, v101
	v_cvt_pk_bf16_f32 v51, v72, v73
	v_mad_i64_i32 v[72:73], s[2:3], v106, s85, v[56:57]
	global_store_dwordx4 v[72:73], v[48:51], off
	v_and_b32_e32 v77, 0xffff0000, v101
	v_lshlrev_b32_e32 v72, 16, v105
	v_pk_fma_f32 v[48:49], v[4:5], v[92:93], v[44:45]
	v_and_b32_e32 v73, 0xffff0000, v105
	v_pk_fma_f32 v[48:49], v[24:25], v[70:71], v[48:49]
	v_pk_fma_f32 v[74:75], v[22:23], v[72:73], v[74:75]
	v_pk_fma_f32 v[48:49], v[32:33], v[62:63], v[48:49]
	v_lshlrev_b32_e32 v106, 16, v100
	v_pk_fma_f32 v[48:49], v[36:37], v[110:111], v[48:49]
	v_lshlrev_b32_e32 v100, 16, v96
	v_pk_fma_f32 v[48:49], v[40:41], v[80:81], v[48:49]
	v_and_b32_e32 v101, 0xffff0000, v96
	v_mul_f32_e32 v50, 0xbfb8aa3b, v48
	v_mul_f32_e32 v51, 0xbfb8aa3b, v49
	v_exp_f32_e32 v50, v50
	v_exp_f32_e32 v51, v51
	v_lshlrev_b32_e32 v96, 16, v97
	v_and_b32_e32 v97, 0xffff0000, v97
	v_add_f32_e32 v50, 1.0, v50
	v_add_f32_e32 v51, 1.0, v51
	v_rcp_f32_e32 v50, v50
	v_rcp_f32_e32 v51, v51
	v_pk_fma_f32 v[64:65], v[14:15], v[94:95], v[64:65]
	v_and_b32_e32 v105, 0xffff0000, v98
	v_pk_fma_f32 v[64:65], v[18:19], v[72:73], v[64:65]
	v_pk_mul_f32 v[48:49], v[48:49], v[50:51]
	v_pk_fma_f32 v[50:51], v[6:7], v[90:91], v[46:47]
	v_cvt_pk_bf16_f32 v48, v48, v49
	v_pk_fma_f32 v[50:51], v[26:27], v[68:69], v[50:51]
	v_pk_fma_f32 v[64:65], v[22:23], v[84:85], v[64:65]
	v_pk_fma_f32 v[50:51], v[34:35], v[60:61], v[50:51]
	v_lshlrev_b32_e32 v98, 16, v99
	v_pk_fma_f32 v[50:51], v[38:39], v[108:109], v[50:51]
	v_and_b32_e32 v99, 0xffff0000, v99
	v_pk_fma_f32 v[50:51], v[42:43], v[78:79], v[50:51]
	v_pk_fma_f32 v[52:53], v[10:11], v[94:95], v[52:53]
	v_mul_f32_e32 v49, 0xbfb8aa3b, v50
	v_exp_f32_e32 v49, v49
	v_pk_fma_f32 v[52:53], v[14:15], v[72:73], v[52:53]
	v_lshlrev_b32_e32 v92, 16, v129
	v_pk_fma_f32 v[52:53], v[18:19], v[84:85], v[52:53]
; __device__ __forceinline__ float siluf_(float x) { return x * __builtin_amdgcn_rcpf(1.f + __expf(-x)); }
; #define CONV_ACC(rv, j) do { \
;         o[0] += bflo(rv.x) * wgt[j][0]; o[1] += bfhi(rv.x) * wgt[j][1]; \
;         o[2] += bflo(rv.y) * wgt[j][2]; o[3] += bfhi(rv.y) * wgt[j][3]; \
;         o[4] += bflo(rv.z) * wgt[j][4]; o[5] += bfhi(rv.z) * wgt[j][5]; \
;         o[6] += bflo(rv.w) * wgt[j][6]; o[7] += bfhi(rv.w) * wgt[j][7]; } while (0)
; __device__ __forceinline__ void conv_phase(const Params& P, const int pass, const int wvi) {
;     ...
;       for (int j = 0; j < 8; ++j) {
;         float o[8];
; #pragma unroll
;         for (int e = 0; e < 8; ++e) o[e] = bias[e];
;         CONV_ACC(R[j], 0); CONV_ACC(R[j + 1], 1); CONV_ACC(R[j + 2], 2); CONV_ACC(R[j + 3], 3); CONV_ACC(R[j + 4], 4);
;         uint4 ov;
;         ov.x = pk2(siluf_(o[0]), siluf_(o[1])); ov.y = pk2(siluf_(o[2]), siluf_(o[3]));
;         ov.z = pk2(siluf_(o[4]), siluf_(o[5])); ov.w = pk2(siluf_(o[6]), siluf_(o[7]));
;         *(uint4*)(xo + (size_t)(t0 + blk * 8 + j) * CONVD + c0) = ov;
	v_add_f32_e32 v49, 1.0, v49
	v_rcp_f32_e32 v82, v49
	v_mul_f32_e32 v49, 0xbfb8aa3b, v51
	v_exp_f32_e32 v49, v49
	v_and_b32_e32 v93, 0xffff0000, v129
	v_lshlrev_b32_e32 v90, 16, v128
	v_and_b32_e32 v91, 0xffff0000, v128
	v_add_f32_e32 v49, 1.0, v49
	v_rcp_f32_e32 v83, v49
	s_nop 0
	v_pk_mul_f32 v[50:51], v[50:51], v[82:83]
	s_nop 0
	v_cvt_pk_bf16_f32 v49, v50, v51
	v_pk_fma_f32 v[50:51], v[0:1], v[88:89], v[28:29]
	v_lshlrev_b32_e32 v88, 16, v127
	v_pk_fma_f32 v[50:51], v[8:9], v[66:67], v[50:51]
	v_and_b32_e32 v89, 0xffff0000, v127
	v_pk_fma_f32 v[50:51], v[12:13], v[54:55], v[50:51]
	s_nop 0
	v_pk_fma_f32 v[50:51], v[16:17], v[102:103], v[50:51]
	s_nop 0
	v_pk_fma_f32 v[50:51], v[20:21], v[76:77], v[50:51]
	s_nop 0
	v_mul_f32_e32 v82, 0xbfb8aa3b, v50
	v_mul_f32_e32 v83, 0xbfb8aa3b, v51
	v_exp_f32_e32 v82, v82
	v_exp_f32_e32 v83, v83
	v_add_f32_e32 v82, 1.0, v82
	v_add_f32_e32 v83, 1.0, v83
	v_rcp_f32_e32 v82, v82
	v_rcp_f32_e32 v83, v83
	s_nop 0
	v_pk_mul_f32 v[50:51], v[50:51], v[82:83]
	s_nop 0
	v_cvt_pk_bf16_f32 v50, v50, v51
	v_mul_f32_e32 v51, 0xbfb8aa3b, v74
	v_exp_f32_e32 v51, v51
	s_nop 0
	v_add_f32_e32 v51, 1.0, v51
	v_rcp_f32_e32 v82, v51
	v_mul_f32_e32 v51, 0xbfb8aa3b, v75
	v_exp_f32_e32 v51, v51
	s_nop 0
	v_add_f32_e32 v51, 1.0, v51
	v_rcp_f32_e32 v83, v51
	s_nop 0
	v_pk_mul_f32 v[74:75], v[74:75], v[82:83]
	s_nop 0
	v_cvt_pk_bf16_f32 v51, v74, v75
	v_or_b32_e32 v74, 9, v125
	v_mad_i64_i32 v[74:75], s[2:3], v74, s85, v[56:57]
	global_store_dwordx4 v[74:75], v[48:51], off
	v_lshlrev_b32_e32 v82, 16, v135
	v_and_b32_e32 v83, 0xffff0000, v135
	v_pk_fma_f32 v[48:49], v[4:5], v[70:71], v[44:45]
	v_pk_fma_f32 v[52:53], v[22:23], v[82:83], v[52:53]
	v_pk_fma_f32 v[48:49], v[24:25], v[62:63], v[48:49]
	v_lshlrev_b32_e32 v74, 16, v134
	v_pk_fma_f32 v[48:49], v[32:33], v[110:111], v[48:49]
	v_and_b32_e32 v75, 0xffff0000, v134
	v_pk_fma_f32 v[48:49], v[36:37], v[80:81], v[48:49]
	v_lshlrev_b32_e32 v70, 16, v114
	v_pk_fma_f32 v[48:49], v[40:41], v[106:107], v[48:49]
	v_and_b32_e32 v71, 0xffff0000, v114
	v_mul_f32_e32 v50, 0xbfb8aa3b, v48
	v_mul_f32_e32 v51, 0xbfb8aa3b, v49
	v_exp_f32_e32 v50, v50
	v_exp_f32_e32 v51, v51
	v_add_f32_e32 v50, 1.0, v50
	v_add_f32_e32 v51, 1.0, v51
	v_rcp_f32_e32 v50, v50
	v_rcp_f32_e32 v51, v51
	s_nop 0
	v_pk_mul_f32 v[48:49], v[48:49], v[50:51]
	v_pk_fma_f32 v[50:51], v[6:7], v[68:69], v[46:47]
	v_cvt_pk_bf16_f32 v48, v48, v49
	v_pk_fma_f32 v[50:51], v[26:27], v[60:61], v[50:51]
	s_nop 0
	v_pk_fma_f32 v[50:51], v[34:35], v[108:109], v[50:51]
	s_nop 0
	v_pk_fma_f32 v[50:51], v[38:39], v[78:79], v[50:51]
	s_nop 0
	v_pk_fma_f32 v[50:51], v[42:43], v[100:101], v[50:51]
	s_nop 0
	v_mul_f32_e32 v49, 0xbfb8aa3b, v50
	v_exp_f32_e32 v49, v49
	s_nop 0
	v_add_f32_e32 v49, 1.0, v49
	v_rcp_f32_e32 v68, v49
	v_mul_f32_e32 v49, 0xbfb8aa3b, v51
	v_exp_f32_e32 v49, v49
	s_nop 0
	v_add_f32_e32 v49, 1.0, v49
	v_rcp_f32_e32 v69, v49
	s_nop 0
	v_pk_mul_f32 v[50:51], v[50:51], v[68:69]
	s_nop 0
	v_cvt_pk_bf16_f32 v49, v50, v51
	v_pk_fma_f32 v[50:51], v[0:1], v[66:67], v[28:29]
	v_lshlrev_b32_e32 v68, 16, v133
	v_pk_fma_f32 v[50:51], v[8:9], v[54:55], v[50:51]
	v_and_b32_e32 v69, 0xffff0000, v133
	v_pk_fma_f32 v[50:51], v[12:13], v[102:103], v[50:51]
	s_nop 0
	v_pk_fma_f32 v[50:51], v[16:17], v[76:77], v[50:51]
	s_nop 0
	v_pk_fma_f32 v[50:51], v[20:21], v[96:97], v[50:51]
	s_nop 0
	v_mul_f32_e32 v66, 0xbfb8aa3b, v50
	v_mul_f32_e32 v67, 0xbfb8aa3b, v51
	v_exp_f32_e32 v66, v66
	v_exp_f32_e32 v67, v67
	v_add_f32_e32 v66, 1.0, v66
	v_add_f32_e32 v67, 1.0, v67
	v_rcp_f32_e32 v66, v66
	v_rcp_f32_e32 v67, v67
	s_nop 0
	v_pk_mul_f32 v[50:51], v[50:51], v[66:67]
	s_nop 0
	v_cvt_pk_bf16_f32 v50, v50, v51
	v_mul_f32_e32 v51, 0xbfb8aa3b, v64
	v_exp_f32_e32 v51, v51
	s_nop 0
	v_add_f32_e32 v51, 1.0, v51
	v_rcp_f32_e32 v66, v51
	v_mul_f32_e32 v51, 0xbfb8aa3b, v65
	v_exp_f32_e32 v51, v51
	s_nop 0
	v_add_f32_e32 v51, 1.0, v51
	v_rcp_f32_e32 v67, v51
	s_nop 0
	v_pk_mul_f32 v[64:65], v[64:65], v[66:67]
	s_nop 0
	v_cvt_pk_bf16_f32 v51, v64, v65
	v_or_b32_e32 v64, 10, v125
	v_mad_i64_i32 v[64:65], s[2:3], v64, s85, v[56:57]
	global_store_dwordx4 v[64:65], v[48:51], off
	v_lshlrev_b32_e32 v66, 16, v117
	v_and_b32_e32 v67, 0xffff0000, v117
	v_pk_fma_f32 v[48:49], v[4:5], v[62:63], v[44:45]
	v_lshlrev_b32_e32 v62, 16, v132
	v_pk_fma_f32 v[48:49], v[24:25], v[110:111], v[48:49]
	v_and_b32_e32 v63, 0xffff0000, v132
	v_pk_fma_f32 v[48:49], v[32:33], v[80:81], v[48:49]
	s_nop 0
	v_pk_fma_f32 v[48:49], v[36:37], v[106:107], v[48:49]
	s_nop 0
	v_pk_fma_f32 v[48:49], v[40:41], v[104:105], v[48:49]
	s_nop 0
	v_mul_f32_e32 v50, 0xbfb8aa3b, v48
	v_mul_f32_e32 v51, 0xbfb8aa3b, v49
	v_exp_f32_e32 v50, v50
	v_exp_f32_e32 v51, v51
	v_add_f32_e32 v50, 1.0, v50
	v_add_f32_e32 v51, 1.0, v51
	v_rcp_f32_e32 v50, v50
	v_rcp_f32_e32 v51, v51
	s_nop 0
	v_pk_mul_f32 v[48:49], v[48:49], v[50:51]
	v_pk_fma_f32 v[50:51], v[6:7], v[60:61], v[46:47]
	v_cvt_pk_bf16_f32 v48, v48, v49
	v_pk_fma_f32 v[50:51], v[26:27], v[108:109], v[50:51]
	s_nop 0
	v_pk_fma_f32 v[50:51], v[34:35], v[78:79], v[50:51]
	s_nop 0
	v_pk_fma_f32 v[50:51], v[38:39], v[100:101], v[50:51]
	s_nop 0
	v_pk_fma_f32 v[50:51], v[42:43], v[98:99], v[50:51]
	s_nop 0
	v_mul_f32_e32 v49, 0xbfb8aa3b, v50
	v_exp_f32_e32 v49, v49
	s_nop 0
	v_add_f32_e32 v49, 1.0, v49
	v_rcp_f32_e32 v60, v49
	v_mul_f32_e32 v49, 0xbfb8aa3b, v51
	v_exp_f32_e32 v49, v49
	s_nop 0
	v_add_f32_e32 v49, 1.0, v49
	v_rcp_f32_e32 v61, v49
	s_nop 0
	v_pk_mul_f32 v[50:51], v[50:51], v[60:61]
	s_nop 0
	v_cvt_pk_bf16_f32 v49, v50, v51
	v_pk_fma_f32 v[50:51], v[0:1], v[54:55], v[28:29]
	s_nop 0
	v_pk_fma_f32 v[50:51], v[8:9], v[102:103], v[50:51]
; __device__ __forceinline__ float siluf_(float x) { return x * __builtin_amdgcn_rcpf(1.f + __expf(-x)); }
; #define CONV_ACC(rv, j) do { \
;         o[0] += bflo(rv.x) * wgt[j][0]; o[1] += bfhi(rv.x) * wgt[j][1]; \
;         o[2] += bflo(rv.y) * wgt[j][2]; o[3] += bfhi(rv.y) * wgt[j][3]; \
;         o[4] += bflo(rv.z) * wgt[j][4]; o[5] += bfhi(rv.z) * wgt[j][5]; \
;         o[6] += bflo(rv.w) * wgt[j][6]; o[7] += bfhi(rv.w) * wgt[j][7]; } while (0)
; __device__ __forceinline__ void conv_phase(const Params& P, const int pass, const int wvi) {
;     ...
;       for (int j = 0; j < 8; ++j) {
;         float o[8];
; #pragma unroll
;         for (int e = 0; e < 8; ++e) o[e] = bias[e];
;         CONV_ACC(R[j], 0); CONV_ACC(R[j + 1], 1); CONV_ACC(R[j + 2], 2); CONV_ACC(R[j + 3], 3); CONV_ACC(R[j + 4], 4);
;         uint4 ov;
;         ov.x = pk2(siluf_(o[0]), siluf_(o[1])); ov.y = pk2(siluf_(o[2]), siluf_(o[3]));
;         ov.z = pk2(siluf_(o[4]), siluf_(o[5])); ov.w = pk2(siluf_(o[6]), siluf_(o[7]));
;         *(uint4*)(xo + (size_t)(t0 + blk * 8 + j) * CONVD + c0) = ov;
	s_nop 0
	v_pk_fma_f32 v[50:51], v[12:13], v[76:77], v[50:51]
	s_nop 0
	v_pk_fma_f32 v[50:51], v[16:17], v[96:97], v[50:51]
	s_nop 0
	v_pk_fma_f32 v[50:51], v[20:21], v[86:87], v[50:51]
	s_nop 0
	v_mul_f32_e32 v54, 0xbfb8aa3b, v50
	v_mul_f32_e32 v55, 0xbfb8aa3b, v51
	v_exp_f32_e32 v54, v54
	v_exp_f32_e32 v55, v55
	v_add_f32_e32 v54, 1.0, v54
	v_add_f32_e32 v55, 1.0, v55
	v_rcp_f32_e32 v54, v54
	v_rcp_f32_e32 v55, v55
	s_nop 0
	v_pk_mul_f32 v[50:51], v[50:51], v[54:55]
	s_nop 0
	v_cvt_pk_bf16_f32 v50, v50, v51
	v_mul_f32_e32 v51, 0xbfb8aa3b, v52
	v_exp_f32_e32 v51, v51
	s_nop 0
	v_add_f32_e32 v51, 1.0, v51
	v_rcp_f32_e32 v54, v51
	v_mul_f32_e32 v51, 0xbfb8aa3b, v53
	v_exp_f32_e32 v51, v51
	s_nop 0
	v_add_f32_e32 v51, 1.0, v51
	v_rcp_f32_e32 v55, v51
	s_nop 0
	v_pk_mul_f32 v[52:53], v[52:53], v[54:55]
	s_nop 0
	v_cvt_pk_bf16_f32 v51, v52, v53
	v_or_b32_e32 v52, 11, v125
	v_mad_i64_i32 v[52:53], s[2:3], v52, s85, v[56:57]
	global_store_dwordx4 v[52:53], v[48:51], off
	v_lshlrev_b32_e32 v52, 16, v131
	v_and_b32_e32 v53, 0xffff0000, v131
	v_pk_fma_f32 v[48:49], v[4:5], v[110:111], v[44:45]
	s_nop 0
	v_pk_fma_f32 v[48:49], v[24:25], v[80:81], v[48:49]
	s_nop 0
	v_pk_fma_f32 v[48:49], v[32:33], v[106:107], v[48:49]
	s_nop 0
	v_pk_fma_f32 v[48:49], v[36:37], v[104:105], v[48:49]
	s_nop 0
	v_pk_fma_f32 v[48:49], v[40:41], v[74:75], v[48:49]
	s_nop 0
	v_mul_f32_e32 v50, 0xbfb8aa3b, v48
	v_mul_f32_e32 v51, 0xbfb8aa3b, v49
	v_exp_f32_e32 v50, v50
	v_exp_f32_e32 v51, v51
	v_add_f32_e32 v50, 1.0, v50
	v_add_f32_e32 v51, 1.0, v51
	v_rcp_f32_e32 v50, v50
	v_rcp_f32_e32 v51, v51
	s_nop 0
	v_pk_mul_f32 v[48:49], v[48:49], v[50:51]
	v_pk_fma_f32 v[50:51], v[6:7], v[108:109], v[46:47]
	v_cvt_pk_bf16_f32 v48, v48, v49
	v_pk_fma_f32 v[50:51], v[26:27], v[78:79], v[50:51]
	s_nop 0
	v_pk_fma_f32 v[50:51], v[34:35], v[100:101], v[50:51]
	s_nop 0
	v_pk_fma_f32 v[50:51], v[38:39], v[98:99], v[50:51]
	s_nop 0
	v_pk_fma_f32 v[50:51], v[42:43], v[68:69], v[50:51]
	s_nop 0
	v_mul_f32_e32 v49, 0xbfb8aa3b, v50
	v_exp_f32_e32 v49, v49
	s_nop 0
	v_add_f32_e32 v49, 1.0, v49
	v_rcp_f32_e32 v54, v49
	v_mul_f32_e32 v49, 0xbfb8aa3b, v51
	v_exp_f32_e32 v49, v49
	s_nop 0
	v_add_f32_e32 v49, 1.0, v49
	v_rcp_f32_e32 v55, v49
	s_nop 0
	v_pk_mul_f32 v[50:51], v[50:51], v[54:55]
	s_nop 0
	v_cvt_pk_bf16_f32 v49, v50, v51
	v_pk_fma_f32 v[50:51], v[0:1], v[102:103], v[28:29]
	s_nop 0
	v_pk_fma_f32 v[50:51], v[8:9], v[76:77], v[50:51]
	s_nop 0
	v_pk_fma_f32 v[50:51], v[12:13], v[96:97], v[50:51]
	s_nop 0
	v_pk_fma_f32 v[50:51], v[16:17], v[86:87], v[50:51]
	s_nop 0
	v_pk_fma_f32 v[50:51], v[20:21], v[62:63], v[50:51]
	s_nop 0
	v_mul_f32_e32 v54, 0xbfb8aa3b, v50
	v_mul_f32_e32 v55, 0xbfb8aa3b, v51
	v_exp_f32_e32 v54, v54
	v_exp_f32_e32 v55, v55
	v_add_f32_e32 v54, 1.0, v54
	v_add_f32_e32 v55, 1.0, v55
	v_rcp_f32_e32 v54, v54
	v_rcp_f32_e32 v55, v55
	s_nop 0
	v_pk_mul_f32 v[50:51], v[50:51], v[54:55]
	v_pk_fma_f32 v[54:55], v[2:3], v[94:95], v[30:31]
	v_cvt_pk_bf16_f32 v50, v50, v51
	v_pk_fma_f32 v[54:55], v[10:11], v[72:73], v[54:55]
	v_lshlrev_b32_e32 v94, 16, v130
	v_pk_fma_f32 v[54:55], v[14:15], v[84:85], v[54:55]
	v_and_b32_e32 v95, 0xffff0000, v130
	v_pk_fma_f32 v[54:55], v[18:19], v[82:83], v[54:55]
	s_nop 0
	v_pk_fma_f32 v[54:55], v[22:23], v[52:53], v[54:55]
	s_nop 0
	v_mul_f32_e32 v51, 0xbfb8aa3b, v54
	v_exp_f32_e32 v51, v51
	s_nop 0
	v_add_f32_e32 v51, 1.0, v51
	v_rcp_f32_e32 v60, v51
	v_mul_f32_e32 v51, 0xbfb8aa3b, v55
	v_exp_f32_e32 v51, v51
	s_nop 0
	v_add_f32_e32 v51, 1.0, v51
	v_rcp_f32_e32 v61, v51
	s_nop 0
	v_pk_mul_f32 v[54:55], v[54:55], v[60:61]
	s_nop 0
	v_cvt_pk_bf16_f32 v51, v54, v55
	v_or_b32_e32 v54, 12, v125
	v_mad_i64_i32 v[54:55], s[2:3], v54, s85, v[56:57]
	global_store_dwordx4 v[54:55], v[48:51], off
	s_nop 1
	v_pk_fma_f32 v[48:49], v[4:5], v[80:81], v[44:45]
	s_nop 0
	v_pk_fma_f32 v[48:49], v[24:25], v[106:107], v[48:49]
	s_nop 0
	v_pk_fma_f32 v[48:49], v[32:33], v[104:105], v[48:49]
	s_nop 0
	v_pk_fma_f32 v[48:49], v[36:37], v[74:75], v[48:49]
	s_nop 0
	v_pk_fma_f32 v[48:49], v[40:41], v[94:95], v[48:49]
	s_nop 0
	v_mul_f32_e32 v50, 0xbfb8aa3b, v48
	v_mul_f32_e32 v51, 0xbfb8aa3b, v49
	v_exp_f32_e32 v50, v50
	v_exp_f32_e32 v51, v51
	v_add_f32_e32 v50, 1.0, v50
	v_add_f32_e32 v51, 1.0, v51
	v_rcp_f32_e32 v50, v50
	v_rcp_f32_e32 v51, v51
	s_nop 0
	v_pk_mul_f32 v[48:49], v[48:49], v[50:51]
	v_pk_fma_f32 v[50:51], v[6:7], v[78:79], v[46:47]
	v_cvt_pk_bf16_f32 v48, v48, v49
	v_pk_fma_f32 v[50:51], v[26:27], v[100:101], v[50:51]
	v_lshlrev_b32_e32 v78, 16, v119
	v_pk_fma_f32 v[50:51], v[34:35], v[98:99], v[50:51]
	v_and_b32_e32 v79, 0xffff0000, v119
	v_pk_fma_f32 v[50:51], v[38:39], v[68:69], v[50:51]
	s_nop 0
	v_pk_fma_f32 v[50:51], v[42:43], v[92:93], v[50:51]
	s_nop 0
	v_mul_f32_e32 v49, 0xbfb8aa3b, v50
	v_exp_f32_e32 v49, v49
	s_nop 0
	v_add_f32_e32 v49, 1.0, v49
	v_rcp_f32_e32 v54, v49
	v_mul_f32_e32 v49, 0xbfb8aa3b, v51
	v_exp_f32_e32 v49, v49
	s_nop 0
	v_add_f32_e32 v49, 1.0, v49
	v_rcp_f32_e32 v55, v49
	s_nop 0
	v_pk_mul_f32 v[50:51], v[50:51], v[54:55]
	s_nop 0
	v_cvt_pk_bf16_f32 v49, v50, v51
	v_pk_fma_f32 v[50:51], v[0:1], v[76:77], v[28:29]
	v_lshlrev_b32_e32 v76, 16, v115
	v_pk_fma_f32 v[50:51], v[8:9], v[96:97], v[50:51]
	v_and_b32_e32 v77, 0xffff0000, v115
	v_pk_fma_f32 v[50:51], v[12:13], v[86:87], v[50:51]
	s_nop 0
	v_pk_fma_f32 v[50:51], v[16:17], v[62:63], v[50:51]
	s_nop 0
	v_pk_fma_f32 v[50:51], v[20:21], v[90:91], v[50:51]
	s_nop 0
	v_mul_f32_e32 v54, 0xbfb8aa3b, v50
	v_mul_f32_e32 v55, 0xbfb8aa3b, v51
	v_exp_f32_e32 v54, v54
	v_exp_f32_e32 v55, v55
	v_add_f32_e32 v54, 1.0, v54
	v_add_f32_e32 v55, 1.0, v55
	v_rcp_f32_e32 v54, v54
; __device__ __forceinline__ float siluf_(float x) { return x * __builtin_amdgcn_rcpf(1.f + __expf(-x)); }
; #define CONV_ACC(rv, j) do { \
;         o[0] += bflo(rv.x) * wgt[j][0]; o[1] += bfhi(rv.x) * wgt[j][1]; \
;         o[2] += bflo(rv.y) * wgt[j][2]; o[3] += bfhi(rv.y) * wgt[j][3]; \
;         o[4] += bflo(rv.z) * wgt[j][4]; o[5] += bfhi(rv.z) * wgt[j][5]; \
;         o[6] += bflo(rv.w) * wgt[j][6]; o[7] += bfhi(rv.w) * wgt[j][7]; } while (0)
; __device__ __forceinline__ void conv_phase(const Params& P, const int pass, const int wvi) {
;     ...
;       for (int j = 0; j < 8; ++j) {
;         float o[8];
; #pragma unroll
;         for (int e = 0; e < 8; ++e) o[e] = bias[e];
;         CONV_ACC(R[j], 0); CONV_ACC(R[j + 1], 1); CONV_ACC(R[j + 2], 2); CONV_ACC(R[j + 3], 3); CONV_ACC(R[j + 4], 4);
;         uint4 ov;
;         ov.x = pk2(siluf_(o[0]), siluf_(o[1])); ov.y = pk2(siluf_(o[2]), siluf_(o[3]));
;         ov.z = pk2(siluf_(o[4]), siluf_(o[5])); ov.w = pk2(siluf_(o[6]), siluf_(o[7]));
;         *(uint4*)(xo + (size_t)(t0 + blk * 8 + j) * CONVD + c0) = ov;
	v_rcp_f32_e32 v55, v55
	s_nop 0
	v_pk_mul_f32 v[50:51], v[50:51], v[54:55]
	v_pk_fma_f32 v[54:55], v[2:3], v[72:73], v[30:31]
	v_cvt_pk_bf16_f32 v50, v50, v51
	v_pk_fma_f32 v[54:55], v[10:11], v[84:85], v[54:55]
	v_lshlrev_b32_e32 v72, 16, v118
	v_pk_fma_f32 v[54:55], v[14:15], v[82:83], v[54:55]
	v_and_b32_e32 v73, 0xffff0000, v118
	v_pk_fma_f32 v[54:55], v[18:19], v[52:53], v[54:55]
	s_nop 0
	v_pk_fma_f32 v[54:55], v[22:23], v[88:89], v[54:55]
	s_nop 0
	v_mul_f32_e32 v51, 0xbfb8aa3b, v54
	v_exp_f32_e32 v51, v51
	s_nop 0
	v_add_f32_e32 v51, 1.0, v51
	v_rcp_f32_e32 v60, v51
	v_mul_f32_e32 v51, 0xbfb8aa3b, v55
	v_exp_f32_e32 v51, v51
	s_nop 0
	v_add_f32_e32 v51, 1.0, v51
	v_rcp_f32_e32 v61, v51
	s_nop 0
	v_pk_mul_f32 v[54:55], v[54:55], v[60:61]
	s_nop 0
	v_cvt_pk_bf16_f32 v51, v54, v55
	v_or_b32_e32 v54, 13, v125
	v_mad_i64_i32 v[54:55], s[2:3], v54, s85, v[56:57]
	global_store_dwordx4 v[54:55], v[48:51], off
	v_lshlrev_b32_e32 v60, 16, v116
	v_and_b32_e32 v61, 0xffff0000, v116
	v_pk_fma_f32 v[48:49], v[4:5], v[106:107], v[44:45]
	s_nop 0
	v_pk_fma_f32 v[48:49], v[24:25], v[104:105], v[48:49]
	s_nop 0
	v_pk_fma_f32 v[48:49], v[32:33], v[74:75], v[48:49]
	s_nop 0
	v_pk_fma_f32 v[48:49], v[36:37], v[94:95], v[48:49]
	s_nop 0
	v_pk_fma_f32 v[48:49], v[40:41], v[78:79], v[48:49]
	s_nop 0
	v_mul_f32_e32 v50, 0xbfb8aa3b, v48
	v_mul_f32_e32 v51, 0xbfb8aa3b, v49
	v_exp_f32_e32 v50, v50
	v_exp_f32_e32 v51, v51
	v_add_f32_e32 v50, 1.0, v50
	v_add_f32_e32 v51, 1.0, v51
	v_rcp_f32_e32 v50, v50
	v_rcp_f32_e32 v51, v51
	s_nop 0
	v_pk_mul_f32 v[48:49], v[48:49], v[50:51]
	v_pk_fma_f32 v[50:51], v[6:7], v[100:101], v[46:47]
	v_cvt_pk_bf16_f32 v48, v48, v49
	v_pk_fma_f32 v[50:51], v[26:27], v[98:99], v[50:51]
	s_nop 0
	v_pk_fma_f32 v[50:51], v[34:35], v[68:69], v[50:51]
	s_nop 0
	v_pk_fma_f32 v[50:51], v[38:39], v[92:93], v[50:51]
	s_nop 0
	v_pk_fma_f32 v[50:51], v[42:43], v[72:73], v[50:51]
	s_nop 0
	v_mul_f32_e32 v49, 0xbfb8aa3b, v50
	v_exp_f32_e32 v49, v49
	s_nop 0
	v_add_f32_e32 v49, 1.0, v49
	v_rcp_f32_e32 v54, v49
	v_mul_f32_e32 v49, 0xbfb8aa3b, v51
	v_exp_f32_e32 v49, v49
	s_nop 0
	v_add_f32_e32 v49, 1.0, v49
	v_rcp_f32_e32 v55, v49
	s_nop 0
	v_pk_mul_f32 v[50:51], v[50:51], v[54:55]
	s_nop 0
	v_cvt_pk_bf16_f32 v49, v50, v51
	v_pk_fma_f32 v[50:51], v[0:1], v[96:97], v[28:29]
	s_nop 0
	v_pk_fma_f32 v[50:51], v[8:9], v[86:87], v[50:51]
	s_nop 0
	v_pk_fma_f32 v[50:51], v[12:13], v[62:63], v[50:51]
	s_nop 0
	v_pk_fma_f32 v[50:51], v[16:17], v[90:91], v[50:51]
	s_nop 0
	v_pk_fma_f32 v[50:51], v[20:21], v[66:67], v[50:51]
	s_nop 0
	v_mul_f32_e32 v54, 0xbfb8aa3b, v50
	v_mul_f32_e32 v55, 0xbfb8aa3b, v51
	v_exp_f32_e32 v54, v54
	v_exp_f32_e32 v55, v55
	v_add_f32_e32 v54, 1.0, v54
	v_add_f32_e32 v55, 1.0, v55
	v_rcp_f32_e32 v54, v54
	v_rcp_f32_e32 v55, v55
	s_nop 0
	v_pk_mul_f32 v[50:51], v[50:51], v[54:55]
	v_pk_fma_f32 v[54:55], v[2:3], v[84:85], v[30:31]
	v_cvt_pk_bf16_f32 v50, v50, v51
	v_pk_fma_f32 v[54:55], v[10:11], v[82:83], v[54:55]
	s_nop 0
	v_pk_fma_f32 v[54:55], v[14:15], v[52:53], v[54:55]
	s_nop 0
	v_pk_fma_f32 v[54:55], v[18:19], v[88:89], v[54:55]
	s_nop 0
	v_pk_fma_f32 v[54:55], v[22:23], v[60:61], v[54:55]
	s_nop 0
	v_mul_f32_e32 v51, 0xbfb8aa3b, v54
	v_exp_f32_e32 v51, v51
	s_nop 0
	v_add_f32_e32 v51, 1.0, v51
	v_rcp_f32_e32 v64, v51
	v_mul_f32_e32 v51, 0xbfb8aa3b, v55
	v_exp_f32_e32 v51, v51
	s_nop 0
	v_add_f32_e32 v51, 1.0, v51
	v_rcp_f32_e32 v65, v51
	s_nop 0
	v_pk_mul_f32 v[54:55], v[54:55], v[64:65]
	s_nop 0
	v_cvt_pk_bf16_f32 v51, v54, v55
	v_or_b32_e32 v54, 14, v125
	v_mad_i64_i32 v[54:55], s[2:3], v54, s85, v[56:57]
	global_store_dwordx4 v[54:55], v[48:51], off
	v_lshlrev_b32_e32 v64, 16, v113
	v_and_b32_e32 v65, 0xffff0000, v113
	v_pk_fma_f32 v[48:49], v[4:5], v[104:105], v[44:45]
	v_lshlrev_b32_e32 v54, 16, v112
	v_pk_fma_f32 v[48:49], v[24:25], v[74:75], v[48:49]
	v_and_b32_e32 v55, 0xffff0000, v112
	v_pk_fma_f32 v[48:49], v[32:33], v[94:95], v[48:49]
	s_nop 0
	v_pk_fma_f32 v[48:49], v[36:37], v[78:79], v[48:49]
	s_nop 0
	v_pk_fma_f32 v[48:49], v[40:41], v[76:77], v[48:49]
	s_nop 0
	v_mul_f32_e32 v50, 0xbfb8aa3b, v48
	v_mul_f32_e32 v51, 0xbfb8aa3b, v49
	v_exp_f32_e32 v50, v50
	v_exp_f32_e32 v51, v51
	v_add_f32_e32 v50, 1.0, v50
	v_add_f32_e32 v51, 1.0, v51
	v_rcp_f32_e32 v50, v50
	v_rcp_f32_e32 v51, v51
	s_nop 0
	v_pk_mul_f32 v[48:49], v[48:49], v[50:51]
	v_pk_fma_f32 v[50:51], v[6:7], v[98:99], v[46:47]
	v_cvt_pk_bf16_f32 v48, v48, v49
	v_pk_fma_f32 v[50:51], v[26:27], v[68:69], v[50:51]
	s_nop 0
	v_pk_fma_f32 v[50:51], v[34:35], v[92:93], v[50:51]
	s_nop 0
	v_pk_fma_f32 v[50:51], v[38:39], v[72:73], v[50:51]
	s_nop 0
	v_pk_fma_f32 v[50:51], v[42:43], v[70:71], v[50:51]
	s_nop 0
	v_mul_f32_e32 v49, 0xbfb8aa3b, v50
	v_exp_f32_e32 v49, v49
	s_nop 0
	v_add_f32_e32 v49, 1.0, v49
	v_rcp_f32_e32 v80, v49
	v_mul_f32_e32 v49, 0xbfb8aa3b, v51
	v_exp_f32_e32 v49, v49
	s_nop 0
	v_add_f32_e32 v49, 1.0, v49
	v_rcp_f32_e32 v81, v49
	s_nop 0
	v_pk_mul_f32 v[50:51], v[50:51], v[80:81]
	s_nop 0
	v_cvt_pk_bf16_f32 v49, v50, v51
	v_pk_fma_f32 v[50:51], v[0:1], v[86:87], v[28:29]
	v_or_b32_e32 v86, 16, v125
	v_pk_fma_f32 v[50:51], v[8:9], v[62:63], v[50:51]
	s_nop 0
	v_pk_fma_f32 v[50:51], v[12:13], v[90:91], v[50:51]
	s_nop 0
	v_pk_fma_f32 v[50:51], v[16:17], v[66:67], v[50:51]
	s_nop 0
	v_pk_fma_f32 v[50:51], v[20:21], v[64:65], v[50:51]
	s_nop 0
	v_mul_f32_e32 v80, 0xbfb8aa3b, v50
	v_mul_f32_e32 v81, 0xbfb8aa3b, v51
	v_exp_f32_e32 v80, v80
	v_exp_f32_e32 v81, v81
	v_add_f32_e32 v80, 1.0, v80
	v_add_f32_e32 v81, 1.0, v81
	v_rcp_f32_e32 v80, v80
	v_rcp_f32_e32 v81, v81
	s_nop 0
	v_pk_mul_f32 v[50:51], v[50:51], v[80:81]
; __device__ __forceinline__ float siluf_(float x) { return x * __builtin_amdgcn_rcpf(1.f + __expf(-x)); }
; #define CONV_ACC(rv, j) do { \
;         o[0] += bflo(rv.x) * wgt[j][0]; o[1] += bfhi(rv.x) * wgt[j][1]; \
;         o[2] += bflo(rv.y) * wgt[j][2]; o[3] += bfhi(rv.y) * wgt[j][3]; \
;         o[4] += bflo(rv.z) * wgt[j][4]; o[5] += bfhi(rv.z) * wgt[j][5]; \
;         o[6] += bflo(rv.w) * wgt[j][6]; o[7] += bfhi(rv.w) * wgt[j][7]; } while (0)
; __device__ __forceinline__ void conv_phase(const Params& P, const int pass, const int wvi) {
;     ...
;     for (int blk = 0; blk < TCH / 8; ++blk) {
; #pragma unroll
;       for (int j = 0; j < 8; ++j) {
;         const int tt2 = blk * 8 + j + 2;
;         const bool v4 = (pos0 + tt2 < S);
;         const uint4 l4 = *(const uint4*)(xin + (size_t)(v4 ? t0 + tt2 : t0) * CONVD + c0);
;         R[4 + j].x = v4 ? l4.x : 0u; R[4 + j].y = v4 ? l4.y : 0u; R[4 + j].z = v4 ? l4.z : 0u; R[4 + j].w = v4 ? l4.w : 0u;
;       }
; #pragma unroll
;       for (int j = 0; j < 8; ++j) {
;         float o[8];
; #pragma unroll
;         for (int e = 0; e < 8; ++e) o[e] = bias[e];
;         CONV_ACC(R[j], 0); CONV_ACC(R[j + 1], 1); CONV_ACC(R[j + 2], 2); CONV_ACC(R[j + 3], 3); CONV_ACC(R[j + 4], 4);
;         uint4 ov;
;         ov.x = pk2(siluf_(o[0]), siluf_(o[1])); ov.y = pk2(siluf_(o[2]), siluf_(o[3]));
;         ov.z = pk2(siluf_(o[4]), siluf_(o[5])); ov.w = pk2(siluf_(o[6]), siluf_(o[7]));
;         *(uint4*)(xo + (size_t)(t0 + blk * 8 + j) * CONVD + c0) = ov;
	v_pk_fma_f32 v[80:81], v[2:3], v[82:83], v[30:31]
	v_cvt_pk_bf16_f32 v50, v50, v51
	v_pk_fma_f32 v[80:81], v[10:11], v[52:53], v[80:81]
	v_pk_fma_f32 v[52:53], v[2:3], v[52:53], v[30:31]
	v_pk_fma_f32 v[80:81], v[14:15], v[88:89], v[80:81]
	v_pk_fma_f32 v[52:53], v[10:11], v[88:89], v[52:53]
	v_pk_fma_f32 v[80:81], v[18:19], v[60:61], v[80:81]
	v_pk_fma_f32 v[52:53], v[14:15], v[60:61], v[52:53]
	v_pk_fma_f32 v[80:81], v[22:23], v[54:55], v[80:81]
	v_pk_fma_f32 v[52:53], v[18:19], v[54:55], v[52:53]
	v_mul_f32_e32 v51, 0xbfb8aa3b, v80
	v_exp_f32_e32 v51, v51
	s_nop 0
	v_add_f32_e32 v51, 1.0, v51
	v_rcp_f32_e32 v82, v51
	v_mul_f32_e32 v51, 0xbfb8aa3b, v81
	v_exp_f32_e32 v51, v51
	s_nop 0
	v_add_f32_e32 v51, 1.0, v51
	v_rcp_f32_e32 v83, v51
	s_nop 0
	v_pk_mul_f32 v[80:81], v[80:81], v[82:83]
	s_nop 0
	v_cvt_pk_bf16_f32 v51, v80, v81
	v_or_b32_e32 v80, 15, v125
	v_mad_i64_i32 v[80:81], s[2:3], v80, s85, v[56:57]
	global_store_dwordx4 v[80:81], v[48:51], off
	v_cmp_lt_i32_e32 vcc, 18, v126
	s_nop 1
	v_cndmask_b32_e64 v210, 0, 18, vcc
	v_or_b32_e32 v210, v210, v125
	v_mad_i64_i32 v[210:211], s[2:3], v210, s85, v[58:59]
	global_load_dwordx4 v[210:213], v[210:211], off
	v_cmp_lt_i32_e32 vcc, 19, v126
	s_nop 1
	v_cndmask_b32_e64 v214, 0, 19, vcc
	v_or_b32_e32 v214, v214, v125
	v_mad_i64_i32 v[214:215], s[2:3], v214, s85, v[58:59]
	global_load_dwordx4 v[214:217], v[214:215], off
	v_cmp_lt_i32_e32 vcc, 20, v126
	s_nop 1
	v_cndmask_b32_e64 v218, 0, 20, vcc
	v_or_b32_e32 v218, v218, v125
	v_mad_i64_i32 v[218:219], s[2:3], v218, s85, v[58:59]
	global_load_dwordx4 v[218:221], v[218:219], off
	v_cmp_lt_i32_e32 vcc, 21, v126
	s_nop 1
	v_cndmask_b32_e64 v222, 0, 21, vcc
	v_or_b32_e32 v222, v222, v125
	v_mad_i64_i32 v[222:223], s[2:3], v222, s85, v[58:59]
	global_load_dwordx4 v[222:225], v[222:223], off
	v_cmp_lt_i32_e32 vcc, 22, v126
	s_nop 1
	v_cndmask_b32_e64 v226, 0, 22, vcc
	v_or_b32_e32 v226, v226, v125
	v_mad_i64_i32 v[226:227], s[2:3], v226, s85, v[58:59]
	global_load_dwordx4 v[226:229], v[226:227], off
	v_cmp_lt_i32_e32 vcc, 23, v126
	s_nop 1
	v_cndmask_b32_e64 v230, 0, 23, vcc
	v_or_b32_e32 v230, v230, v125
	v_mad_i64_i32 v[230:231], s[2:3], v230, s85, v[58:59]
	global_load_dwordx4 v[230:233], v[230:231], off
	v_cmp_lt_i32_e32 vcc, 24, v126
	s_nop 1
	v_cndmask_b32_e64 v234, 0, 24, vcc
	v_or_b32_e32 v234, v234, v125
	v_mad_i64_i32 v[234:235], s[2:3], v234, s85, v[58:59]
	global_load_dwordx4 v[234:237], v[234:235], off
	v_cmp_lt_i32_e32 vcc, 25, v126
	s_nop 1
	v_cndmask_b32_e64 v238, 0, 25, vcc
	v_or_b32_e32 v238, v238, v125
	v_mad_i64_i32 v[238:239], s[2:3], v238, s85, v[58:59]
	global_load_dwordx4 v[238:241], v[238:239], off
	s_waitcnt vmcnt(7)
	v_cmp_lt_i32_e32 vcc, 18, v126
	s_nop 1
	v_cndmask_b32_e32 v80, 0, v210, vcc
	v_cndmask_b32_e32 v81, 0, v211, vcc
	v_cndmask_b32_e32 v82, 0, v212, vcc
	v_cndmask_b32_e32 v83, 0, v213, vcc
	s_waitcnt vmcnt(6)
	v_cmp_lt_i32_e32 vcc, 19, v126
	s_nop 1
	v_cndmask_b32_e32 v84, 0, v214, vcc
	v_cndmask_b32_e32 v85, 0, v215, vcc
	v_cndmask_b32_e32 v106, 0, v216, vcc
	v_cndmask_b32_e32 v107, 0, v217, vcc
	s_waitcnt vmcnt(5)
	v_cmp_lt_i32_e32 vcc, 20, v126
	s_nop 1
	v_cndmask_b32_e32 v103, 0, v218, vcc
	v_cndmask_b32_e32 v102, 0, v219, vcc
	v_cndmask_b32_e32 v98, 0, v220, vcc
	v_cndmask_b32_e32 v99, 0, v221, vcc
	s_waitcnt vmcnt(4)
	v_cmp_lt_i32_e32 vcc, 21, v126
	s_nop 1
	v_cndmask_b32_e32 v101, 0, v222, vcc
	v_cndmask_b32_e32 v100, 0, v223, vcc
	v_cndmask_b32_e32 v96, 0, v224, vcc
	v_cndmask_b32_e32 v97, 0, v225, vcc
	s_waitcnt vmcnt(3)
	v_cmp_lt_i32_e32 vcc, 22, v126
	s_nop 1
	v_cndmask_b32_e32 v142, 0, v226, vcc
	v_cndmask_b32_e32 v141, 0, v227, vcc
	v_cndmask_b32_e32 v140, 0, v228, vcc
	v_cndmask_b32_e32 v139, 0, v229, vcc
	s_waitcnt vmcnt(2)
	v_cmp_lt_i32_e32 vcc, 23, v126
	s_nop 1
	v_cndmask_b32_e32 v138, 0, v230, vcc
	v_cndmask_b32_e32 v137, 0, v231, vcc
	v_cndmask_b32_e32 v136, 0, v232, vcc
	v_cndmask_b32_e32 v135, 0, v233, vcc
	s_waitcnt vmcnt(1)
	v_cmp_lt_i32_e32 vcc, 24, v126
	s_nop 1
	v_cndmask_b32_e32 v134, 0, v234, vcc
	v_cndmask_b32_e32 v133, 0, v235, vcc
	v_cndmask_b32_e32 v132, 0, v236, vcc
	v_cndmask_b32_e32 v131, 0, v237, vcc
	s_waitcnt vmcnt(0)
	v_cmp_lt_i32_e32 vcc, 25, v126
	s_nop 1
	v_cndmask_b32_e32 v130, 0, v238, vcc
	v_cndmask_b32_e32 v129, 0, v239, vcc
	v_cndmask_b32_e32 v128, 0, v240, vcc
	v_cndmask_b32_e32 v127, 0, v241, vcc
	v_lshlrev_b32_e32 v118, 16, v80
	v_and_b32_e32 v119, 0xffff0000, v80
	v_lshlrev_b32_e32 v116, 16, v81
	v_and_b32_e32 v117, 0xffff0000, v81
	v_lshlrev_b32_e32 v110, 16, v82
	v_and_b32_e32 v111, 0xffff0000, v82
	v_lshlrev_b32_e32 v104, 16, v83
	v_and_b32_e32 v105, 0xffff0000, v83
	v_pk_fma_f32 v[52:53], v[22:23], v[104:105], v[52:53]
	s_nop 0
	v_and_b32_e32 v87, 0xffff0000, v84
	v_lshlrev_b32_e32 v82, 16, v106
	v_and_b32_e32 v83, 0xffff0000, v106
	v_lshlrev_b32_e32 v80, 16, v107
	v_and_b32_e32 v81, 0xffff0000, v107
	v_lshlrev_b32_e32 v114, 16, v103
	v_and_b32_e32 v115, 0xffff0000, v103
	v_lshlrev_b32_e32 v108, 16, v102
	v_and_b32_e32 v109, 0xffff0000, v102
	v_lshlrev_b32_e32 v102, 16, v98
	v_and_b32_e32 v103, 0xffff0000, v98
	v_lshlrev_b32_e32 v98, 16, v99
	v_and_b32_e32 v99, 0xffff0000, v99
	v_lshlrev_b32_e32 v112, 16, v101
	v_and_b32_e32 v113, 0xffff0000, v101
	v_lshlrev_b32_e32 v106, 16, v100
	v_and_b32_e32 v107, 0xffff0000, v100
	v_lshlrev_b32_e32 v100, 16, v96
	v_and_b32_e32 v101, 0xffff0000, v96
	v_lshlrev_b32_e32 v96, 16, v97
	v_and_b32_e32 v97, 0xffff0000, v97
	v_pk_fma_f32 v[48:49], v[4:5], v[74:75], v[44:45]
	s_nop 0
	v_pk_fma_f32 v[48:49], v[24:25], v[94:95], v[48:49]
	s_nop 0
	v_pk_fma_f32 v[48:49], v[32:33], v[78:79], v[48:49]
	v_lshlrev_b32_e32 v74, 16, v142
; __device__ __forceinline__ float siluf_(float x) { return x * __builtin_amdgcn_rcpf(1.f + __expf(-x)); }
; #define CONV_ACC(rv, j) do { \
;         o[0] += bflo(rv.x) * wgt[j][0]; o[1] += bfhi(rv.x) * wgt[j][1]; \
;         o[2] += bflo(rv.y) * wgt[j][2]; o[3] += bfhi(rv.y) * wgt[j][3]; \
;         o[4] += bflo(rv.z) * wgt[j][4]; o[5] += bfhi(rv.z) * wgt[j][5]; \
;         o[6] += bflo(rv.w) * wgt[j][6]; o[7] += bfhi(rv.w) * wgt[j][7]; } while (0)
; __device__ __forceinline__ void conv_phase(const Params& P, const int pass, const int wvi) {
;     ...
;       for (int j = 0; j < 8; ++j) {
;         float o[8];
; #pragma unroll
;         for (int e = 0; e < 8; ++e) o[e] = bias[e];
;         CONV_ACC(R[j], 0); CONV_ACC(R[j + 1], 1); CONV_ACC(R[j + 2], 2); CONV_ACC(R[j + 3], 3); CONV_ACC(R[j + 4], 4);
;         uint4 ov;
;         ov.x = pk2(siluf_(o[0]), siluf_(o[1])); ov.y = pk2(siluf_(o[2]), siluf_(o[3]));
;         ov.z = pk2(siluf_(o[4]), siluf_(o[5])); ov.w = pk2(siluf_(o[6]), siluf_(o[7]));
;         *(uint4*)(xo + (size_t)(t0 + blk * 8 + j) * CONVD + c0) = ov;
	v_pk_fma_f32 v[48:49], v[36:37], v[76:77], v[48:49]
	v_and_b32_e32 v75, 0xffff0000, v142
	v_pk_fma_f32 v[48:49], v[40:41], v[118:119], v[48:49]
	v_cmp_lt_i32_e32 vcc, 26, v126
	v_mul_f32_e32 v50, 0xbfb8aa3b, v48
	v_mul_f32_e32 v51, 0xbfb8aa3b, v49
	v_exp_f32_e32 v50, v50
	v_exp_f32_e32 v51, v51
	v_add_f32_e32 v50, 1.0, v50
	v_add_f32_e32 v51, 1.0, v51
	v_rcp_f32_e32 v50, v50
	v_rcp_f32_e32 v51, v51
	s_nop 0
	v_pk_mul_f32 v[48:49], v[48:49], v[50:51]
	v_pk_fma_f32 v[50:51], v[6:7], v[68:69], v[46:47]
	v_cvt_pk_bf16_f32 v48, v48, v49
	v_pk_fma_f32 v[50:51], v[26:27], v[92:93], v[50:51]
	s_nop 0
	v_pk_fma_f32 v[50:51], v[34:35], v[72:73], v[50:51]
	s_nop 0
	v_pk_fma_f32 v[50:51], v[38:39], v[70:71], v[50:51]
	s_nop 0
	v_pk_fma_f32 v[50:51], v[42:43], v[116:117], v[50:51]
	s_nop 0
	v_mul_f32_e32 v49, 0xbfb8aa3b, v50
	v_exp_f32_e32 v49, v49
	s_nop 0
	v_add_f32_e32 v49, 1.0, v49
	v_rcp_f32_e32 v68, v49
	v_mul_f32_e32 v49, 0xbfb8aa3b, v51
	v_exp_f32_e32 v49, v49
	s_nop 0
	v_add_f32_e32 v49, 1.0, v49
	v_rcp_f32_e32 v69, v49
	s_nop 0
	v_pk_mul_f32 v[50:51], v[50:51], v[68:69]
	s_nop 0
	v_cvt_pk_bf16_f32 v49, v50, v51
	v_pk_fma_f32 v[50:51], v[0:1], v[62:63], v[28:29]
	v_lshlrev_b32_e32 v68, 16, v141
	v_pk_fma_f32 v[50:51], v[8:9], v[90:91], v[50:51]
	v_and_b32_e32 v69, 0xffff0000, v141
	v_pk_fma_f32 v[50:51], v[12:13], v[66:67], v[50:51]
	s_nop 0
	v_pk_fma_f32 v[50:51], v[16:17], v[64:65], v[50:51]
	s_nop 0
	v_pk_fma_f32 v[50:51], v[20:21], v[110:111], v[50:51]
	s_nop 0
	v_mul_f32_e32 v62, 0xbfb8aa3b, v50
	v_mul_f32_e32 v63, 0xbfb8aa3b, v51
	v_exp_f32_e32 v62, v62
	v_exp_f32_e32 v63, v63
	v_add_f32_e32 v62, 1.0, v62
	v_add_f32_e32 v63, 1.0, v63
	v_rcp_f32_e32 v62, v62
	v_rcp_f32_e32 v63, v63
	s_nop 0
	v_pk_mul_f32 v[50:51], v[50:51], v[62:63]
	s_nop 0
	v_cvt_pk_bf16_f32 v50, v50, v51
	v_mul_f32_e32 v51, 0xbfb8aa3b, v52
	v_exp_f32_e32 v51, v51
	s_nop 0
	v_add_f32_e32 v51, 1.0, v51
	v_rcp_f32_e32 v62, v51
	v_mul_f32_e32 v51, 0xbfb8aa3b, v53
	v_exp_f32_e32 v51, v51
	s_nop 0
	v_add_f32_e32 v51, 1.0, v51
	v_rcp_f32_e32 v63, v51
	s_nop 0
	v_pk_mul_f32 v[52:53], v[52:53], v[62:63]
	s_nop 0
	v_cvt_pk_bf16_f32 v51, v52, v53
	v_mad_i64_i32 v[52:53], s[2:3], v86, s85, v[56:57]
	global_store_dwordx4 v[52:53], v[48:51], off
	v_lshlrev_b32_e32 v86, 16, v84
	v_lshlrev_b32_e32 v84, 16, v85
	v_pk_fma_f32 v[48:49], v[4:5], v[94:95], v[44:45]
	v_and_b32_e32 v85, 0xffff0000, v85
	v_pk_fma_f32 v[48:49], v[24:25], v[78:79], v[48:49]
	v_lshlrev_b32_e32 v94, 16, v138
	v_pk_fma_f32 v[48:49], v[32:33], v[76:77], v[48:49]
	v_and_b32_e32 v95, 0xffff0000, v138
	v_pk_fma_f32 v[48:49], v[36:37], v[118:119], v[48:49]
	s_nop 0
	v_pk_fma_f32 v[48:49], v[40:41], v[86:87], v[48:49]
	s_nop 0
	v_mul_f32_e32 v50, 0xbfb8aa3b, v48
	v_mul_f32_e32 v51, 0xbfb8aa3b, v49
	v_exp_f32_e32 v50, v50
	v_exp_f32_e32 v51, v51
	v_add_f32_e32 v50, 1.0, v50
	v_add_f32_e32 v51, 1.0, v51
	v_rcp_f32_e32 v50, v50
	v_rcp_f32_e32 v51, v51
	s_nop 0
	v_pk_mul_f32 v[48:49], v[48:49], v[50:51]
	v_pk_fma_f32 v[50:51], v[6:7], v[92:93], v[46:47]
	v_cvt_pk_bf16_f32 v48, v48, v49
	v_pk_fma_f32 v[50:51], v[26:27], v[72:73], v[50:51]
	v_lshlrev_b32_e32 v92, 16, v137
	v_pk_fma_f32 v[50:51], v[34:35], v[70:71], v[50:51]
	v_and_b32_e32 v93, 0xffff0000, v137
	v_pk_fma_f32 v[50:51], v[38:39], v[116:117], v[50:51]
	s_nop 0
	v_pk_fma_f32 v[50:51], v[42:43], v[84:85], v[50:51]
	s_nop 0
	v_mul_f32_e32 v49, 0xbfb8aa3b, v50
	v_exp_f32_e32 v49, v49
	s_nop 0
	v_add_f32_e32 v49, 1.0, v49
	v_rcp_f32_e32 v52, v49
	v_mul_f32_e32 v49, 0xbfb8aa3b, v51
	v_exp_f32_e32 v49, v49
	s_nop 0
	v_add_f32_e32 v49, 1.0, v49
	v_rcp_f32_e32 v53, v49
	s_nop 0
	v_pk_mul_f32 v[50:51], v[50:51], v[52:53]
	s_nop 0
	v_cvt_pk_bf16_f32 v49, v50, v51
	v_pk_fma_f32 v[50:51], v[0:1], v[90:91], v[28:29]
	v_lshlrev_b32_e32 v90, 16, v136
	v_pk_fma_f32 v[50:51], v[8:9], v[66:67], v[50:51]
	v_and_b32_e32 v91, 0xffff0000, v136
	v_pk_fma_f32 v[50:51], v[12:13], v[64:65], v[50:51]
	s_nop 0
	v_pk_fma_f32 v[50:51], v[16:17], v[110:111], v[50:51]
	s_nop 0
	v_pk_fma_f32 v[50:51], v[20:21], v[82:83], v[50:51]
	s_nop 0
	v_mul_f32_e32 v52, 0xbfb8aa3b, v50
	v_mul_f32_e32 v53, 0xbfb8aa3b, v51
	v_exp_f32_e32 v52, v52
	v_exp_f32_e32 v53, v53
	v_add_f32_e32 v52, 1.0, v52
	v_add_f32_e32 v53, 1.0, v53
	v_rcp_f32_e32 v52, v52
	v_rcp_f32_e32 v53, v53
	s_nop 0
	v_pk_mul_f32 v[50:51], v[50:51], v[52:53]
	v_pk_fma_f32 v[52:53], v[2:3], v[88:89], v[30:31]
	v_cvt_pk_bf16_f32 v50, v50, v51
	v_pk_fma_f32 v[52:53], v[10:11], v[60:61], v[52:53]
	v_lshlrev_b32_e32 v88, 16, v135
	v_pk_fma_f32 v[52:53], v[14:15], v[54:55], v[52:53]
	v_and_b32_e32 v89, 0xffff0000, v135
	v_pk_fma_f32 v[52:53], v[18:19], v[104:105], v[52:53]
	s_nop 0
	v_pk_fma_f32 v[52:53], v[22:23], v[80:81], v[52:53]
	s_nop 0
	v_mul_f32_e32 v51, 0xbfb8aa3b, v52
	v_exp_f32_e32 v51, v51
	s_nop 0
	v_add_f32_e32 v51, 1.0, v51
	v_rcp_f32_e32 v62, v51
	v_mul_f32_e32 v51, 0xbfb8aa3b, v53
	v_exp_f32_e32 v51, v51
	s_nop 0
	v_add_f32_e32 v51, 1.0, v51
	v_rcp_f32_e32 v63, v51
	s_nop 0
	v_pk_mul_f32 v[52:53], v[52:53], v[62:63]
	s_nop 0
	v_cvt_pk_bf16_f32 v51, v52, v53
	v_or_b32_e32 v52, 17, v125
	v_mad_i64_i32 v[52:53], s[2:3], v52, s85, v[56:57]
	global_store_dwordx4 v[52:53], v[48:51], off
	v_lshlrev_b32_e32 v62, 16, v140
	v_and_b32_e32 v63, 0xffff0000, v140
	v_pk_fma_f32 v[48:49], v[4:5], v[78:79], v[44:45]
	v_lshlrev_b32_e32 v78, 16, v134
	v_pk_fma_f32 v[48:49], v[24:25], v[76:77], v[48:49]
	v_and_b32_e32 v79, 0xffff0000, v134
	v_pk_fma_f32 v[48:49], v[32:33], v[118:119], v[48:49]
	s_nop 0
	v_pk_fma_f32 v[48:49], v[36:37], v[86:87], v[48:49]
	s_nop 0
	v_pk_fma_f32 v[48:49], v[40:41], v[114:115], v[48:49]
	s_nop 0
	v_mul_f32_e32 v50, 0xbfb8aa3b, v48
; __device__ __forceinline__ float siluf_(float x) { return x * __builtin_amdgcn_rcpf(1.f + __expf(-x)); }
; #define CONV_ACC(rv, j) do { \
;         o[0] += bflo(rv.x) * wgt[j][0]; o[1] += bfhi(rv.x) * wgt[j][1]; \
;         o[2] += bflo(rv.y) * wgt[j][2]; o[3] += bfhi(rv.y) * wgt[j][3]; \
;         o[4] += bflo(rv.z) * wgt[j][4]; o[5] += bfhi(rv.z) * wgt[j][5]; \
;         o[6] += bflo(rv.w) * wgt[j][6]; o[7] += bfhi(rv.w) * wgt[j][7]; } while (0)
; __device__ __forceinline__ void conv_phase(const Params& P, const int pass, const int wvi) {
;     ...
;       for (int j = 0; j < 8; ++j) {
;         float o[8];
; #pragma unroll
;         for (int e = 0; e < 8; ++e) o[e] = bias[e];
;         CONV_ACC(R[j], 0); CONV_ACC(R[j + 1], 1); CONV_ACC(R[j + 2], 2); CONV_ACC(R[j + 3], 3); CONV_ACC(R[j + 4], 4);
;         uint4 ov;
;         ov.x = pk2(siluf_(o[0]), siluf_(o[1])); ov.y = pk2(siluf_(o[2]), siluf_(o[3]));
;         ov.z = pk2(siluf_(o[4]), siluf_(o[5])); ov.w = pk2(siluf_(o[6]), siluf_(o[7]));
;         *(uint4*)(xo + (size_t)(t0 + blk * 8 + j) * CONVD + c0) = ov;
	v_mul_f32_e32 v51, 0xbfb8aa3b, v49
	v_exp_f32_e32 v50, v50
	v_exp_f32_e32 v51, v51
	v_add_f32_e32 v50, 1.0, v50
	v_add_f32_e32 v51, 1.0, v51
	v_rcp_f32_e32 v50, v50
	v_rcp_f32_e32 v51, v51
	s_nop 0
	v_pk_mul_f32 v[48:49], v[48:49], v[50:51]
	v_pk_fma_f32 v[50:51], v[6:7], v[72:73], v[46:47]
	v_cvt_pk_bf16_f32 v48, v48, v49
	v_pk_fma_f32 v[50:51], v[26:27], v[70:71], v[50:51]
	v_lshlrev_b32_e32 v72, 16, v133
	v_pk_fma_f32 v[50:51], v[34:35], v[116:117], v[50:51]
	v_and_b32_e32 v73, 0xffff0000, v133
	v_pk_fma_f32 v[50:51], v[38:39], v[84:85], v[50:51]
	s_nop 0
	v_pk_fma_f32 v[50:51], v[42:43], v[108:109], v[50:51]
	s_nop 0
	v_mul_f32_e32 v49, 0xbfb8aa3b, v50
	v_exp_f32_e32 v49, v49
	s_nop 0
	v_add_f32_e32 v49, 1.0, v49
	v_rcp_f32_e32 v52, v49
	v_mul_f32_e32 v49, 0xbfb8aa3b, v51
	v_exp_f32_e32 v49, v49
	s_nop 0
	v_add_f32_e32 v49, 1.0, v49
	v_rcp_f32_e32 v53, v49
	s_nop 0
	v_pk_mul_f32 v[50:51], v[50:51], v[52:53]
	s_nop 0
	v_cvt_pk_bf16_f32 v49, v50, v51
	v_pk_fma_f32 v[50:51], v[0:1], v[66:67], v[28:29]
	v_lshlrev_b32_e32 v66, 16, v132
	v_pk_fma_f32 v[50:51], v[8:9], v[64:65], v[50:51]
	v_and_b32_e32 v67, 0xffff0000, v132
	v_pk_fma_f32 v[50:51], v[12:13], v[110:111], v[50:51]
	s_nop 0
	v_pk_fma_f32 v[50:51], v[16:17], v[82:83], v[50:51]
	s_nop 0
	v_pk_fma_f32 v[50:51], v[20:21], v[102:103], v[50:51]
	s_nop 0
	v_mul_f32_e32 v52, 0xbfb8aa3b, v50
	v_mul_f32_e32 v53, 0xbfb8aa3b, v51
	v_exp_f32_e32 v52, v52
	v_exp_f32_e32 v53, v53
	v_add_f32_e32 v52, 1.0, v52
	v_add_f32_e32 v53, 1.0, v53
	v_rcp_f32_e32 v52, v52
	v_rcp_f32_e32 v53, v53
	s_nop 0
	v_pk_mul_f32 v[50:51], v[50:51], v[52:53]
	v_pk_fma_f32 v[52:53], v[2:3], v[60:61], v[30:31]
	v_cvt_pk_bf16_f32 v50, v50, v51
	v_pk_fma_f32 v[52:53], v[10:11], v[54:55], v[52:53]
	s_nop 0
	v_pk_fma_f32 v[52:53], v[14:15], v[104:105], v[52:53]
	s_nop 0
	v_pk_fma_f32 v[52:53], v[18:19], v[80:81], v[52:53]
	s_nop 0
	v_pk_fma_f32 v[52:53], v[22:23], v[98:99], v[52:53]
	s_nop 0
	v_mul_f32_e32 v51, 0xbfb8aa3b, v52
	v_exp_f32_e32 v51, v51
	s_nop 0
	v_add_f32_e32 v51, 1.0, v51
	v_rcp_f32_e32 v60, v51
	v_mul_f32_e32 v51, 0xbfb8aa3b, v53
	v_exp_f32_e32 v51, v51
	s_nop 0
	v_add_f32_e32 v51, 1.0, v51
	v_rcp_f32_e32 v61, v51
	s_nop 0
	v_pk_mul_f32 v[52:53], v[52:53], v[60:61]
	s_nop 0
	v_cvt_pk_bf16_f32 v51, v52, v53
	v_or_b32_e32 v52, 18, v125
	v_mad_i64_i32 v[52:53], s[2:3], v52, s85, v[56:57]
	global_store_dwordx4 v[52:53], v[48:51], off
	s_nop 1
	v_pk_fma_f32 v[48:49], v[4:5], v[76:77], v[44:45]
	v_lshlrev_b32_e32 v76, 16, v130
	v_pk_fma_f32 v[48:49], v[24:25], v[118:119], v[48:49]
	v_and_b32_e32 v77, 0xffff0000, v130
	v_pk_fma_f32 v[48:49], v[32:33], v[86:87], v[48:49]
	s_nop 0
	v_pk_fma_f32 v[48:49], v[36:37], v[114:115], v[48:49]
	s_nop 0
	v_pk_fma_f32 v[48:49], v[40:41], v[112:113], v[48:49]
	s_nop 0
	v_mul_f32_e32 v50, 0xbfb8aa3b, v48
	v_mul_f32_e32 v51, 0xbfb8aa3b, v49
	v_exp_f32_e32 v50, v50
	v_exp_f32_e32 v51, v51
	v_add_f32_e32 v50, 1.0, v50
	v_add_f32_e32 v51, 1.0, v51
	v_rcp_f32_e32 v50, v50
	v_rcp_f32_e32 v51, v51
	s_nop 0
	v_pk_mul_f32 v[48:49], v[48:49], v[50:51]
	v_pk_fma_f32 v[50:51], v[6:7], v[70:71], v[46:47]
	v_cvt_pk_bf16_f32 v48, v48, v49
	v_pk_fma_f32 v[50:51], v[26:27], v[116:117], v[50:51]
	v_lshlrev_b32_e32 v70, 16, v129
	v_pk_fma_f32 v[50:51], v[34:35], v[84:85], v[50:51]
	v_and_b32_e32 v71, 0xffff0000, v129
	v_pk_fma_f32 v[50:51], v[38:39], v[108:109], v[50:51]
	s_nop 0
	v_pk_fma_f32 v[50:51], v[42:43], v[106:107], v[50:51]
	s_nop 0
	v_mul_f32_e32 v49, 0xbfb8aa3b, v50
	v_exp_f32_e32 v49, v49
	s_nop 0
	v_add_f32_e32 v49, 1.0, v49
	v_rcp_f32_e32 v52, v49
	v_mul_f32_e32 v49, 0xbfb8aa3b, v51
	v_exp_f32_e32 v49, v49
	s_nop 0
	v_add_f32_e32 v49, 1.0, v49
	v_rcp_f32_e32 v53, v49
	s_nop 0
	v_pk_mul_f32 v[50:51], v[50:51], v[52:53]
	s_nop 0
	v_cvt_pk_bf16_f32 v49, v50, v51
	v_pk_fma_f32 v[50:51], v[0:1], v[64:65], v[28:29]
	s_nop 0
	v_pk_fma_f32 v[50:51], v[8:9], v[110:111], v[50:51]
	s_nop 0
	v_pk_fma_f32 v[50:51], v[12:13], v[82:83], v[50:51]
	s_nop 0
	v_pk_fma_f32 v[50:51], v[16:17], v[102:103], v[50:51]
	s_nop 0
	v_pk_fma_f32 v[50:51], v[20:21], v[100:101], v[50:51]
	s_nop 0
	v_mul_f32_e32 v52, 0xbfb8aa3b, v50
	v_mul_f32_e32 v53, 0xbfb8aa3b, v51
	v_exp_f32_e32 v52, v52
	v_exp_f32_e32 v53, v53
	v_add_f32_e32 v52, 1.0, v52
	v_add_f32_e32 v53, 1.0, v53
	v_rcp_f32_e32 v52, v52
	v_rcp_f32_e32 v53, v53
	s_nop 0
	v_pk_mul_f32 v[50:51], v[50:51], v[52:53]
	v_pk_fma_f32 v[52:53], v[2:3], v[54:55], v[30:31]
	v_cvt_pk_bf16_f32 v50, v50, v51
	v_pk_fma_f32 v[52:53], v[10:11], v[104:105], v[52:53]
	s_nop 0
	v_pk_fma_f32 v[52:53], v[14:15], v[80:81], v[52:53]
	s_nop 0
	v_pk_fma_f32 v[52:53], v[18:19], v[98:99], v[52:53]
	s_nop 0
	v_pk_fma_f32 v[52:53], v[22:23], v[96:97], v[52:53]
	s_nop 0
	v_mul_f32_e32 v51, 0xbfb8aa3b, v52
	v_exp_f32_e32 v51, v51
	s_nop 0
	v_add_f32_e32 v51, 1.0, v51
	v_rcp_f32_e32 v54, v51
	v_mul_f32_e32 v51, 0xbfb8aa3b, v53
	v_exp_f32_e32 v51, v51
	s_nop 0
	v_add_f32_e32 v51, 1.0, v51
	v_rcp_f32_e32 v55, v51
	s_nop 0
	v_pk_mul_f32 v[52:53], v[52:53], v[54:55]
	s_nop 0
	v_cvt_pk_bf16_f32 v51, v52, v53
	v_or_b32_e32 v52, 19, v125
	v_mad_i64_i32 v[52:53], s[2:3], v52, s85, v[56:57]
	global_store_dwordx4 v[52:53], v[48:51], off
	v_lshlrev_b32_e32 v52, 16, v139
	v_and_b32_e32 v53, 0xffff0000, v139
	v_pk_fma_f32 v[48:49], v[4:5], v[118:119], v[44:45]
	s_nop 0
	v_pk_fma_f32 v[48:49], v[24:25], v[86:87], v[48:49]
	s_nop 0
	v_pk_fma_f32 v[48:49], v[32:33], v[114:115], v[48:49]
	s_nop 0
	v_pk_fma_f32 v[48:49], v[36:37], v[112:113], v[48:49]
	s_nop 0
	v_pk_fma_f32 v[48:49], v[40:41], v[74:75], v[48:49]
	s_nop 0
	v_mul_f32_e32 v50, 0xbfb8aa3b, v48
	v_mul_f32_e32 v51, 0xbfb8aa3b, v49
; __device__ __forceinline__ float siluf_(float x) { return x * __builtin_amdgcn_rcpf(1.f + __expf(-x)); }
; #define CONV_ACC(rv, j) do { \
;         o[0] += bflo(rv.x) * wgt[j][0]; o[1] += bfhi(rv.x) * wgt[j][1]; \
;         o[2] += bflo(rv.y) * wgt[j][2]; o[3] += bfhi(rv.y) * wgt[j][3]; \
;         o[4] += bflo(rv.z) * wgt[j][4]; o[5] += bfhi(rv.z) * wgt[j][5]; \
;         o[6] += bflo(rv.w) * wgt[j][6]; o[7] += bfhi(rv.w) * wgt[j][7]; } while (0)
; __device__ __forceinline__ void conv_phase(const Params& P, const int pass, const int wvi) {
;     ...
;       for (int j = 0; j < 8; ++j) {
;         float o[8];
; #pragma unroll
;         for (int e = 0; e < 8; ++e) o[e] = bias[e];
;         CONV_ACC(R[j], 0); CONV_ACC(R[j + 1], 1); CONV_ACC(R[j + 2], 2); CONV_ACC(R[j + 3], 3); CONV_ACC(R[j + 4], 4);
;         uint4 ov;
;         ov.x = pk2(siluf_(o[0]), siluf_(o[1])); ov.y = pk2(siluf_(o[2]), siluf_(o[3]));
;         ov.z = pk2(siluf_(o[4]), siluf_(o[5])); ov.w = pk2(siluf_(o[6]), siluf_(o[7]));
;         *(uint4*)(xo + (size_t)(t0 + blk * 8 + j) * CONVD + c0) = ov;
	v_exp_f32_e32 v50, v50
	v_exp_f32_e32 v51, v51
	v_add_f32_e32 v50, 1.0, v50
	v_add_f32_e32 v51, 1.0, v51
	v_rcp_f32_e32 v50, v50
	v_rcp_f32_e32 v51, v51
	s_nop 0
	v_pk_mul_f32 v[48:49], v[48:49], v[50:51]
	v_pk_fma_f32 v[50:51], v[6:7], v[116:117], v[46:47]
	v_cvt_pk_bf16_f32 v48, v48, v49
	v_pk_fma_f32 v[50:51], v[26:27], v[84:85], v[50:51]
	s_nop 0
	v_pk_fma_f32 v[50:51], v[34:35], v[108:109], v[50:51]
	s_nop 0
	v_pk_fma_f32 v[50:51], v[38:39], v[106:107], v[50:51]
	s_nop 0
	v_pk_fma_f32 v[50:51], v[42:43], v[68:69], v[50:51]
	s_nop 0
	v_mul_f32_e32 v49, 0xbfb8aa3b, v50
	v_exp_f32_e32 v49, v49
	s_nop 0
	v_add_f32_e32 v49, 1.0, v49
	v_rcp_f32_e32 v54, v49
	v_mul_f32_e32 v49, 0xbfb8aa3b, v51
	v_exp_f32_e32 v49, v49
	s_nop 0
	v_add_f32_e32 v49, 1.0, v49
	v_rcp_f32_e32 v55, v49
	s_nop 0
	v_pk_mul_f32 v[50:51], v[50:51], v[54:55]
	s_nop 0
	v_cvt_pk_bf16_f32 v49, v50, v51
	v_pk_fma_f32 v[50:51], v[0:1], v[110:111], v[28:29]
	s_nop 0
	v_pk_fma_f32 v[50:51], v[8:9], v[82:83], v[50:51]
	s_nop 0
	v_pk_fma_f32 v[50:51], v[12:13], v[102:103], v[50:51]
	s_nop 0
	v_pk_fma_f32 v[50:51], v[16:17], v[100:101], v[50:51]
	s_nop 0
	v_pk_fma_f32 v[50:51], v[20:21], v[62:63], v[50:51]
	s_nop 0
	v_mul_f32_e32 v54, 0xbfb8aa3b, v50
	v_mul_f32_e32 v55, 0xbfb8aa3b, v51
	v_exp_f32_e32 v54, v54
	v_exp_f32_e32 v55, v55
	v_add_f32_e32 v54, 1.0, v54
	v_add_f32_e32 v55, 1.0, v55
	v_rcp_f32_e32 v54, v54
	v_rcp_f32_e32 v55, v55
	s_nop 0
	v_pk_mul_f32 v[50:51], v[50:51], v[54:55]
	v_pk_fma_f32 v[54:55], v[2:3], v[104:105], v[30:31]
	v_cvt_pk_bf16_f32 v50, v50, v51
	v_pk_fma_f32 v[54:55], v[10:11], v[80:81], v[54:55]
	s_nop 0
	v_pk_fma_f32 v[54:55], v[14:15], v[98:99], v[54:55]
	s_nop 0
	v_pk_fma_f32 v[54:55], v[18:19], v[96:97], v[54:55]
	s_nop 0
	v_pk_fma_f32 v[54:55], v[22:23], v[52:53], v[54:55]
	s_nop 0
	v_mul_f32_e32 v51, 0xbfb8aa3b, v54
	v_exp_f32_e32 v51, v51
	s_nop 0
	v_add_f32_e32 v51, 1.0, v51
	v_rcp_f32_e32 v60, v51
	v_mul_f32_e32 v51, 0xbfb8aa3b, v55
	v_exp_f32_e32 v51, v51
	s_nop 0
	v_add_f32_e32 v51, 1.0, v51
	v_rcp_f32_e32 v61, v51
	s_nop 0
	v_pk_mul_f32 v[54:55], v[54:55], v[60:61]
	s_nop 0
	v_cvt_pk_bf16_f32 v51, v54, v55
	v_or_b32_e32 v54, 20, v125
	v_mad_i64_i32 v[54:55], s[2:3], v54, s85, v[56:57]
	global_store_dwordx4 v[54:55], v[48:51], off
	s_nop 1
	v_pk_fma_f32 v[48:49], v[4:5], v[86:87], v[44:45]
	s_nop 0
	v_pk_fma_f32 v[48:49], v[24:25], v[114:115], v[48:49]
	s_nop 0
	v_pk_fma_f32 v[48:49], v[32:33], v[112:113], v[48:49]
	s_nop 0
	v_pk_fma_f32 v[48:49], v[36:37], v[74:75], v[48:49]
	s_nop 0
	v_pk_fma_f32 v[48:49], v[40:41], v[94:95], v[48:49]
	s_nop 0
	v_mul_f32_e32 v50, 0xbfb8aa3b, v48
	v_mul_f32_e32 v51, 0xbfb8aa3b, v49
	v_exp_f32_e32 v50, v50
	v_exp_f32_e32 v51, v51
	v_add_f32_e32 v50, 1.0, v50
	v_add_f32_e32 v51, 1.0, v51
	v_rcp_f32_e32 v50, v50
	v_rcp_f32_e32 v51, v51
	s_nop 0
	v_pk_mul_f32 v[48:49], v[48:49], v[50:51]
	v_pk_fma_f32 v[50:51], v[6:7], v[84:85], v[46:47]
	v_cvt_pk_bf16_f32 v48, v48, v49
	v_pk_fma_f32 v[50:51], v[26:27], v[108:109], v[50:51]
	s_nop 0
	v_pk_fma_f32 v[50:51], v[34:35], v[106:107], v[50:51]
	s_nop 0
	v_pk_fma_f32 v[50:51], v[38:39], v[68:69], v[50:51]
	s_nop 0
	v_pk_fma_f32 v[50:51], v[42:43], v[92:93], v[50:51]
	s_nop 0
	v_mul_f32_e32 v49, 0xbfb8aa3b, v50
	v_exp_f32_e32 v49, v49
	s_nop 0
	v_add_f32_e32 v49, 1.0, v49
	v_rcp_f32_e32 v54, v49
	v_mul_f32_e32 v49, 0xbfb8aa3b, v51
	v_exp_f32_e32 v49, v49
	s_nop 0
	v_add_f32_e32 v49, 1.0, v49
	v_rcp_f32_e32 v55, v49
	s_nop 0
	v_pk_mul_f32 v[50:51], v[50:51], v[54:55]
	s_nop 0
	v_cvt_pk_bf16_f32 v49, v50, v51
	v_pk_fma_f32 v[50:51], v[0:1], v[82:83], v[28:29]
	s_nop 0
	v_pk_fma_f32 v[50:51], v[8:9], v[102:103], v[50:51]
	s_nop 0
	v_pk_fma_f32 v[50:51], v[12:13], v[100:101], v[50:51]
	s_nop 0
	v_pk_fma_f32 v[50:51], v[16:17], v[62:63], v[50:51]
	s_nop 0
	v_pk_fma_f32 v[50:51], v[20:21], v[90:91], v[50:51]
	s_nop 0
	v_mul_f32_e32 v54, 0xbfb8aa3b, v50
	v_mul_f32_e32 v55, 0xbfb8aa3b, v51
	v_exp_f32_e32 v54, v54
	v_exp_f32_e32 v55, v55
	v_add_f32_e32 v54, 1.0, v54
	v_add_f32_e32 v55, 1.0, v55
	v_rcp_f32_e32 v54, v54
	v_rcp_f32_e32 v55, v55
	s_nop 0
	v_pk_mul_f32 v[50:51], v[50:51], v[54:55]
	v_pk_fma_f32 v[54:55], v[2:3], v[80:81], v[30:31]
	v_cvt_pk_bf16_f32 v50, v50, v51
	v_pk_fma_f32 v[54:55], v[10:11], v[98:99], v[54:55]
	s_nop 0
	v_pk_fma_f32 v[54:55], v[14:15], v[96:97], v[54:55]
	s_nop 0
	v_pk_fma_f32 v[54:55], v[18:19], v[52:53], v[54:55]
	s_nop 0
	v_pk_fma_f32 v[54:55], v[22:23], v[88:89], v[54:55]
	s_nop 0
	v_mul_f32_e32 v51, 0xbfb8aa3b, v54
	v_exp_f32_e32 v51, v51
	s_nop 0
	v_add_f32_e32 v51, 1.0, v51
	v_rcp_f32_e32 v60, v51
	v_mul_f32_e32 v51, 0xbfb8aa3b, v55
	v_exp_f32_e32 v51, v51
	s_nop 0
	v_add_f32_e32 v51, 1.0, v51
	v_rcp_f32_e32 v61, v51
	s_nop 0
	v_pk_mul_f32 v[54:55], v[54:55], v[60:61]
	s_nop 0
	v_cvt_pk_bf16_f32 v51, v54, v55
	v_or_b32_e32 v54, 21, v125
	v_mad_i64_i32 v[54:55], s[2:3], v54, s85, v[56:57]
	global_store_dwordx4 v[54:55], v[48:51], off
	v_lshlrev_b32_e32 v60, 16, v131
	v_and_b32_e32 v61, 0xffff0000, v131
	v_pk_fma_f32 v[48:49], v[4:5], v[114:115], v[44:45]
	s_nop 0
	v_pk_fma_f32 v[48:49], v[24:25], v[112:113], v[48:49]
	s_nop 0
	v_pk_fma_f32 v[48:49], v[32:33], v[74:75], v[48:49]
	s_nop 0
	v_pk_fma_f32 v[48:49], v[36:37], v[94:95], v[48:49]
	s_nop 0
	v_pk_fma_f32 v[48:49], v[40:41], v[78:79], v[48:49]
	s_nop 0
	v_mul_f32_e32 v50, 0xbfb8aa3b, v48
	v_mul_f32_e32 v51, 0xbfb8aa3b, v49
	v_exp_f32_e32 v50, v50
	v_exp_f32_e32 v51, v51
	v_add_f32_e32 v50, 1.0, v50
	v_add_f32_e32 v51, 1.0, v51
	v_rcp_f32_e32 v50, v50
	v_rcp_f32_e32 v51, v51
	s_nop 0
	v_pk_mul_f32 v[48:49], v[48:49], v[50:51]
	v_pk_fma_f32 v[50:51], v[6:7], v[108:109], v[46:47]
; __device__ __forceinline__ float siluf_(float x) { return x * __builtin_amdgcn_rcpf(1.f + __expf(-x)); }
; #define CONV_ACC(rv, j) do { \
;         o[0] += bflo(rv.x) * wgt[j][0]; o[1] += bfhi(rv.x) * wgt[j][1]; \
;         o[2] += bflo(rv.y) * wgt[j][2]; o[3] += bfhi(rv.y) * wgt[j][3]; \
;         o[4] += bflo(rv.z) * wgt[j][4]; o[5] += bfhi(rv.z) * wgt[j][5]; \
;         o[6] += bflo(rv.w) * wgt[j][6]; o[7] += bfhi(rv.w) * wgt[j][7]; } while (0)
; __device__ __forceinline__ void conv_phase(const Params& P, const int pass, const int wvi) {
;     ...
;     for (int blk = 0; blk < TCH / 8; ++blk) {
; #pragma unroll
;       for (int j = 0; j < 8; ++j) {
;         const int tt2 = blk * 8 + j + 2;
;         const bool v4 = (pos0 + tt2 < S);
;         const uint4 l4 = *(const uint4*)(xin + (size_t)(v4 ? t0 + tt2 : t0) * CONVD + c0);
;         R[4 + j].x = v4 ? l4.x : 0u; R[4 + j].y = v4 ? l4.y : 0u; R[4 + j].z = v4 ? l4.z : 0u; R[4 + j].w = v4 ? l4.w : 0u;
;       }
; #pragma unroll
;       for (int j = 0; j < 8; ++j) {
;         float o[8];
; #pragma unroll
;         for (int e = 0; e < 8; ++e) o[e] = bias[e];
;         CONV_ACC(R[j], 0); CONV_ACC(R[j + 1], 1); CONV_ACC(R[j + 2], 2); CONV_ACC(R[j + 3], 3); CONV_ACC(R[j + 4], 4);
;         uint4 ov;
;         ov.x = pk2(siluf_(o[0]), siluf_(o[1])); ov.y = pk2(siluf_(o[2]), siluf_(o[3]));
;         ov.z = pk2(siluf_(o[4]), siluf_(o[5])); ov.w = pk2(siluf_(o[6]), siluf_(o[7]));
;         *(uint4*)(xo + (size_t)(t0 + blk * 8 + j) * CONVD + c0) = ov;
	v_cvt_pk_bf16_f32 v48, v48, v49
	v_pk_fma_f32 v[50:51], v[26:27], v[106:107], v[50:51]
	s_nop 0
	v_pk_fma_f32 v[50:51], v[34:35], v[68:69], v[50:51]
	s_nop 0
	v_pk_fma_f32 v[50:51], v[38:39], v[92:93], v[50:51]
	s_nop 0
	v_pk_fma_f32 v[50:51], v[42:43], v[72:73], v[50:51]
	s_nop 0
	v_mul_f32_e32 v49, 0xbfb8aa3b, v50
	v_exp_f32_e32 v49, v49
	s_nop 0
	v_add_f32_e32 v49, 1.0, v49
	v_rcp_f32_e32 v54, v49
	v_mul_f32_e32 v49, 0xbfb8aa3b, v51
	v_exp_f32_e32 v49, v49
	s_nop 0
	v_add_f32_e32 v49, 1.0, v49
	v_rcp_f32_e32 v55, v49
	s_nop 0
	v_pk_mul_f32 v[50:51], v[50:51], v[54:55]
	s_nop 0
	v_cvt_pk_bf16_f32 v49, v50, v51
	v_pk_fma_f32 v[50:51], v[0:1], v[102:103], v[28:29]
	s_nop 0
	v_pk_fma_f32 v[50:51], v[8:9], v[100:101], v[50:51]
	s_nop 0
	v_pk_fma_f32 v[50:51], v[12:13], v[62:63], v[50:51]
	s_nop 0
	v_pk_fma_f32 v[50:51], v[16:17], v[90:91], v[50:51]
	s_nop 0
	v_pk_fma_f32 v[50:51], v[20:21], v[66:67], v[50:51]
	s_nop 0
	v_mul_f32_e32 v54, 0xbfb8aa3b, v50
	v_mul_f32_e32 v55, 0xbfb8aa3b, v51
	v_exp_f32_e32 v54, v54
	v_exp_f32_e32 v55, v55
	v_add_f32_e32 v54, 1.0, v54
	v_add_f32_e32 v55, 1.0, v55
	v_rcp_f32_e32 v54, v54
	v_rcp_f32_e32 v55, v55
	s_nop 0
	v_pk_mul_f32 v[50:51], v[50:51], v[54:55]
	v_pk_fma_f32 v[54:55], v[2:3], v[98:99], v[30:31]
	v_cvt_pk_bf16_f32 v50, v50, v51
	v_pk_fma_f32 v[54:55], v[10:11], v[96:97], v[54:55]
	s_nop 0
	v_pk_fma_f32 v[54:55], v[14:15], v[52:53], v[54:55]
	s_nop 0
	v_pk_fma_f32 v[54:55], v[18:19], v[88:89], v[54:55]
	s_nop 0
	v_pk_fma_f32 v[54:55], v[22:23], v[60:61], v[54:55]
	s_nop 0
	v_mul_f32_e32 v51, 0xbfb8aa3b, v54
	v_exp_f32_e32 v51, v51
	s_nop 0
	v_add_f32_e32 v51, 1.0, v51
	v_rcp_f32_e32 v64, v51
	v_mul_f32_e32 v51, 0xbfb8aa3b, v55
	v_exp_f32_e32 v51, v51
	s_nop 0
	v_add_f32_e32 v51, 1.0, v51
	v_rcp_f32_e32 v65, v51
	s_nop 0
	v_pk_mul_f32 v[54:55], v[54:55], v[64:65]
	s_nop 0
	v_cvt_pk_bf16_f32 v51, v54, v55
	v_or_b32_e32 v54, 22, v125
	v_mad_i64_i32 v[54:55], s[2:3], v54, s85, v[56:57]
	global_store_dwordx4 v[54:55], v[48:51], off
	v_lshlrev_b32_e32 v64, 16, v128
	v_and_b32_e32 v65, 0xffff0000, v128
	v_pk_fma_f32 v[48:49], v[4:5], v[112:113], v[44:45]
	v_lshlrev_b32_e32 v54, 16, v127
	v_pk_fma_f32 v[48:49], v[24:25], v[74:75], v[48:49]
	v_and_b32_e32 v55, 0xffff0000, v127
	v_pk_fma_f32 v[48:49], v[32:33], v[94:95], v[48:49]
	s_nop 0
	v_pk_fma_f32 v[48:49], v[36:37], v[78:79], v[48:49]
	s_nop 0
	v_pk_fma_f32 v[48:49], v[40:41], v[76:77], v[48:49]
	s_nop 0
	v_mul_f32_e32 v50, 0xbfb8aa3b, v48
	v_mul_f32_e32 v51, 0xbfb8aa3b, v49
	v_exp_f32_e32 v50, v50
	v_exp_f32_e32 v51, v51
	v_add_f32_e32 v50, 1.0, v50
	v_add_f32_e32 v51, 1.0, v51
	v_rcp_f32_e32 v50, v50
	v_rcp_f32_e32 v51, v51
	s_nop 0
	v_pk_mul_f32 v[48:49], v[48:49], v[50:51]
	v_pk_fma_f32 v[50:51], v[6:7], v[106:107], v[46:47]
	v_cvt_pk_bf16_f32 v48, v48, v49
	v_pk_fma_f32 v[50:51], v[26:27], v[68:69], v[50:51]
	s_nop 0
	v_pk_fma_f32 v[50:51], v[34:35], v[92:93], v[50:51]
	s_nop 0
	v_pk_fma_f32 v[50:51], v[38:39], v[72:73], v[50:51]
	s_nop 0
	v_pk_fma_f32 v[50:51], v[42:43], v[70:71], v[50:51]
	s_nop 0
	v_mul_f32_e32 v49, 0xbfb8aa3b, v50
	v_exp_f32_e32 v49, v49
	s_nop 0
	v_add_f32_e32 v49, 1.0, v49
	v_rcp_f32_e32 v80, v49
	v_mul_f32_e32 v49, 0xbfb8aa3b, v51
	v_exp_f32_e32 v49, v49
	s_nop 0
	v_add_f32_e32 v49, 1.0, v49
	v_rcp_f32_e32 v81, v49
	s_nop 0
	v_pk_mul_f32 v[50:51], v[50:51], v[80:81]
	s_nop 0
	v_cvt_pk_bf16_f32 v49, v50, v51
	v_pk_fma_f32 v[50:51], v[0:1], v[100:101], v[28:29]
	s_nop 0
	v_pk_fma_f32 v[50:51], v[8:9], v[62:63], v[50:51]
	s_nop 0
	v_pk_fma_f32 v[50:51], v[12:13], v[90:91], v[50:51]
	s_nop 0
	v_pk_fma_f32 v[50:51], v[16:17], v[66:67], v[50:51]
	s_nop 0
	v_pk_fma_f32 v[50:51], v[20:21], v[64:65], v[50:51]
	s_nop 0
	v_mul_f32_e32 v80, 0xbfb8aa3b, v50
	v_mul_f32_e32 v81, 0xbfb8aa3b, v51
	v_exp_f32_e32 v80, v80
	v_exp_f32_e32 v81, v81
	v_add_f32_e32 v80, 1.0, v80
	v_add_f32_e32 v81, 1.0, v81
	v_rcp_f32_e32 v80, v80
	v_rcp_f32_e32 v81, v81
	s_nop 0
	v_pk_mul_f32 v[50:51], v[50:51], v[80:81]
	v_pk_fma_f32 v[80:81], v[2:3], v[96:97], v[30:31]
	v_cvt_pk_bf16_f32 v50, v50, v51
	v_pk_fma_f32 v[80:81], v[10:11], v[52:53], v[80:81]
	v_pk_fma_f32 v[52:53], v[2:3], v[52:53], v[30:31]
	v_pk_fma_f32 v[80:81], v[14:15], v[88:89], v[80:81]
	v_pk_fma_f32 v[52:53], v[10:11], v[88:89], v[52:53]
	v_pk_fma_f32 v[80:81], v[18:19], v[60:61], v[80:81]
	v_pk_fma_f32 v[52:53], v[14:15], v[60:61], v[52:53]
	v_pk_fma_f32 v[80:81], v[22:23], v[54:55], v[80:81]
	v_pk_fma_f32 v[52:53], v[18:19], v[54:55], v[52:53]
	v_mul_f32_e32 v51, 0xbfb8aa3b, v80
	v_exp_f32_e32 v51, v51
	s_nop 0
	v_add_f32_e32 v51, 1.0, v51
	v_rcp_f32_e32 v82, v51
	v_mul_f32_e32 v51, 0xbfb8aa3b, v81
	v_exp_f32_e32 v51, v51
	s_nop 0
	v_add_f32_e32 v51, 1.0, v51
	v_rcp_f32_e32 v83, v51
	s_nop 0
	v_pk_mul_f32 v[80:81], v[80:81], v[82:83]
	s_nop 0
	v_cvt_pk_bf16_f32 v51, v80, v81
	v_or_b32_e32 v80, 23, v125
	v_mad_i64_i32 v[80:81], s[2:3], v80, s85, v[56:57]
	global_store_dwordx4 v[80:81], v[48:51], off
	v_cmp_lt_i32_e32 vcc, 26, v126
	s_nop 1
	v_cndmask_b32_e64 v210, 0, 26, vcc
	v_or_b32_e32 v210, v210, v125
	v_mad_i64_i32 v[210:211], s[2:3], v210, s85, v[58:59]
	global_load_dwordx4 v[210:213], v[210:211], off
	v_cmp_lt_i32_e32 vcc, 27, v126
	s_nop 1
	v_cndmask_b32_e64 v214, 0, 27, vcc
	v_or_b32_e32 v214, v214, v125
	v_mad_i64_i32 v[214:215], s[2:3], v214, s85, v[58:59]
	global_load_dwordx4 v[214:217], v[214:215], off
	v_cmp_lt_i32_e32 vcc, 28, v126
	s_nop 1
	v_cndmask_b32_e64 v218, 0, 28, vcc
	v_or_b32_e32 v218, v218, v125
	v_mad_i64_i32 v[218:219], s[2:3], v218, s85, v[58:59]
	global_load_dwordx4 v[218:221], v[218:219], off
	v_cmp_lt_i32_e32 vcc, 29, v126
	s_nop 1
	v_cndmask_b32_e64 v222, 0, 29, vcc
	v_or_b32_e32 v222, v222, v125
	v_mad_i64_i32 v[222:223], s[2:3], v222, s85, v[58:59]
	global_load_dwordx4 v[222:225], v[222:223], off
	v_cmp_lt_i32_e32 vcc, 30, v126
	s_nop 1
	v_cndmask_b32_e64 v226, 0, 30, vcc
	v_or_b32_e32 v226, v226, v125
	v_mad_i64_i32 v[226:227], s[2:3], v226, s85, v[58:59]
	global_load_dwordx4 v[226:229], v[226:227], off
	v_cmp_lt_i32_e32 vcc, 31, v126
	s_nop 1
	v_cndmask_b32_e64 v230, 0, 31, vcc
	v_or_b32_e32 v230, v230, v125
	v_mad_i64_i32 v[230:231], s[2:3], v230, s85, v[58:59]
	global_load_dwordx4 v[230:233], v[230:231], off
	s_waitcnt vmcnt(5)
; __device__ __forceinline__ float siluf_(float x) { return x * __builtin_amdgcn_rcpf(1.f + __expf(-x)); }
; #define CONV_ACC(rv, j) do { \
;         o[0] += bflo(rv.x) * wgt[j][0]; o[1] += bfhi(rv.x) * wgt[j][1]; \
;         o[2] += bflo(rv.y) * wgt[j][2]; o[3] += bfhi(rv.y) * wgt[j][3]; \
;         o[4] += bflo(rv.z) * wgt[j][4]; o[5] += bfhi(rv.z) * wgt[j][5]; \
;         o[6] += bflo(rv.w) * wgt[j][6]; o[7] += bfhi(rv.w) * wgt[j][7]; } while (0)
; __device__ __forceinline__ void conv_phase(const Params& P, const int pass, const int wvi) {
;     ...
;     for (int blk = 0; blk < TCH / 8; ++blk) {
; #pragma unroll
;       for (int j = 0; j < 8; ++j) {
;         const int tt2 = blk * 8 + j + 2;
;         const bool v4 = (pos0 + tt2 < S);
;         const uint4 l4 = *(const uint4*)(xin + (size_t)(v4 ? t0 + tt2 : t0) * CONVD + c0);
;         R[4 + j].x = v4 ? l4.x : 0u; R[4 + j].y = v4 ? l4.y : 0u; R[4 + j].z = v4 ? l4.z : 0u; R[4 + j].w = v4 ? l4.w : 0u;
;       }
; #pragma unroll
;       for (int j = 0; j < 8; ++j) {
;         float o[8];
; #pragma unroll
;         for (int e = 0; e < 8; ++e) o[e] = bias[e];
;         CONV_ACC(R[j], 0); CONV_ACC(R[j + 1], 1); CONV_ACC(R[j + 2], 2); CONV_ACC(R[j + 3], 3); CONV_ACC(R[j + 4], 4);
;         uint4 ov;
;         ov.x = pk2(siluf_(o[0]), siluf_(o[1])); ov.y = pk2(siluf_(o[2]), siluf_(o[3]));
;         ov.z = pk2(siluf_(o[4]), siluf_(o[5])); ov.w = pk2(siluf_(o[6]), siluf_(o[7]));
;         *(uint4*)(xo + (size_t)(t0 + blk * 8 + j) * CONVD + c0) = ov;
	v_cmp_lt_i32_e32 vcc, 26, v126
	s_nop 1
	v_cndmask_b32_e32 v82, 0, v210, vcc
	v_cndmask_b32_e32 v83, 0, v211, vcc
	v_cndmask_b32_e32 v85, 0, v212, vcc
	v_cndmask_b32_e32 v128, 0, v213, vcc
	s_waitcnt vmcnt(4)
	v_cmp_lt_i32_e32 vcc, 27, v126
	s_nop 1
	v_cndmask_b32_e32 v129, 0, v214, vcc
	v_cndmask_b32_e32 v130, 0, v215, vcc
	v_cndmask_b32_e32 v131, 0, v216, vcc
	v_cndmask_b32_e32 v132, 0, v217, vcc
	s_waitcnt vmcnt(3)
	v_cmp_lt_i32_e32 vcc, 28, v126
	s_nop 1
	v_cndmask_b32_e32 v84, 0, v218, vcc
	v_cndmask_b32_e32 v80, 0, v219, vcc
	v_cndmask_b32_e32 v81, 0, v220, vcc
	v_cndmask_b32_e32 v127, 0, v221, vcc
	s_waitcnt vmcnt(2)
	v_cmp_lt_i32_e32 vcc, 29, v126
	s_nop 1
	v_cndmask_b32_e32 v119, 0, v222, vcc
	v_cndmask_b32_e32 v118, 0, v223, vcc
	v_cndmask_b32_e32 v117, 0, v224, vcc
	v_cndmask_b32_e32 v116, 0, v225, vcc
	s_waitcnt vmcnt(1)
	v_cmp_lt_i32_e32 vcc, 30, v126
	s_nop 1
	v_cndmask_b32_e32 v115, 0, v226, vcc
	v_cndmask_b32_e32 v114, 0, v227, vcc
	v_cndmask_b32_e32 v113, 0, v228, vcc
	v_cndmask_b32_e32 v112, 0, v229, vcc
	s_waitcnt vmcnt(0)
	v_cmp_lt_i32_e32 vcc, 31, v126
	s_nop 1
	v_cndmask_b32_e32 v111, 0, v230, vcc
	v_cndmask_b32_e32 v110, 0, v231, vcc
	v_cndmask_b32_e32 v109, 0, v232, vcc
	v_cndmask_b32_e32 v108, 0, v233, vcc
	v_lshlrev_b32_e32 v98, 16, v82
	v_and_b32_e32 v99, 0xffff0000, v82
	v_lshlrev_b32_e32 v96, 16, v83
	v_and_b32_e32 v97, 0xffff0000, v83
	v_lshlrev_b32_e32 v86, 16, v85
	v_and_b32_e32 v87, 0xffff0000, v85
	v_lshlrev_b32_e32 v82, 16, v128
	v_and_b32_e32 v83, 0xffff0000, v128
	v_pk_fma_f32 v[52:53], v[22:23], v[82:83], v[52:53]
	s_nop 0
	v_and_b32_e32 v85, 0xffff0000, v80
	s_nop 0
	v_cmp_lt_i32_e32 vcc, 32, v126
	s_nop 1
	v_cndmask_b32_e64 v48, 0, 32, vcc
	v_add_u32_e32 v48, v48, v125
	v_mad_i64_i32 v[48:49], s[2:3], v48, s85, v[58:59]
	global_load_dwordx4 v[48:51], v[48:49], off
	s_waitcnt vmcnt(0)
	v_cndmask_b32_e32 v107, 0, v48, vcc
	v_cndmask_b32_e32 v106, 0, v49, vcc
	v_cndmask_b32_e32 v105, 0, v50, vcc
	v_cndmask_b32_e32 v104, 0, v51, vcc
	v_cmp_lt_i32_e32 vcc, 33, v126
	v_or_b32_e32 v126, 24, v125
	s_nop 0
	v_cndmask_b32_e64 v48, 0, 33, vcc
	v_add_u32_e32 v48, v48, v125
	v_mad_i64_i32 v[48:49], s[2:3], v48, s85, v[58:59]
	global_load_dwordx4 v[48:51], v[48:49], off
	s_waitcnt vmcnt(0)
	v_cndmask_b32_e32 v103, 0, v48, vcc
	v_cndmask_b32_e32 v102, 0, v49, vcc
	v_pk_fma_f32 v[48:49], v[4:5], v[74:75], v[44:45]
	v_cndmask_b32_e32 v101, 0, v50, vcc
	v_pk_fma_f32 v[48:49], v[24:25], v[94:95], v[48:49]
	v_cndmask_b32_e32 v100, 0, v51, vcc
	v_pk_fma_f32 v[48:49], v[32:33], v[78:79], v[48:49]
	s_nop 0
	v_pk_fma_f32 v[48:49], v[36:37], v[76:77], v[48:49]
	s_nop 0
	v_pk_fma_f32 v[48:49], v[40:41], v[98:99], v[48:49]
	s_nop 0
	v_mul_f32_e32 v50, 0xbfb8aa3b, v48
	v_mul_f32_e32 v51, 0xbfb8aa3b, v49
	v_exp_f32_e32 v50, v50
	v_exp_f32_e32 v51, v51
	v_add_f32_e32 v50, 1.0, v50
	v_add_f32_e32 v51, 1.0, v51
	v_rcp_f32_e32 v50, v50
	v_rcp_f32_e32 v51, v51
	s_nop 0
	v_pk_mul_f32 v[48:49], v[48:49], v[50:51]
	v_pk_fma_f32 v[50:51], v[6:7], v[68:69], v[46:47]
	v_cvt_pk_bf16_f32 v48, v48, v49
	v_pk_fma_f32 v[50:51], v[26:27], v[92:93], v[50:51]
	v_lshlrev_b32_e32 v68, 16, v129
	v_pk_fma_f32 v[50:51], v[34:35], v[72:73], v[50:51]
	v_and_b32_e32 v69, 0xffff0000, v129
	v_pk_fma_f32 v[50:51], v[38:39], v[70:71], v[50:51]
	s_nop 0
	v_pk_fma_f32 v[50:51], v[42:43], v[96:97], v[50:51]
	s_nop 0
	v_mul_f32_e32 v49, 0xbfb8aa3b, v50
	v_exp_f32_e32 v49, v49
	s_nop 0
	v_add_f32_e32 v49, 1.0, v49
	v_rcp_f32_e32 v58, v49
	v_mul_f32_e32 v49, 0xbfb8aa3b, v51
	v_exp_f32_e32 v49, v49
	s_nop 0
	v_add_f32_e32 v49, 1.0, v49
	v_rcp_f32_e32 v59, v49
	s_nop 0
	v_pk_mul_f32 v[50:51], v[50:51], v[58:59]
	s_nop 0
	v_cvt_pk_bf16_f32 v49, v50, v51
	v_pk_fma_f32 v[50:51], v[0:1], v[62:63], v[28:29]
	v_lshlrev_b32_e32 v62, 16, v130
	v_pk_fma_f32 v[50:51], v[8:9], v[90:91], v[50:51]
	v_and_b32_e32 v63, 0xffff0000, v130
	v_pk_fma_f32 v[50:51], v[12:13], v[66:67], v[50:51]
	s_nop 0
	v_pk_fma_f32 v[50:51], v[16:17], v[64:65], v[50:51]
	s_nop 0
	v_pk_fma_f32 v[50:51], v[20:21], v[86:87], v[50:51]
	s_nop 0
	v_mul_f32_e32 v58, 0xbfb8aa3b, v50
	v_mul_f32_e32 v59, 0xbfb8aa3b, v51
	v_exp_f32_e32 v58, v58
	v_exp_f32_e32 v59, v59
	v_add_f32_e32 v58, 1.0, v58
	v_add_f32_e32 v59, 1.0, v59
	v_rcp_f32_e32 v58, v58
	v_rcp_f32_e32 v59, v59
	s_nop 0
	v_pk_mul_f32 v[50:51], v[50:51], v[58:59]
	s_nop 0
	v_cvt_pk_bf16_f32 v50, v50, v51
	v_mul_f32_e32 v51, 0xbfb8aa3b, v52
	v_exp_f32_e32 v51, v51
	s_nop 0
	v_add_f32_e32 v51, 1.0, v51
	v_rcp_f32_e32 v58, v51
	v_mul_f32_e32 v51, 0xbfb8aa3b, v53
	v_exp_f32_e32 v51, v51
	s_nop 0
	v_add_f32_e32 v51, 1.0, v51
	v_rcp_f32_e32 v59, v51
	s_nop 0
	v_pk_mul_f32 v[52:53], v[52:53], v[58:59]
	s_nop 0
	v_cvt_pk_bf16_f32 v51, v52, v53
	v_mad_i64_i32 v[52:53], s[2:3], v126, s85, v[56:57]
	global_store_dwordx4 v[52:53], v[48:51], off
	v_lshlrev_b32_e32 v58, 16, v131
	v_and_b32_e32 v59, 0xffff0000, v131
	v_pk_fma_f32 v[48:49], v[4:5], v[94:95], v[44:45]
	v_lshlrev_b32_e32 v52, 16, v132
	v_pk_fma_f32 v[48:49], v[24:25], v[78:79], v[48:49]
	v_and_b32_e32 v53, 0xffff0000, v132
	v_pk_fma_f32 v[48:49], v[32:33], v[76:77], v[48:49]
	s_nop 0
	v_pk_fma_f32 v[48:49], v[36:37], v[98:99], v[48:49]
	s_nop 0
	v_pk_fma_f32 v[48:49], v[40:41], v[68:69], v[48:49]
	s_nop 0
	v_mul_f32_e32 v50, 0xbfb8aa3b, v48
	v_mul_f32_e32 v51, 0xbfb8aa3b, v49
	v_exp_f32_e32 v50, v50
	v_exp_f32_e32 v51, v51
	v_add_f32_e32 v50, 1.0, v50
	v_add_f32_e32 v51, 1.0, v51
	v_rcp_f32_e32 v50, v50
	v_rcp_f32_e32 v51, v51
	s_nop 0
	v_pk_mul_f32 v[48:49], v[48:49], v[50:51]
	v_pk_fma_f32 v[50:51], v[6:7], v[92:93], v[46:47]
	v_cvt_pk_bf16_f32 v48, v48, v49
	v_pk_fma_f32 v[50:51], v[26:27], v[72:73], v[50:51]
; __device__ __forceinline__ float siluf_(float x) { return x * __builtin_amdgcn_rcpf(1.f + __expf(-x)); }
; #define CONV_ACC(rv, j) do { \
;         o[0] += bflo(rv.x) * wgt[j][0]; o[1] += bfhi(rv.x) * wgt[j][1]; \
;         o[2] += bflo(rv.y) * wgt[j][2]; o[3] += bfhi(rv.y) * wgt[j][3]; \
;         o[4] += bflo(rv.z) * wgt[j][4]; o[5] += bfhi(rv.z) * wgt[j][5]; \
;         o[6] += bflo(rv.w) * wgt[j][6]; o[7] += bfhi(rv.w) * wgt[j][7]; } while (0)
; __device__ __forceinline__ void conv_phase(const Params& P, const int pass, const int wvi) {
;     ...
;       for (int j = 0; j < 8; ++j) {
;         float o[8];
; #pragma unroll
;         for (int e = 0; e < 8; ++e) o[e] = bias[e];
;         CONV_ACC(R[j], 0); CONV_ACC(R[j + 1], 1); CONV_ACC(R[j + 2], 2); CONV_ACC(R[j + 3], 3); CONV_ACC(R[j + 4], 4);
;         uint4 ov;
;         ov.x = pk2(siluf_(o[0]), siluf_(o[1])); ov.y = pk2(siluf_(o[2]), siluf_(o[3]));
;         ov.z = pk2(siluf_(o[4]), siluf_(o[5])); ov.w = pk2(siluf_(o[6]), siluf_(o[7]));
;         *(uint4*)(xo + (size_t)(t0 + blk * 8 + j) * CONVD + c0) = ov;
	v_lshlrev_b32_e32 v92, 16, v111
	v_pk_fma_f32 v[50:51], v[34:35], v[70:71], v[50:51]
	v_and_b32_e32 v93, 0xffff0000, v111
	v_pk_fma_f32 v[50:51], v[38:39], v[96:97], v[50:51]
	s_nop 0
	v_pk_fma_f32 v[50:51], v[42:43], v[62:63], v[50:51]
	s_nop 0
	v_mul_f32_e32 v49, 0xbfb8aa3b, v50
	v_exp_f32_e32 v49, v49
	s_nop 0
	v_add_f32_e32 v49, 1.0, v49
	v_rcp_f32_e32 v74, v49
	v_mul_f32_e32 v49, 0xbfb8aa3b, v51
	v_exp_f32_e32 v49, v49
	s_nop 0
	v_add_f32_e32 v49, 1.0, v49
	v_rcp_f32_e32 v75, v49
	s_nop 0
	v_pk_mul_f32 v[50:51], v[50:51], v[74:75]
	s_nop 0
	v_cvt_pk_bf16_f32 v49, v50, v51
	v_pk_fma_f32 v[50:51], v[0:1], v[90:91], v[28:29]
	s_nop 0
	v_pk_fma_f32 v[50:51], v[8:9], v[66:67], v[50:51]
	s_nop 0
	v_pk_fma_f32 v[50:51], v[12:13], v[64:65], v[50:51]
	s_nop 0
	v_pk_fma_f32 v[50:51], v[16:17], v[86:87], v[50:51]
	s_nop 0
	v_pk_fma_f32 v[50:51], v[20:21], v[58:59], v[50:51]
	s_nop 0
	v_mul_f32_e32 v74, 0xbfb8aa3b, v50
	v_mul_f32_e32 v75, 0xbfb8aa3b, v51
	v_exp_f32_e32 v74, v74
	v_exp_f32_e32 v75, v75
	v_add_f32_e32 v74, 1.0, v74
	v_add_f32_e32 v75, 1.0, v75
	v_rcp_f32_e32 v74, v74
	v_rcp_f32_e32 v75, v75
	s_nop 0
	v_pk_mul_f32 v[50:51], v[50:51], v[74:75]
	v_pk_fma_f32 v[74:75], v[2:3], v[88:89], v[30:31]
	v_cvt_pk_bf16_f32 v50, v50, v51
	v_pk_fma_f32 v[74:75], v[10:11], v[60:61], v[74:75]
	v_pk_fma_f32 v[60:61], v[2:3], v[60:61], v[30:31]
	v_pk_fma_f32 v[74:75], v[14:15], v[54:55], v[74:75]
	v_pk_fma_f32 v[60:61], v[10:11], v[54:55], v[60:61]
	v_pk_fma_f32 v[74:75], v[18:19], v[82:83], v[74:75]
	v_pk_fma_f32 v[60:61], v[14:15], v[82:83], v[60:61]
	v_pk_fma_f32 v[74:75], v[22:23], v[52:53], v[74:75]
	v_pk_fma_f32 v[60:61], v[18:19], v[52:53], v[60:61]
	v_mul_f32_e32 v51, 0xbfb8aa3b, v74
	v_exp_f32_e32 v51, v51
	v_pk_fma_f32 v[54:55], v[2:3], v[54:55], v[30:31]
	v_add_f32_e32 v51, 1.0, v51
	v_rcp_f32_e32 v88, v51
	v_mul_f32_e32 v51, 0xbfb8aa3b, v75
	v_exp_f32_e32 v51, v51
	v_pk_fma_f32 v[54:55], v[10:11], v[82:83], v[54:55]
	v_pk_fma_f32 v[82:83], v[2:3], v[82:83], v[30:31]
	v_pk_fma_f32 v[54:55], v[14:15], v[52:53], v[54:55]
	v_add_f32_e32 v51, 1.0, v51
	v_rcp_f32_e32 v89, v51
	v_pk_fma_f32 v[82:83], v[10:11], v[52:53], v[82:83]
	v_pk_fma_f32 v[52:53], v[2:3], v[52:53], v[30:31]
	v_pk_mul_f32 v[74:75], v[74:75], v[88:89]
	s_nop 0
	v_cvt_pk_bf16_f32 v51, v74, v75
	v_or_b32_e32 v74, 25, v125
	v_mad_i64_i32 v[74:75], s[2:3], v74, s85, v[56:57]
	global_store_dwordx4 v[74:75], v[48:51], off
	v_lshlrev_b32_e32 v88, 16, v84
	v_and_b32_e32 v89, 0xffff0000, v84
	v_pk_fma_f32 v[48:49], v[4:5], v[78:79], v[44:45]
	v_lshlrev_b32_e32 v84, 16, v80
	v_pk_fma_f32 v[48:49], v[24:25], v[76:77], v[48:49]
	v_lshlrev_b32_e32 v80, 16, v81
	v_pk_fma_f32 v[48:49], v[32:33], v[98:99], v[48:49]
	v_and_b32_e32 v81, 0xffff0000, v81
	v_pk_fma_f32 v[48:49], v[36:37], v[68:69], v[48:49]
	v_lshlrev_b32_e32 v74, 16, v127
	v_pk_fma_f32 v[48:49], v[40:41], v[88:89], v[48:49]
	v_and_b32_e32 v75, 0xffff0000, v127
	v_mul_f32_e32 v50, 0xbfb8aa3b, v48
	v_mul_f32_e32 v51, 0xbfb8aa3b, v49
	v_exp_f32_e32 v50, v50
	v_exp_f32_e32 v51, v51
	v_pk_fma_f32 v[60:61], v[22:23], v[74:75], v[60:61]
	v_lshlrev_b32_e32 v78, 16, v119
	v_add_f32_e32 v50, 1.0, v50
	v_add_f32_e32 v51, 1.0, v51
	v_rcp_f32_e32 v50, v50
	v_rcp_f32_e32 v51, v51
	v_and_b32_e32 v79, 0xffff0000, v119
	v_pk_fma_f32 v[54:55], v[18:19], v[74:75], v[54:55]
	v_pk_fma_f32 v[82:83], v[14:15], v[74:75], v[82:83]
	v_pk_mul_f32 v[48:49], v[48:49], v[50:51]
	v_pk_fma_f32 v[50:51], v[6:7], v[72:73], v[46:47]
	v_cvt_pk_bf16_f32 v48, v48, v49
	v_pk_fma_f32 v[50:51], v[26:27], v[70:71], v[50:51]
	v_pk_fma_f32 v[52:53], v[10:11], v[74:75], v[52:53]
	v_pk_fma_f32 v[50:51], v[34:35], v[96:97], v[50:51]
	v_pk_fma_f32 v[74:75], v[2:3], v[74:75], v[30:31]
	v_pk_fma_f32 v[50:51], v[38:39], v[62:63], v[50:51]
	s_nop 0
	v_pk_fma_f32 v[50:51], v[42:43], v[84:85], v[50:51]
	s_nop 0
	v_mul_f32_e32 v49, 0xbfb8aa3b, v50
	v_exp_f32_e32 v49, v49
	s_nop 0
	v_add_f32_e32 v49, 1.0, v49
	v_rcp_f32_e32 v72, v49
	v_mul_f32_e32 v49, 0xbfb8aa3b, v51
	v_exp_f32_e32 v49, v49
	s_nop 0
	v_add_f32_e32 v49, 1.0, v49
	v_rcp_f32_e32 v73, v49
	s_nop 0
	v_pk_mul_f32 v[50:51], v[50:51], v[72:73]
	s_nop 0
	v_cvt_pk_bf16_f32 v49, v50, v51
	v_pk_fma_f32 v[50:51], v[0:1], v[66:67], v[28:29]
	v_lshlrev_b32_e32 v72, 16, v118
	v_pk_fma_f32 v[50:51], v[8:9], v[64:65], v[50:51]
	v_and_b32_e32 v73, 0xffff0000, v118
	v_pk_fma_f32 v[50:51], v[12:13], v[86:87], v[50:51]
	s_nop 0
	v_pk_fma_f32 v[50:51], v[16:17], v[58:59], v[50:51]
	s_nop 0
	v_pk_fma_f32 v[50:51], v[20:21], v[80:81], v[50:51]
	s_nop 0
	v_mul_f32_e32 v66, 0xbfb8aa3b, v50
	v_mul_f32_e32 v67, 0xbfb8aa3b, v51
	v_exp_f32_e32 v66, v66
	v_exp_f32_e32 v67, v67
	v_add_f32_e32 v66, 1.0, v66
	v_add_f32_e32 v67, 1.0, v67
	v_rcp_f32_e32 v66, v66
	v_rcp_f32_e32 v67, v67
	s_nop 0
	v_pk_mul_f32 v[50:51], v[50:51], v[66:67]
	s_nop 0
	v_cvt_pk_bf16_f32 v50, v50, v51
	v_mul_f32_e32 v51, 0xbfb8aa3b, v60
	v_exp_f32_e32 v51, v51
	s_nop 0
	v_add_f32_e32 v51, 1.0, v51
	v_rcp_f32_e32 v66, v51
	v_mul_f32_e32 v51, 0xbfb8aa3b, v61
	v_exp_f32_e32 v51, v51
	s_nop 0
	v_add_f32_e32 v51, 1.0, v51
	v_rcp_f32_e32 v67, v51
	s_nop 0
	v_pk_mul_f32 v[60:61], v[60:61], v[66:67]
	s_nop 0
	v_cvt_pk_bf16_f32 v51, v60, v61
	v_or_b32_e32 v60, 26, v125
	v_mad_i64_i32 v[60:61], s[2:3], v60, s85, v[56:57]
	global_store_dwordx4 v[60:61], v[48:51], off
	v_lshlrev_b32_e32 v66, 16, v117
	v_and_b32_e32 v67, 0xffff0000, v117
	v_pk_fma_f32 v[48:49], v[4:5], v[76:77], v[44:45]
	v_lshlrev_b32_e32 v60, 16, v116
	v_pk_fma_f32 v[48:49], v[24:25], v[98:99], v[48:49]
	v_and_b32_e32 v61, 0xffff0000, v116
	v_pk_fma_f32 v[48:49], v[32:33], v[68:69], v[48:49]
; __device__ __forceinline__ float siluf_(float x) { return x * __builtin_amdgcn_rcpf(1.f + __expf(-x)); }
; #define CONV_ACC(rv, j) do { \
;         o[0] += bflo(rv.x) * wgt[j][0]; o[1] += bfhi(rv.x) * wgt[j][1]; \
;         o[2] += bflo(rv.y) * wgt[j][2]; o[3] += bfhi(rv.y) * wgt[j][3]; \
;         o[4] += bflo(rv.z) * wgt[j][4]; o[5] += bfhi(rv.z) * wgt[j][5]; \
;         o[6] += bflo(rv.w) * wgt[j][6]; o[7] += bfhi(rv.w) * wgt[j][7]; } while (0)
; __device__ __forceinline__ void conv_phase(const Params& P, const int pass, const int wvi) {
;     ...
;       for (int j = 0; j < 8; ++j) {
;         float o[8];
; #pragma unroll
;         for (int e = 0; e < 8; ++e) o[e] = bias[e];
;         CONV_ACC(R[j], 0); CONV_ACC(R[j + 1], 1); CONV_ACC(R[j + 2], 2); CONV_ACC(R[j + 3], 3); CONV_ACC(R[j + 4], 4);
;         uint4 ov;
;         ov.x = pk2(siluf_(o[0]), siluf_(o[1])); ov.y = pk2(siluf_(o[2]), siluf_(o[3]));
;         ov.z = pk2(siluf_(o[4]), siluf_(o[5])); ov.w = pk2(siluf_(o[6]), siluf_(o[7]));
;         *(uint4*)(xo + (size_t)(t0 + blk * 8 + j) * CONVD + c0) = ov;
	v_pk_fma_f32 v[54:55], v[22:23], v[60:61], v[54:55]
	v_pk_fma_f32 v[48:49], v[36:37], v[88:89], v[48:49]
	v_lshlrev_b32_e32 v76, 16, v115
	v_pk_fma_f32 v[48:49], v[40:41], v[78:79], v[48:49]
	v_and_b32_e32 v77, 0xffff0000, v115
	v_mul_f32_e32 v50, 0xbfb8aa3b, v48
	v_mul_f32_e32 v51, 0xbfb8aa3b, v49
	v_exp_f32_e32 v50, v50
	v_exp_f32_e32 v51, v51
	v_pk_fma_f32 v[82:83], v[18:19], v[60:61], v[82:83]
	v_pk_fma_f32 v[52:53], v[14:15], v[60:61], v[52:53]
	v_add_f32_e32 v50, 1.0, v50
	v_add_f32_e32 v51, 1.0, v51
	v_rcp_f32_e32 v50, v50
	v_rcp_f32_e32 v51, v51
	v_pk_fma_f32 v[74:75], v[10:11], v[60:61], v[74:75]
	v_pk_mul_f32 v[48:49], v[48:49], v[50:51]
	v_pk_fma_f32 v[50:51], v[6:7], v[70:71], v[46:47]
	v_cvt_pk_bf16_f32 v48, v48, v49
	v_pk_fma_f32 v[50:51], v[26:27], v[96:97], v[50:51]
	s_nop 0
	v_pk_fma_f32 v[50:51], v[34:35], v[62:63], v[50:51]
	s_nop 0
	v_pk_fma_f32 v[50:51], v[38:39], v[84:85], v[50:51]
	s_nop 0
	v_pk_fma_f32 v[50:51], v[42:43], v[72:73], v[50:51]
	s_nop 0
	v_mul_f32_e32 v49, 0xbfb8aa3b, v50
	v_exp_f32_e32 v49, v49
	s_nop 0
	v_add_f32_e32 v49, 1.0, v49
	v_rcp_f32_e32 v70, v49
	v_mul_f32_e32 v49, 0xbfb8aa3b, v51
	v_exp_f32_e32 v49, v49
	s_nop 0
	v_add_f32_e32 v49, 1.0, v49
	v_rcp_f32_e32 v71, v49
	s_nop 0
	v_pk_mul_f32 v[50:51], v[50:51], v[70:71]
	s_nop 0
	v_cvt_pk_bf16_f32 v49, v50, v51
	v_pk_fma_f32 v[50:51], v[0:1], v[64:65], v[28:29]
	v_lshlrev_b32_e32 v70, 16, v114
	v_pk_fma_f32 v[50:51], v[8:9], v[86:87], v[50:51]
	v_and_b32_e32 v71, 0xffff0000, v114
	v_pk_fma_f32 v[50:51], v[12:13], v[58:59], v[50:51]
	s_nop 0
	v_pk_fma_f32 v[50:51], v[16:17], v[80:81], v[50:51]
	s_nop 0
	v_pk_fma_f32 v[50:51], v[20:21], v[66:67], v[50:51]
	s_nop 0
	v_mul_f32_e32 v64, 0xbfb8aa3b, v50
	v_mul_f32_e32 v65, 0xbfb8aa3b, v51
	v_exp_f32_e32 v64, v64
	v_exp_f32_e32 v65, v65
	v_add_f32_e32 v64, 1.0, v64
	v_add_f32_e32 v65, 1.0, v65
	v_rcp_f32_e32 v64, v64
	v_rcp_f32_e32 v65, v65
	s_nop 0
	v_pk_mul_f32 v[50:51], v[50:51], v[64:65]
	s_nop 0
	v_cvt_pk_bf16_f32 v50, v50, v51
	v_mul_f32_e32 v51, 0xbfb8aa3b, v54
	v_exp_f32_e32 v51, v51
	s_nop 0
	v_add_f32_e32 v51, 1.0, v51
	v_rcp_f32_e32 v64, v51
	v_mul_f32_e32 v51, 0xbfb8aa3b, v55
	v_exp_f32_e32 v51, v51
	s_nop 0
	v_add_f32_e32 v51, 1.0, v51
	v_rcp_f32_e32 v65, v51
	s_nop 0
	v_pk_mul_f32 v[54:55], v[54:55], v[64:65]
	s_nop 0
	v_cvt_pk_bf16_f32 v51, v54, v55
	v_or_b32_e32 v54, 27, v125
	v_mad_i64_i32 v[54:55], s[2:3], v54, s85, v[56:57]
	global_store_dwordx4 v[54:55], v[48:51], off
	v_lshlrev_b32_e32 v64, 16, v113
	v_and_b32_e32 v65, 0xffff0000, v113
	v_pk_fma_f32 v[48:49], v[4:5], v[98:99], v[44:45]
	v_lshlrev_b32_e32 v54, 16, v112
	v_pk_fma_f32 v[48:49], v[24:25], v[68:69], v[48:49]
	v_and_b32_e32 v55, 0xffff0000, v112
	v_pk_fma_f32 v[48:49], v[32:33], v[88:89], v[48:49]
	v_pk_fma_f32 v[82:83], v[22:23], v[54:55], v[82:83]
	v_pk_fma_f32 v[48:49], v[36:37], v[78:79], v[48:49]
	v_pk_fma_f32 v[52:53], v[18:19], v[54:55], v[52:53]
	v_pk_fma_f32 v[48:49], v[40:41], v[76:77], v[48:49]
	v_pk_fma_f32 v[74:75], v[14:15], v[54:55], v[74:75]
	v_mul_f32_e32 v50, 0xbfb8aa3b, v48
	v_mul_f32_e32 v51, 0xbfb8aa3b, v49
	v_exp_f32_e32 v50, v50
	v_exp_f32_e32 v51, v51
	v_add_f32_e32 v50, 1.0, v50
	v_add_f32_e32 v51, 1.0, v51
	v_rcp_f32_e32 v50, v50
	v_rcp_f32_e32 v51, v51
	s_nop 0
	v_pk_mul_f32 v[48:49], v[48:49], v[50:51]
	v_pk_fma_f32 v[50:51], v[6:7], v[96:97], v[46:47]
	v_cvt_pk_bf16_f32 v48, v48, v49
	v_pk_fma_f32 v[50:51], v[26:27], v[62:63], v[50:51]
	s_nop 0
	v_pk_fma_f32 v[50:51], v[34:35], v[84:85], v[50:51]
	s_nop 0
	v_pk_fma_f32 v[50:51], v[38:39], v[72:73], v[50:51]
	s_nop 0
	v_pk_fma_f32 v[50:51], v[42:43], v[70:71], v[50:51]
	s_nop 0
	v_mul_f32_e32 v49, 0xbfb8aa3b, v50
	v_exp_f32_e32 v49, v49
	s_nop 0
	v_add_f32_e32 v49, 1.0, v49
	v_rcp_f32_e32 v90, v49
	v_mul_f32_e32 v49, 0xbfb8aa3b, v51
	v_exp_f32_e32 v49, v49
	s_nop 0
	v_add_f32_e32 v49, 1.0, v49
	v_rcp_f32_e32 v91, v49
	s_nop 0
	v_pk_mul_f32 v[50:51], v[50:51], v[90:91]
	s_nop 0
	v_cvt_pk_bf16_f32 v49, v50, v51
	v_pk_fma_f32 v[50:51], v[0:1], v[86:87], v[28:29]
	v_lshlrev_b32_e32 v90, 16, v110
	v_pk_fma_f32 v[50:51], v[8:9], v[58:59], v[50:51]
	v_and_b32_e32 v91, 0xffff0000, v110
	v_pk_fma_f32 v[50:51], v[12:13], v[80:81], v[50:51]
	s_nop 0
	v_pk_fma_f32 v[50:51], v[16:17], v[66:67], v[50:51]
	s_nop 0
	v_pk_fma_f32 v[50:51], v[20:21], v[64:65], v[50:51]
	s_nop 0
	v_mul_f32_e32 v86, 0xbfb8aa3b, v50
	v_mul_f32_e32 v87, 0xbfb8aa3b, v51
	v_exp_f32_e32 v86, v86
	v_exp_f32_e32 v87, v87
	v_add_f32_e32 v86, 1.0, v86
	v_add_f32_e32 v87, 1.0, v87
	v_rcp_f32_e32 v86, v86
	v_rcp_f32_e32 v87, v87
	s_nop 0
	v_pk_mul_f32 v[50:51], v[50:51], v[86:87]
	s_nop 0
	v_cvt_pk_bf16_f32 v50, v50, v51
	v_mul_f32_e32 v51, 0xbfb8aa3b, v82
	v_exp_f32_e32 v51, v51
	s_nop 0
	v_add_f32_e32 v51, 1.0, v51
	v_rcp_f32_e32 v86, v51
	v_mul_f32_e32 v51, 0xbfb8aa3b, v83
	v_exp_f32_e32 v51, v51
	s_nop 0
	v_add_f32_e32 v51, 1.0, v51
	v_rcp_f32_e32 v87, v51
	s_nop 0
	v_pk_mul_f32 v[82:83], v[82:83], v[86:87]
	s_nop 0
	v_cvt_pk_bf16_f32 v51, v82, v83
	v_or_b32_e32 v82, 28, v125
	v_mad_i64_i32 v[82:83], s[2:3], v82, s85, v[56:57]
	global_store_dwordx4 v[82:83], v[48:51], off
	v_lshlrev_b32_e32 v86, 16, v109
	v_and_b32_e32 v87, 0xffff0000, v109
	v_pk_fma_f32 v[48:49], v[4:5], v[68:69], v[44:45]
	v_lshlrev_b32_e32 v82, 16, v108
	v_pk_fma_f32 v[48:49], v[24:25], v[88:89], v[48:49]
	v_and_b32_e32 v83, 0xffff0000, v108
	v_pk_fma_f32 v[48:49], v[32:33], v[78:79], v[48:49]
	v_pk_fma_f32 v[52:53], v[22:23], v[82:83], v[52:53]
	v_pk_fma_f32 v[48:49], v[36:37], v[76:77], v[48:49]
	v_lshlrev_b32_e32 v68, 16, v107
	v_pk_fma_f32 v[48:49], v[40:41], v[92:93], v[48:49]
	v_and_b32_e32 v69, 0xffff0000, v107
; __device__ __forceinline__ float siluf_(float x) { return x * __builtin_amdgcn_rcpf(1.f + __expf(-x)); }
; #define CONV_ACC(rv, j) do { \
;         o[0] += bflo(rv.x) * wgt[j][0]; o[1] += bfhi(rv.x) * wgt[j][1]; \
;         o[2] += bflo(rv.y) * wgt[j][2]; o[3] += bfhi(rv.y) * wgt[j][3]; \
;         o[4] += bflo(rv.z) * wgt[j][4]; o[5] += bfhi(rv.z) * wgt[j][5]; \
;         o[6] += bflo(rv.w) * wgt[j][6]; o[7] += bfhi(rv.w) * wgt[j][7]; } while (0)
; __device__ __forceinline__ void conv_phase(const Params& P, const int pass, const int wvi) {
;     ...
;       for (int j = 0; j < 8; ++j) {
;         float o[8];
; #pragma unroll
;         for (int e = 0; e < 8; ++e) o[e] = bias[e];
;         CONV_ACC(R[j], 0); CONV_ACC(R[j + 1], 1); CONV_ACC(R[j + 2], 2); CONV_ACC(R[j + 3], 3); CONV_ACC(R[j + 4], 4);
;         uint4 ov;
;         ov.x = pk2(siluf_(o[0]), siluf_(o[1])); ov.y = pk2(siluf_(o[2]), siluf_(o[3]));
;         ov.z = pk2(siluf_(o[4]), siluf_(o[5])); ov.w = pk2(siluf_(o[6]), siluf_(o[7]));
;         *(uint4*)(xo + (size_t)(t0 + blk * 8 + j) * CONVD + c0) = ov;
	v_mul_f32_e32 v50, 0xbfb8aa3b, v48
	v_mul_f32_e32 v51, 0xbfb8aa3b, v49
	v_exp_f32_e32 v50, v50
	v_exp_f32_e32 v51, v51
	v_pk_fma_f32 v[74:75], v[18:19], v[82:83], v[74:75]
	v_add_f32_e32 v50, 1.0, v50
	v_add_f32_e32 v51, 1.0, v51
	v_rcp_f32_e32 v50, v50
	v_rcp_f32_e32 v51, v51
	s_nop 0
	v_pk_mul_f32 v[48:49], v[48:49], v[50:51]
	v_pk_fma_f32 v[50:51], v[6:7], v[62:63], v[46:47]
	v_cvt_pk_bf16_f32 v48, v48, v49
	v_pk_fma_f32 v[50:51], v[26:27], v[84:85], v[50:51]
	s_nop 0
	v_pk_fma_f32 v[50:51], v[34:35], v[72:73], v[50:51]
	s_nop 0
	v_pk_fma_f32 v[50:51], v[38:39], v[70:71], v[50:51]
	s_nop 0
	v_pk_fma_f32 v[50:51], v[42:43], v[90:91], v[50:51]
	s_nop 0
	v_mul_f32_e32 v49, 0xbfb8aa3b, v50
	v_exp_f32_e32 v49, v49
	s_nop 0
	v_add_f32_e32 v49, 1.0, v49
	v_rcp_f32_e32 v62, v49
	v_mul_f32_e32 v49, 0xbfb8aa3b, v51
	v_exp_f32_e32 v49, v49
	s_nop 0
	v_add_f32_e32 v49, 1.0, v49
	v_rcp_f32_e32 v63, v49
	s_nop 0
	v_pk_mul_f32 v[50:51], v[50:51], v[62:63]
	s_nop 0
	v_cvt_pk_bf16_f32 v49, v50, v51
	v_pk_fma_f32 v[50:51], v[0:1], v[58:59], v[28:29]
	v_lshlrev_b32_e32 v62, 16, v106
	v_pk_fma_f32 v[50:51], v[8:9], v[80:81], v[50:51]
	v_and_b32_e32 v63, 0xffff0000, v106
	v_pk_fma_f32 v[50:51], v[12:13], v[66:67], v[50:51]
	s_nop 0
	v_pk_fma_f32 v[50:51], v[16:17], v[64:65], v[50:51]
	s_nop 0
	v_pk_fma_f32 v[50:51], v[20:21], v[86:87], v[50:51]
	s_nop 0
	v_mul_f32_e32 v58, 0xbfb8aa3b, v50
	v_mul_f32_e32 v59, 0xbfb8aa3b, v51
	v_exp_f32_e32 v58, v58
	v_exp_f32_e32 v59, v59
	v_add_f32_e32 v58, 1.0, v58
	v_add_f32_e32 v59, 1.0, v59
	v_rcp_f32_e32 v58, v58
	v_rcp_f32_e32 v59, v59
	s_nop 0
	v_pk_mul_f32 v[50:51], v[50:51], v[58:59]
	s_nop 0
	v_cvt_pk_bf16_f32 v50, v50, v51
	v_mul_f32_e32 v51, 0xbfb8aa3b, v52
	v_exp_f32_e32 v51, v51
	s_nop 0
	v_add_f32_e32 v51, 1.0, v51
	v_rcp_f32_e32 v58, v51
	v_mul_f32_e32 v51, 0xbfb8aa3b, v53
	v_exp_f32_e32 v51, v51
	s_nop 0
	v_add_f32_e32 v51, 1.0, v51
	v_rcp_f32_e32 v59, v51
	s_nop 0
	v_pk_mul_f32 v[52:53], v[52:53], v[58:59]
	s_nop 0
	v_cvt_pk_bf16_f32 v51, v52, v53
	v_or_b32_e32 v52, 29, v125
	v_mad_i64_i32 v[52:53], s[2:3], v52, s85, v[56:57]
	global_store_dwordx4 v[52:53], v[48:51], off
	v_lshlrev_b32_e32 v58, 16, v105
	v_and_b32_e32 v59, 0xffff0000, v105
	v_pk_fma_f32 v[48:49], v[4:5], v[88:89], v[44:45]
	v_lshlrev_b32_e32 v52, 16, v104
	v_pk_fma_f32 v[48:49], v[24:25], v[78:79], v[48:49]
	v_and_b32_e32 v53, 0xffff0000, v104
	v_pk_fma_f32 v[48:49], v[32:33], v[76:77], v[48:49]
	v_pk_fma_f32 v[74:75], v[22:23], v[52:53], v[74:75]
	v_pk_fma_f32 v[48:49], v[36:37], v[92:93], v[48:49]
	v_pk_fma_f32 v[4:5], v[4:5], v[78:79], v[44:45]
	v_pk_fma_f32 v[48:49], v[40:41], v[68:69], v[48:49]
	v_pk_fma_f32 v[4:5], v[24:25], v[76:77], v[4:5]
	v_mul_f32_e32 v50, 0xbfb8aa3b, v48
	v_mul_f32_e32 v51, 0xbfb8aa3b, v49
	v_exp_f32_e32 v50, v50
	v_exp_f32_e32 v51, v51
	v_pk_fma_f32 v[4:5], v[32:33], v[92:93], v[4:5]
	v_add_f32_e32 v50, 1.0, v50
	v_add_f32_e32 v51, 1.0, v51
	v_rcp_f32_e32 v50, v50
	v_rcp_f32_e32 v51, v51
	v_pk_fma_f32 v[4:5], v[36:37], v[68:69], v[4:5]
	v_pk_mul_f32 v[48:49], v[48:49], v[50:51]
	v_pk_fma_f32 v[50:51], v[6:7], v[84:85], v[46:47]
	v_cvt_pk_bf16_f32 v48, v48, v49
	v_pk_fma_f32 v[50:51], v[26:27], v[72:73], v[50:51]
	v_pk_fma_f32 v[6:7], v[6:7], v[72:73], v[46:47]
	v_pk_fma_f32 v[50:51], v[34:35], v[70:71], v[50:51]
	v_pk_fma_f32 v[6:7], v[26:27], v[70:71], v[6:7]
	v_pk_fma_f32 v[50:51], v[38:39], v[90:91], v[50:51]
	v_pk_fma_f32 v[6:7], v[34:35], v[90:91], v[6:7]
	v_pk_fma_f32 v[50:51], v[42:43], v[62:63], v[50:51]
	v_pk_fma_f32 v[6:7], v[38:39], v[62:63], v[6:7]
	v_mul_f32_e32 v49, 0xbfb8aa3b, v50
	v_exp_f32_e32 v49, v49
	s_nop 0
	v_add_f32_e32 v49, 1.0, v49
	v_rcp_f32_e32 v84, v49
; __device__ __forceinline__ float siluf_(float x) { return x * __builtin_amdgcn_rcpf(1.f + __expf(-x)); }
; #define CONV_ACC(rv, j) do { \
;         o[0] += bflo(rv.x) * wgt[j][0]; o[1] += bfhi(rv.x) * wgt[j][1]; \
;         o[2] += bflo(rv.y) * wgt[j][2]; o[3] += bfhi(rv.y) * wgt[j][3]; \
;         o[4] += bflo(rv.z) * wgt[j][4]; o[5] += bfhi(rv.z) * wgt[j][5]; \
;         o[6] += bflo(rv.w) * wgt[j][6]; o[7] += bfhi(rv.w) * wgt[j][7]; } while (0)
; __device__ __forceinline__ void conv_phase(const Params& P, const int pass, const int wvi) {
;     ...
;   for (int idx = blockIdx.x * NTHR + tid; idx < nitems; idx += gridDim.x * NTHR) {
;     ...
;       for (int j = 0; j < 8; ++j) {
;         float o[8];
; #pragma unroll
;         for (int e = 0; e < 8; ++e) o[e] = bias[e];
;         CONV_ACC(R[j], 0); CONV_ACC(R[j + 1], 1); CONV_ACC(R[j + 2], 2); CONV_ACC(R[j + 3], 3); CONV_ACC(R[j + 4], 4);
;         uint4 ov;
;         ov.x = pk2(siluf_(o[0]), siluf_(o[1])); ov.y = pk2(siluf_(o[2]), siluf_(o[3]));
;         ov.z = pk2(siluf_(o[4]), siluf_(o[5])); ov.w = pk2(siluf_(o[6]), siluf_(o[7]));
;         *(uint4*)(xo + (size_t)(t0 + blk * 8 + j) * CONVD + c0) = ov;
;       }
;       R[0] = R[8]; R[1] = R[9]; R[2] = R[10]; R[3] = R[11];
	v_mul_f32_e32 v49, 0xbfb8aa3b, v51
	v_exp_f32_e32 v49, v49
	s_nop 0
	v_add_f32_e32 v49, 1.0, v49
	v_rcp_f32_e32 v85, v49
	s_nop 0
	v_pk_mul_f32 v[50:51], v[50:51], v[84:85]
	s_nop 0
	v_cvt_pk_bf16_f32 v49, v50, v51
	v_pk_fma_f32 v[50:51], v[0:1], v[80:81], v[28:29]
	v_pk_fma_f32 v[0:1], v[0:1], v[66:67], v[28:29]
	v_pk_fma_f32 v[50:51], v[8:9], v[66:67], v[50:51]
	v_pk_fma_f32 v[0:1], v[8:9], v[64:65], v[0:1]
	v_pk_fma_f32 v[50:51], v[12:13], v[64:65], v[50:51]
	v_pk_fma_f32 v[0:1], v[12:13], v[86:87], v[0:1]
	v_pk_fma_f32 v[50:51], v[16:17], v[86:87], v[50:51]
	v_pk_fma_f32 v[0:1], v[16:17], v[58:59], v[0:1]
	v_pk_fma_f32 v[50:51], v[20:21], v[58:59], v[50:51]
	s_nop 0
	v_mul_f32_e32 v80, 0xbfb8aa3b, v50
	v_mul_f32_e32 v81, 0xbfb8aa3b, v51
	v_exp_f32_e32 v80, v80
	v_exp_f32_e32 v81, v81
	v_add_f32_e32 v80, 1.0, v80
	v_add_f32_e32 v81, 1.0, v81
	v_rcp_f32_e32 v80, v80
	v_rcp_f32_e32 v81, v81
	s_nop 0
	v_pk_mul_f32 v[50:51], v[50:51], v[80:81]
	s_nop 0
	v_cvt_pk_bf16_f32 v50, v50, v51
	v_mul_f32_e32 v51, 0xbfb8aa3b, v74
	v_exp_f32_e32 v51, v51
	s_nop 0
	v_add_f32_e32 v51, 1.0, v51
	v_rcp_f32_e32 v80, v51
	v_mul_f32_e32 v51, 0xbfb8aa3b, v75
	v_exp_f32_e32 v51, v51
	s_nop 0
	v_add_f32_e32 v51, 1.0, v51
	v_rcp_f32_e32 v81, v51
	s_nop 0
	v_pk_mul_f32 v[74:75], v[74:75], v[80:81]
	s_nop 0
	v_cvt_pk_bf16_f32 v51, v74, v75
	v_or_b32_e32 v74, 30, v125
	v_mad_i64_i32 v[74:75], s[2:3], v74, s85, v[56:57]
	global_store_dwordx4 v[74:75], v[48:51], off
	v_lshlrev_b32_e32 v74, 16, v101
	v_and_b32_e32 v75, 0xffff0000, v101
	v_lshlrev_b32_e32 v48, 16, v103
	v_and_b32_e32 v49, 0xffff0000, v103
	v_pk_fma_f32 v[4:5], v[40:41], v[48:49], v[4:5]
	v_lshlrev_b32_e32 v50, 16, v102
	v_mul_f32_e32 v24, 0xbfb8aa3b, v4
	v_mul_f32_e32 v25, 0xbfb8aa3b, v5
	v_exp_f32_e32 v24, v24
	v_exp_f32_e32 v25, v25
	v_and_b32_e32 v51, 0xffff0000, v102
	v_pk_fma_f32 v[6:7], v[42:43], v[50:51], v[6:7]
	v_add_f32_e32 v24, 1.0, v24
	v_add_f32_e32 v25, 1.0, v25
	v_rcp_f32_e32 v24, v24
	v_rcp_f32_e32 v25, v25
	v_pk_fma_f32 v[0:1], v[20:21], v[74:75], v[0:1]
	v_lshlrev_b32_e32 v80, 16, v100
	v_and_b32_e32 v81, 0xffff0000, v100
	v_pk_mul_f32 v[4:5], v[4:5], v[24:25]
	s_nop 0
	v_cvt_pk_bf16_f32 v4, v4, v5
	v_mul_f32_e32 v5, 0xbfb8aa3b, v6
	v_exp_f32_e32 v5, v5
	s_nop 0
	v_add_f32_e32 v5, 1.0, v5
	v_rcp_f32_e32 v24, v5
	v_mul_f32_e32 v5, 0xbfb8aa3b, v7
	v_exp_f32_e32 v5, v5
	s_nop 0
	v_add_f32_e32 v5, 1.0, v5
	v_rcp_f32_e32 v25, v5
	s_nop 0
	v_pk_mul_f32 v[6:7], v[6:7], v[24:25]
	s_nop 0
	v_cvt_pk_bf16_f32 v5, v6, v7
	v_mul_f32_e32 v6, 0xbfb8aa3b, v0
	v_mul_f32_e32 v7, 0xbfb8aa3b, v1
	v_exp_f32_e32 v6, v6
	v_exp_f32_e32 v7, v7
	v_add_f32_e32 v6, 1.0, v6
	v_add_f32_e32 v7, 1.0, v7
	v_rcp_f32_e32 v6, v6
	v_rcp_f32_e32 v7, v7
	s_nop 0
	v_pk_mul_f32 v[0:1], v[0:1], v[6:7]
	s_nop 0
	v_cvt_pk_bf16_f32 v6, v0, v1
	v_pk_fma_f32 v[0:1], v[2:3], v[60:61], v[30:31]
	s_nop 0
	v_pk_fma_f32 v[0:1], v[10:11], v[54:55], v[0:1]
	s_nop 0
	v_pk_fma_f32 v[0:1], v[14:15], v[82:83], v[0:1]
	s_nop 0
	v_pk_fma_f32 v[0:1], v[18:19], v[52:53], v[0:1]
	s_nop 0
	v_pk_fma_f32 v[0:1], v[22:23], v[80:81], v[0:1]
	s_nop 0
	v_mul_f32_e32 v2, 0xbfb8aa3b, v0
	v_mul_f32_e32 v3, 0xbfb8aa3b, v1
	v_exp_f32_e32 v2, v2
	v_exp_f32_e32 v3, v3
	v_add_f32_e32 v2, 1.0, v2
	v_add_f32_e32 v3, 1.0, v3
	v_rcp_f32_e32 v2, v2
	v_rcp_f32_e32 v3, v3
	s_nop 0
	v_pk_mul_f32 v[0:1], v[0:1], v[2:3]
	s_nop 0
	v_cvt_pk_bf16_f32 v7, v0, v1
	v_or_b32_e32 v0, 31, v125
	v_mad_i64_i32 v[0:1], s[2:3], v0, s85, v[56:57]
	s_mov_b32 s2, 0x5ffff
	s_nop 0
	v_cmp_lt_i32_e32 vcc, s2, v122
	s_or_b64 s[12:13], vcc, s[12:13]
	global_store_dwordx4 v[0:1], v[4:7], off
	s_andn2_b64 exec, exec, s[12:13]
	s_cbranch_execnz .LBB0_324
